# five more in-loop LDS-DMA pieces (in-place +0x180 add across the barrier) use offset:384 with the m0 constant reduced
# speedup vs baseline: 1.0038x; 1.0038x over previous
; #define G_LDA(dst, b, h)                                                                                                  \
;   _Pragma("unroll") for (int m = 0; m < 4; ++m) _Pragma("unroll") for (int k = 0; k < 2; ++k)                             \
;       dst[m][k] = *(const bf16x8*)((const char*)G_SA(b, h) + ((wr * 4 + m) * 2 + k) * 1024 + rdo)
; #define G_LDB(dst, b, h)                                                                                                  \
;   _Pragma("unroll") for (int n = 0; n < 2; ++n) _Pragma("unroll") for (int k = 0; k < 2; ++k)                             \
;       dst[n][k] = *(const bf16x8*)((const char*)G_SB(b, h) + ((wc * 2 + n) * 2 + k) * 1024 + rdo)
; #define G_WAIT_V(n) asm volatile("s_waitcnt vmcnt(" #n ")" ::: "memory")
; #define G_WAIT_L(n) asm volatile("s_waitcnt lgkmcnt(" #n ")" ::: "memory")
; #define G_BAR __builtin_amdgcn_s_barrier()
; #define G_SCHED __builtin_amdgcn_sched_barrier(0)
;     ...
;   for (int tt = 0; tt < nt - 2; tt += 2) {
;     G_LDB(B0, 0, 0); G_SCHED; G_LDA(At, 0, 0); G_STAGE(G_SA(1, 1), A, oa0, oa1, LDA, 128, KA(tt + 1));
;     G_WAIT_L(8); G_BAR; G_WAIT_L(0); G_MMA(0, 0, At, B0); G_BAR; G_SCHED;
;     G_LDB(B1, 0, 1); G_STAGE(G_SB(0, 0), B, ob0, ob1, LDB, 0, KB(tt + 2));
;     G_BAR; G_WAIT_L(0); G_MMA(0, 1, At, B1); G_BAR;
;     G_LDA(At, 0, 1); G_STAGE(G_SA(0, 0), A, oa0, oa1, LDA, 0, KA(tt + 2));
;     G_BAR; G_WAIT_L(0); G_MMA(1, 0, At, B0); G_BAR; G_SCHED;
;     G_STAGE(G_SB(0, 1), B, ob0, ob1, LDB, 128, KB(tt + 2));
;     G_WAIT_V(6); G_BAR; G_MMA(1, 1, At, B1); G_BAR;
.LBB0_40:
	ds_read_b128 v[164:167], v162
	ds_read_b128 v[182:185], v162 offset:1024
	ds_read_b128 v[186:189], v162 offset:2048
	ds_read_b128 v[190:193], v162 offset:3072
	v_lshl_add_u64 v[242:243], v[136:137], 0, s[20:21]
	v_lshl_add_u64 v[226:227], v[242:243], 0, s[78:79]
	s_add_u32 m0, s32, 0xc000
	v_lshl_add_u64 v[244:245], v[134:135], 0, s[20:21]
	ds_read_b128 v[194:197], v142
	ds_read_b128 v[198:201], v142 offset:1024
	ds_read_b128 v[202:205], v142 offset:2048
	ds_read_b128 v[206:209], v142 offset:3072
	ds_read_b128 v[210:213], v142 offset:4096
	ds_read_b128 v[214:217], v142 offset:5120
	ds_read_b128 v[218:221], v142 offset:6144
	ds_read_b128 v[222:225], v142 offset:7168
	global_load_lds_dwordx4 v[226:227], off
	s_add_u32 m0, s32, 0xe000
	v_lshl_add_u64 v[226:227], v[244:245], 0, s[78:79]
	global_load_lds_dwordx4 v[226:227], off
	s_waitcnt lgkmcnt(8)
	s_barrier
	s_waitcnt lgkmcnt(0)
	v_mfma_f32_16x16x32_bf16 v[126:129], v[194:197], v[164:167], v[126:129]
	v_mfma_f32_16x16x32_bf16 v[122:125], v[194:197], v[186:189], v[122:125]
	v_mfma_f32_16x16x32_bf16 v[118:121], v[202:205], v[164:167], v[118:121]
	v_mfma_f32_16x16x32_bf16 v[114:117], v[202:205], v[186:189], v[114:117]
	v_mfma_f32_16x16x32_bf16 v[110:113], v[210:213], v[164:167], v[110:113]
	v_mfma_f32_16x16x32_bf16 v[106:109], v[210:213], v[186:189], v[106:109]
	v_mfma_f32_16x16x32_bf16 v[102:105], v[218:221], v[164:167], v[102:105]
	v_mfma_f32_16x16x32_bf16 v[98:101], v[218:221], v[186:189], v[98:101]
	v_mfma_f32_16x16x32_bf16 v[126:129], v[198:201], v[182:185], v[126:129]
	v_mfma_f32_16x16x32_bf16 v[122:125], v[198:201], v[190:193], v[122:125]
	v_mfma_f32_16x16x32_bf16 v[118:121], v[206:209], v[182:185], v[118:121]
	v_mfma_f32_16x16x32_bf16 v[114:117], v[206:209], v[190:193], v[114:117]
	v_mfma_f32_16x16x32_bf16 v[110:113], v[214:217], v[182:185], v[110:113]
	v_mfma_f32_16x16x32_bf16 v[106:109], v[214:217], v[190:193], v[106:109]
	v_mfma_f32_16x16x32_bf16 v[102:105], v[222:225], v[182:185], v[102:105]
	v_mfma_f32_16x16x32_bf16 v[98:101], v[222:225], v[190:193], v[98:101]
	s_barrier
	v_lshl_add_u64 v[246:247], v[140:141], 0, s[20:21]
	v_lshl_add_u64 v[248:249], v[246:247], 0, s[42:43]
	s_add_u32 m0, s32, 0x10000
	ds_read_b128 v[226:229], v159
	ds_read_b128 v[230:233], v159 offset:1024
	ds_read_b128 v[234:237], v159 offset:2048
	ds_read_b128 v[238:241], v159 offset:3072
	global_load_lds_dwordx4 v[248:249], off
	v_lshl_add_u64 v[248:249], v[138:139], 0, s[20:21]
	s_add_u32 m0, s32, 0x12000
	v_lshl_add_u64 v[250:251], v[248:249], 0, s[42:43]
	global_load_lds_dwordx4 v[250:251], off
	s_barrier
	s_waitcnt lgkmcnt(0)
	v_mfma_f32_16x16x32_bf16 v[94:97], v[194:197], v[226:229], v[94:97]
	v_mfma_f32_16x16x32_bf16 v[78:81], v[194:197], v[234:237], v[78:81]
	v_mfma_f32_16x16x32_bf16 v[62:65], v[202:205], v[226:229], v[62:65]
	v_mfma_f32_16x16x32_bf16 v[54:57], v[202:205], v[234:237], v[54:57]
	v_mfma_f32_16x16x32_bf16 v[50:53], v[210:213], v[226:229], v[50:53]
	v_mfma_f32_16x16x32_bf16 v[46:49], v[210:213], v[234:237], v[46:49]
	v_mfma_f32_16x16x32_bf16 v[42:45], v[218:221], v[226:229], v[42:45]
	v_mfma_f32_16x16x32_bf16 v[38:41], v[218:221], v[234:237], v[38:41]
	v_mfma_f32_16x16x32_bf16 v[94:97], v[198:201], v[230:233], v[94:97]
	v_mfma_f32_16x16x32_bf16 v[78:81], v[198:201], v[238:241], v[78:81]
	v_mfma_f32_16x16x32_bf16 v[62:65], v[206:209], v[230:233], v[62:65]
	v_mfma_f32_16x16x32_bf16 v[54:57], v[206:209], v[238:241], v[54:57]
	v_mfma_f32_16x16x32_bf16 v[50:53], v[214:217], v[230:233], v[50:53]
	v_mfma_f32_16x16x32_bf16 v[46:49], v[214:217], v[238:241], v[46:49]
	v_mfma_f32_16x16x32_bf16 v[42:45], v[222:225], v[230:233], v[42:45]
	v_mfma_f32_16x16x32_bf16 v[38:41], v[222:225], v[238:241], v[38:41]
	v_lshl_add_u64 v[250:251], v[242:243], 0, s[82:83]
	s_mov_b32 m0, s32
	s_barrier
	ds_read_b128 v[194:197], v142 offset:16384
	ds_read_b128 v[198:201], v142 offset:17408
	ds_read_b128 v[202:205], v142 offset:18432
	ds_read_b128 v[206:209], v142 offset:19456
	ds_read_b128 v[210:213], v142 offset:20480
	ds_read_b128 v[214:217], v142 offset:21504
	ds_read_b128 v[218:221], v142 offset:22528
	ds_read_b128 v[222:225], v142 offset:23552
	global_load_lds_dwordx4 v[250:251], off
	s_add_u32 m0, s32, 0x1f00
	s_nop 0
	global_load_lds_dwordx4 v[244:245], off offset:256
	s_barrier
	s_waitcnt lgkmcnt(0)
	v_mfma_f32_16x16x32_bf16 v[34:37], v[194:197], v[164:167], v[34:37]
	v_mfma_f32_16x16x32_bf16 v[30:33], v[194:197], v[186:189], v[30:33]
	v_mfma_f32_16x16x32_bf16 v[26:29], v[202:205], v[164:167], v[26:29]
	v_mfma_f32_16x16x32_bf16 v[22:25], v[202:205], v[186:189], v[22:25]
	v_mfma_f32_16x16x32_bf16 v[18:21], v[210:213], v[164:167], v[18:21]
	v_mfma_f32_16x16x32_bf16 v[14:17], v[210:213], v[186:189], v[14:17]
	v_mfma_f32_16x16x32_bf16 v[10:13], v[218:221], v[164:167], v[10:13]
	v_mfma_f32_16x16x32_bf16 v[6:9], v[218:221], v[186:189], v[6:9]
	v_mfma_f32_16x16x32_bf16 v[34:37], v[198:201], v[182:185], v[34:37]
	v_mfma_f32_16x16x32_bf16 v[30:33], v[198:201], v[190:193], v[30:33]
	v_mfma_f32_16x16x32_bf16 v[26:29], v[206:209], v[182:185], v[26:29]
	v_mfma_f32_16x16x32_bf16 v[22:25], v[206:209], v[190:193], v[22:25]
	v_mfma_f32_16x16x32_bf16 v[18:21], v[214:217], v[182:185], v[18:21]
	v_mfma_f32_16x16x32_bf16 v[14:17], v[214:217], v[190:193], v[14:17]
	v_mfma_f32_16x16x32_bf16 v[10:13], v[222:225], v[182:185], v[10:13]
	v_mfma_f32_16x16x32_bf16 v[6:9], v[222:225], v[190:193], v[6:9]
	s_barrier
	v_lshl_add_u64 v[164:165], v[246:247], 0, s[24:25]
	s_add_u32 m0, s32, 0x14000
	s_nop 0
	global_load_lds_dwordx4 v[164:165], off
	s_add_u32 m0, s32, 0x16000
	v_lshl_add_u64 v[164:165], v[248:249], 0, s[24:25]
	global_load_lds_dwordx4 v[164:165], off
	s_waitcnt vmcnt(6)
	s_barrier
; #define G_LDA(dst, b, h)                                                                                                  \
;   _Pragma("unroll") for (int m = 0; m < 4; ++m) _Pragma("unroll") for (int k = 0; k < 2; ++k)                             \
;       dst[m][k] = *(const bf16x8*)((const char*)G_SA(b, h) + ((wr * 4 + m) * 2 + k) * 1024 + rdo)
; #define G_LDB(dst, b, h)                                                                                                  \
;   _Pragma("unroll") for (int n = 0; n < 2; ++n) _Pragma("unroll") for (int k = 0; k < 2; ++k)                             \
;       dst[n][k] = *(const bf16x8*)((const char*)G_SB(b, h) + ((wc * 2 + n) * 2 + k) * 1024 + rdo)
; #define G_WAIT_V(n) asm volatile("s_waitcnt vmcnt(" #n ")" ::: "memory")
; #define G_WAIT_L(n) asm volatile("s_waitcnt lgkmcnt(" #n ")" ::: "memory")
; #define G_BAR __builtin_amdgcn_s_barrier()
; #define G_SCHED __builtin_amdgcn_sched_barrier(0)
;     ...
;     G_WAIT_V(6); G_BAR; G_MMA(1, 1, At, B1); G_BAR;
;     G_LDB(B0, 1, 0); G_SCHED; G_LDA(At, 1, 0); G_STAGE(G_SA(0, 1), A, oa0, oa1, LDA, 128, KA(tt + 2));
;     G_WAIT_L(8); G_BAR; G_WAIT_L(0); G_MMA(0, 0, At, B0); G_BAR; G_SCHED;
;     G_LDB(B1, 1, 1); G_STAGE(G_SB(1, 0), B, ob0, ob1, LDB, 0, KB(tt + 3));
;     G_BAR; G_WAIT_L(0); G_MMA(0, 1, At, B1); G_BAR;
;     G_LDA(At, 1, 1); G_STAGE(G_SA(1, 0), A, oa0, oa1, LDA, 0, KA(tt + 3));
	v_mfma_f32_16x16x32_bf16 v[2:5], v[194:197], v[226:229], v[2:5]
	v_mfma_f32_16x16x32_bf16 v[58:61], v[194:197], v[234:237], v[58:61]
	v_mfma_f32_16x16x32_bf16 v[66:69], v[202:205], v[226:229], v[66:69]
	v_mfma_f32_16x16x32_bf16 v[70:73], v[202:205], v[234:237], v[70:73]
	v_mfma_f32_16x16x32_bf16 v[74:77], v[210:213], v[226:229], v[74:77]
	v_mfma_f32_16x16x32_bf16 v[82:85], v[210:213], v[234:237], v[82:85]
	v_mfma_f32_16x16x32_bf16 v[86:89], v[218:221], v[226:229], v[86:89]
	v_mfma_f32_16x16x32_bf16 v[90:93], v[218:221], v[234:237], v[90:93]
	v_mfma_f32_16x16x32_bf16 v[2:5], v[198:201], v[230:233], v[2:5]
	v_mfma_f32_16x16x32_bf16 v[58:61], v[198:201], v[238:241], v[58:61]
	v_mfma_f32_16x16x32_bf16 v[66:69], v[206:209], v[230:233], v[66:69]
	v_mfma_f32_16x16x32_bf16 v[70:73], v[206:209], v[238:241], v[70:73]
	v_mfma_f32_16x16x32_bf16 v[74:77], v[214:217], v[230:233], v[74:77]
	v_mfma_f32_16x16x32_bf16 v[82:85], v[214:217], v[238:241], v[82:85]
	v_mfma_f32_16x16x32_bf16 v[86:89], v[222:225], v[230:233], v[86:89]
	v_mfma_f32_16x16x32_bf16 v[90:93], v[222:225], v[238:241], v[90:93]
	s_barrier
	ds_read_b128 v[164:167], v150
	ds_read_b128 v[182:185], v150 offset:1024
	ds_read_b128 v[186:189], v150 offset:2048
	ds_read_b128 v[190:193], v150 offset:3072
	v_lshl_add_u64 v[226:227], v[242:243], 0, s[86:87]
	s_add_u32 m0, s32, 0x4000
	ds_read_b128 v[194:197], v142 offset:32768
	ds_read_b128 v[198:201], v142 offset:33792
	ds_read_b128 v[202:205], v142 offset:34816
	ds_read_b128 v[206:209], v142 offset:35840
	ds_read_b128 v[210:213], v142 offset:36864
	ds_read_b128 v[214:217], v142 offset:37888
	ds_read_b128 v[218:221], v142 offset:38912
	ds_read_b128 v[222:225], v142 offset:39936
	global_load_lds_dwordx4 v[226:227], off
	s_add_u32 m0, s32, 0x6000
	v_lshl_add_u64 v[226:227], v[244:245], 0, s[86:87]
	global_load_lds_dwordx4 v[226:227], off
	s_waitcnt lgkmcnt(8)
	s_barrier
	s_waitcnt lgkmcnt(0)
	v_mfma_f32_16x16x32_bf16 v[126:129], v[194:197], v[164:167], v[126:129]
	v_mfma_f32_16x16x32_bf16 v[122:125], v[194:197], v[186:189], v[122:125]
	v_mfma_f32_16x16x32_bf16 v[118:121], v[202:205], v[164:167], v[118:121]
	v_mfma_f32_16x16x32_bf16 v[114:117], v[202:205], v[186:189], v[114:117]
	v_mfma_f32_16x16x32_bf16 v[110:113], v[210:213], v[164:167], v[110:113]
	v_mfma_f32_16x16x32_bf16 v[106:109], v[210:213], v[186:189], v[106:109]
	v_mfma_f32_16x16x32_bf16 v[102:105], v[218:221], v[164:167], v[102:105]
	v_mfma_f32_16x16x32_bf16 v[98:101], v[218:221], v[186:189], v[98:101]
	v_mfma_f32_16x16x32_bf16 v[126:129], v[198:201], v[182:185], v[126:129]
	v_mfma_f32_16x16x32_bf16 v[122:125], v[198:201], v[190:193], v[122:125]
	v_mfma_f32_16x16x32_bf16 v[118:121], v[206:209], v[182:185], v[118:121]
	v_mfma_f32_16x16x32_bf16 v[114:117], v[206:209], v[190:193], v[114:117]
	v_mfma_f32_16x16x32_bf16 v[110:113], v[214:217], v[182:185], v[110:113]
	v_mfma_f32_16x16x32_bf16 v[106:109], v[214:217], v[190:193], v[106:109]
	v_mfma_f32_16x16x32_bf16 v[102:105], v[222:225], v[182:185], v[102:105]
	v_mfma_f32_16x16x32_bf16 v[98:101], v[222:225], v[190:193], v[98:101]
	s_barrier
	v_lshl_add_u64 v[250:251], v[246:247], 0, s[36:37]
	s_add_u32 m0, s32, 0x18000
	ds_read_b128 v[226:229], v145
	ds_read_b128 v[230:233], v145 offset:1024
	ds_read_b128 v[234:237], v145 offset:2048
	ds_read_b128 v[238:241], v145 offset:3072
	global_load_lds_dwordx4 v[250:251], off
	s_add_u32 m0, s32, 0x1a000
	v_lshl_add_u64 v[250:251], v[248:249], 0, s[36:37]
	global_load_lds_dwordx4 v[250:251], off
	s_barrier
	s_waitcnt lgkmcnt(0)
	v_mfma_f32_16x16x32_bf16 v[94:97], v[194:197], v[226:229], v[94:97]
	v_mfma_f32_16x16x32_bf16 v[78:81], v[194:197], v[234:237], v[78:81]
	v_mfma_f32_16x16x32_bf16 v[62:65], v[202:205], v[226:229], v[62:65]
	v_mfma_f32_16x16x32_bf16 v[54:57], v[202:205], v[234:237], v[54:57]
	v_mfma_f32_16x16x32_bf16 v[50:53], v[210:213], v[226:229], v[50:53]
	v_mfma_f32_16x16x32_bf16 v[46:49], v[210:213], v[234:237], v[46:49]
	v_mfma_f32_16x16x32_bf16 v[42:45], v[218:221], v[226:229], v[42:45]
	v_mfma_f32_16x16x32_bf16 v[38:41], v[218:221], v[234:237], v[38:41]
	v_mfma_f32_16x16x32_bf16 v[94:97], v[198:201], v[230:233], v[94:97]
	v_mfma_f32_16x16x32_bf16 v[78:81], v[198:201], v[238:241], v[78:81]
	v_mfma_f32_16x16x32_bf16 v[62:65], v[206:209], v[230:233], v[62:65]
	v_mfma_f32_16x16x32_bf16 v[54:57], v[206:209], v[238:241], v[54:57]
	v_mfma_f32_16x16x32_bf16 v[50:53], v[214:217], v[230:233], v[50:53]
	v_mfma_f32_16x16x32_bf16 v[46:49], v[214:217], v[238:241], v[46:49]
	v_mfma_f32_16x16x32_bf16 v[42:45], v[222:225], v[230:233], v[42:45]
	v_mfma_f32_16x16x32_bf16 v[38:41], v[222:225], v[238:241], v[38:41]
	s_add_u32 m0, s32, 0x7e80
	s_barrier
	ds_read_b128 v[194:197], v142 offset:49152
	ds_read_b128 v[198:201], v142 offset:50176
	ds_read_b128 v[202:205], v142 offset:51200
	ds_read_b128 v[206:209], v142 offset:52224
	ds_read_b128 v[210:213], v142 offset:53248
	ds_read_b128 v[214:217], v142 offset:54272
	ds_read_b128 v[218:221], v142 offset:55296
	ds_read_b128 v[222:225], v142 offset:56320
	global_load_lds_dwordx4 v[242:243], off offset:384
	s_add_u32 m0, s32, 0x9e80
	s_nop 0
	global_load_lds_dwordx4 v[244:245], off offset:384
	s_barrier
; #define G_LDA(dst, b, h)                                                                                                  \
;   _Pragma("unroll") for (int m = 0; m < 4; ++m) _Pragma("unroll") for (int k = 0; k < 2; ++k)                             \
;       dst[m][k] = *(const bf16x8*)((const char*)G_SA(b, h) + ((wr * 4 + m) * 2 + k) * 1024 + rdo)
; #define G_LDB(dst, b, h)                                                                                                  \
;   _Pragma("unroll") for (int n = 0; n < 2; ++n) _Pragma("unroll") for (int k = 0; k < 2; ++k)                             \
;       dst[n][k] = *(const bf16x8*)((const char*)G_SB(b, h) + ((wc * 2 + n) * 2 + k) * 1024 + rdo)
; #define G_WAIT_V(n) asm volatile("s_waitcnt vmcnt(" #n ")" ::: "memory")
; #define G_WAIT_L(n) asm volatile("s_waitcnt lgkmcnt(" #n ")" ::: "memory")
; #define G_BAR __builtin_amdgcn_s_barrier()
; #define G_SCHED __builtin_amdgcn_sched_barrier(0)
; DI void br_flush(PREF p, f32x4 (&acc)[2][2][4][2], int slot) { br_store(p, acc, slot); zero_acc256(acc); }
;     ...
;     G_BAR; G_WAIT_L(0); G_MMA(1, 0, At, B0); G_BAR; G_SCHED;
;     G_STAGE(G_SB(1, 1), B, ob0, ob1, LDB, 128, KB(tt + 3));
;     G_WAIT_V(6); G_BAR; G_MMA(1, 1, At, B1); G_BAR;
;     if (MODE && ((tt + 1) & 3) == 3) br_flush(p, acc, (tt + 1) >> 2);
;   }
;   {
;     G_LDB(B0, 0, 0); G_LDA(At, 0, 0); G_STAGE(G_SA(1, 1), A, oa0, oa1, LDA, 128, KA(nt - 1));
;     G_BAR; G_WAIT_L(0); G_MMA(0, 0, At, B0); G_BAR;
;     G_LDB(B1, 0, 1); G_BAR; G_WAIT_L(0); G_MMA(0, 1, At, B1); G_BAR;
	s_waitcnt lgkmcnt(0)
	v_mfma_f32_16x16x32_bf16 v[34:37], v[194:197], v[164:167], v[34:37]
	v_mfma_f32_16x16x32_bf16 v[30:33], v[194:197], v[186:189], v[30:33]
	v_mfma_f32_16x16x32_bf16 v[26:29], v[202:205], v[164:167], v[26:29]
	v_mfma_f32_16x16x32_bf16 v[22:25], v[202:205], v[186:189], v[22:25]
	v_mfma_f32_16x16x32_bf16 v[18:21], v[210:213], v[164:167], v[18:21]
	v_mfma_f32_16x16x32_bf16 v[14:17], v[210:213], v[186:189], v[14:17]
	v_mfma_f32_16x16x32_bf16 v[10:13], v[218:221], v[164:167], v[10:13]
	v_mfma_f32_16x16x32_bf16 v[6:9], v[218:221], v[186:189], v[6:9]
	v_mfma_f32_16x16x32_bf16 v[34:37], v[198:201], v[182:185], v[34:37]
	v_mfma_f32_16x16x32_bf16 v[30:33], v[198:201], v[190:193], v[30:33]
	v_mfma_f32_16x16x32_bf16 v[26:29], v[206:209], v[182:185], v[26:29]
	v_mfma_f32_16x16x32_bf16 v[22:25], v[206:209], v[190:193], v[22:25]
	v_mfma_f32_16x16x32_bf16 v[18:21], v[214:217], v[182:185], v[18:21]
	v_mfma_f32_16x16x32_bf16 v[14:17], v[214:217], v[190:193], v[14:17]
	v_mfma_f32_16x16x32_bf16 v[10:13], v[222:225], v[182:185], v[10:13]
	v_mfma_f32_16x16x32_bf16 v[6:9], v[222:225], v[190:193], v[6:9]
	s_barrier
	v_lshl_add_u64 v[164:165], v[246:247], 0, s[40:41]
	s_add_u32 m0, s32, 0x1c000
	s_nop 0
	global_load_lds_dwordx4 v[164:165], off
	s_add_u32 m0, s32, 0x1e000
	v_lshl_add_u64 v[164:165], v[248:249], 0, s[40:41]
	global_load_lds_dwordx4 v[164:165], off
	s_waitcnt vmcnt(6)
	s_barrier
	v_mfma_f32_16x16x32_bf16 v[2:5], v[194:197], v[226:229], v[2:5]
	v_mfma_f32_16x16x32_bf16 v[58:61], v[194:197], v[234:237], v[58:61]
	v_mfma_f32_16x16x32_bf16 v[66:69], v[202:205], v[226:229], v[66:69]
	v_mfma_f32_16x16x32_bf16 v[70:73], v[202:205], v[234:237], v[70:73]
	v_mfma_f32_16x16x32_bf16 v[74:77], v[210:213], v[226:229], v[74:77]
	v_mfma_f32_16x16x32_bf16 v[82:85], v[210:213], v[234:237], v[82:85]
	v_mfma_f32_16x16x32_bf16 v[86:89], v[218:221], v[226:229], v[86:89]
	v_mfma_f32_16x16x32_bf16 v[90:93], v[218:221], v[234:237], v[90:93]
	v_mfma_f32_16x16x32_bf16 v[2:5], v[198:201], v[230:233], v[2:5]
	v_mfma_f32_16x16x32_bf16 v[58:61], v[198:201], v[238:241], v[58:61]
	v_mfma_f32_16x16x32_bf16 v[66:69], v[206:209], v[230:233], v[66:69]
	v_mfma_f32_16x16x32_bf16 v[70:73], v[206:209], v[238:241], v[70:73]
	v_mfma_f32_16x16x32_bf16 v[74:77], v[214:217], v[230:233], v[74:77]
	v_mfma_f32_16x16x32_bf16 v[82:85], v[214:217], v[238:241], v[82:85]
	v_mfma_f32_16x16x32_bf16 v[86:89], v[222:225], v[230:233], v[86:89]
	v_mfma_f32_16x16x32_bf16 v[90:93], v[222:225], v[238:241], v[90:93]
	s_add_i32 s22, s22, 2
	s_add_u32 s20, s20, 0x100
	s_addc_u32 s21, s21, 0
	s_cmp_lt_u32 s22, 12
	s_barrier
	s_cbranch_scc1 .LBB0_40
	s_add_u32 s0, s16, 0x40780
	s_addc_u32 s1, s17, 0
	v_lshl_add_u64 v[132:133], v[132:133], 1, s[0:1]
	s_add_u32 m0, s32, 0xc000
	v_lshl_add_u64 v[130:131], v[130:131], 1, s[0:1]
	ds_read_b128 v[134:137], v162
	ds_read_b128 v[138:141], v162 offset:1024
	ds_read_b128 v[146:149], v162 offset:2048
	ds_read_b128 v[152:155], v162 offset:3072
	ds_read_b128 v[164:167], v142
	ds_read_b128 v[182:185], v142 offset:1024
	ds_read_b128 v[186:189], v142 offset:2048
	ds_read_b128 v[190:193], v142 offset:3072
	ds_read_b128 v[194:197], v142 offset:4096
	ds_read_b128 v[198:201], v142 offset:5120
	ds_read_b128 v[202:205], v142 offset:6144
	ds_read_b128 v[206:209], v142 offset:7168
	global_load_lds_dwordx4 v[132:133], off
	s_add_u32 m0, s32, 0xe000
	s_nop 0
	global_load_lds_dwordx4 v[130:131], off
	s_barrier
	s_waitcnt lgkmcnt(0)
	v_mfma_f32_16x16x32_bf16 v[126:129], v[164:167], v[134:137], v[126:129]
	v_mfma_f32_16x16x32_bf16 v[122:125], v[164:167], v[146:149], v[122:125]
	v_mfma_f32_16x16x32_bf16 v[110:113], v[194:197], v[134:137], v[110:113]
	v_mfma_f32_16x16x32_bf16 v[102:105], v[202:205], v[134:137], v[102:105]
	v_mfma_f32_16x16x32_bf16 v[126:129], v[182:185], v[138:141], v[126:129]
	v_mfma_f32_16x16x32_bf16 v[122:125], v[182:185], v[152:155], v[122:125]
	v_mfma_f32_16x16x32_bf16 v[118:121], v[186:189], v[134:137], v[118:121]
	v_mfma_f32_16x16x32_bf16 v[114:117], v[186:189], v[146:149], v[114:117]
	v_mfma_f32_16x16x32_bf16 v[110:113], v[198:201], v[138:141], v[110:113]
	v_mfma_f32_16x16x32_bf16 v[106:109], v[194:197], v[146:149], v[106:109]
	v_mfma_f32_16x16x32_bf16 v[102:105], v[206:209], v[138:141], v[102:105]
	v_mfma_f32_16x16x32_bf16 v[98:101], v[202:205], v[146:149], v[98:101]
	v_mfma_f32_16x16x32_bf16 v[130:133], v[190:193], v[138:141], v[118:121]
	v_mfma_f32_16x16x32_bf16 v[210:213], v[190:193], v[152:155], v[114:117]
	v_mfma_f32_16x16x32_bf16 v[214:217], v[198:201], v[152:155], v[106:109]
	v_mfma_f32_16x16x32_bf16 v[218:221], v[206:209], v[152:155], v[98:101]
	s_barrier
	s_nop 1
	s_nop 0
	ds_read_b128 v[98:101], v159
	ds_read_b128 v[106:109], v159 offset:1024
	ds_read_b128 v[114:117], v159 offset:2048
	ds_read_b128 v[118:121], v159 offset:3072
	s_barrier
	s_waitcnt lgkmcnt(0)
	v_mfma_f32_16x16x32_bf16 v[94:97], v[164:167], v[98:101], v[94:97]
	v_mfma_f32_16x16x32_bf16 v[78:81], v[164:167], v[114:117], v[78:81]
	v_mfma_f32_16x16x32_bf16 v[62:65], v[186:189], v[98:101], v[62:65]
	v_mfma_f32_16x16x32_bf16 v[54:57], v[186:189], v[114:117], v[54:57]
	v_mfma_f32_16x16x32_bf16 v[50:53], v[194:197], v[98:101], v[50:53]
	v_mfma_f32_16x16x32_bf16 v[46:49], v[194:197], v[114:117], v[46:49]
	v_mfma_f32_16x16x32_bf16 v[42:45], v[202:205], v[98:101], v[42:45]
	v_mfma_f32_16x16x32_bf16 v[38:41], v[202:205], v[114:117], v[38:41]
	v_mfma_f32_16x16x32_bf16 v[94:97], v[182:185], v[106:109], v[94:97]
	v_mfma_f32_16x16x32_bf16 v[78:81], v[182:185], v[118:121], v[78:81]
	v_mfma_f32_16x16x32_bf16 v[62:65], v[190:193], v[106:109], v[62:65]
	v_mfma_f32_16x16x32_bf16 v[54:57], v[190:193], v[118:121], v[54:57]
	v_mfma_f32_16x16x32_bf16 v[50:53], v[198:201], v[106:109], v[50:53]
	v_mfma_f32_16x16x32_bf16 v[46:49], v[198:201], v[118:121], v[46:49]
	v_mfma_f32_16x16x32_bf16 v[42:45], v[206:209], v[106:109], v[42:45]
	v_mfma_f32_16x16x32_bf16 v[38:41], v[206:209], v[118:121], v[38:41]
	s_barrier
; #define G_LDA(dst, b, h)                                                                                                  \
;   _Pragma("unroll") for (int m = 0; m < 4; ++m) _Pragma("unroll") for (int k = 0; k < 2; ++k)                             \
;       dst[m][k] = *(const bf16x8*)((const char*)G_SA(b, h) + ((wr * 4 + m) * 2 + k) * 1024 + rdo)
; #define G_LDB(dst, b, h)                                                                                                  \
;   _Pragma("unroll") for (int n = 0; n < 2; ++n) _Pragma("unroll") for (int k = 0; k < 2; ++k)                             \
;       dst[n][k] = *(const bf16x8*)((const char*)G_SB(b, h) + ((wc * 2 + n) * 2 + k) * 1024 + rdo)
; #define G_WAIT_V(n) asm volatile("s_waitcnt vmcnt(" #n ")" ::: "memory")
; #define G_WAIT_L(n) asm volatile("s_waitcnt lgkmcnt(" #n ")" ::: "memory")
; #define G_BAR __builtin_amdgcn_s_barrier()
;     ...
;     G_LDB(B1, 0, 1); G_BAR; G_WAIT_L(0); G_MMA(0, 1, At, B1); G_BAR;
;     G_LDA(At, 0, 1); G_WAIT_V(4); G_BAR; G_WAIT_L(0); G_MMA(1, 0, At, B0); G_MMA(1, 1, At, B1); G_BAR;
;   }
;   {
;     G_LDB(B0, 1, 0); G_LDA(At, 1, 0); G_WAIT_V(2); G_BAR; G_WAIT_L(0); G_MMA(0, 0, At, B0); G_BAR;
	ds_read_b128 v[156:159], v142 offset:16384
	ds_read_b128 v[164:167], v142 offset:17408
	ds_read_b128 v[182:185], v142 offset:18432
	ds_read_b128 v[186:189], v142 offset:19456
	ds_read_b128 v[190:193], v142 offset:20480
	ds_read_b128 v[194:197], v142 offset:21504
	ds_read_b128 v[198:201], v142 offset:22528
	ds_read_b128 v[202:205], v142 offset:23552
	s_waitcnt vmcnt(4)
	s_barrier
	s_waitcnt lgkmcnt(0)
	v_mfma_f32_16x16x32_bf16 v[34:37], v[156:159], v[134:137], v[34:37]
	v_mfma_f32_16x16x32_bf16 v[30:33], v[156:159], v[146:149], v[30:33]
	v_mfma_f32_16x16x32_bf16 v[26:29], v[182:185], v[134:137], v[26:29]
	v_mfma_f32_16x16x32_bf16 v[22:25], v[182:185], v[146:149], v[22:25]
	v_mfma_f32_16x16x32_bf16 v[18:21], v[190:193], v[134:137], v[18:21]
	v_mfma_f32_16x16x32_bf16 v[14:17], v[190:193], v[146:149], v[14:17]
	v_mfma_f32_16x16x32_bf16 v[10:13], v[198:201], v[134:137], v[10:13]
	v_mfma_f32_16x16x32_bf16 v[6:9], v[198:201], v[146:149], v[6:9]
	v_mfma_f32_16x16x32_bf16 v[34:37], v[164:167], v[138:141], v[34:37]
	v_mfma_f32_16x16x32_bf16 v[30:33], v[164:167], v[152:155], v[30:33]
	v_mfma_f32_16x16x32_bf16 v[26:29], v[186:189], v[138:141], v[26:29]
	v_mfma_f32_16x16x32_bf16 v[22:25], v[186:189], v[152:155], v[22:25]
	v_mfma_f32_16x16x32_bf16 v[18:21], v[194:197], v[138:141], v[18:21]
	v_mfma_f32_16x16x32_bf16 v[14:17], v[194:197], v[152:155], v[14:17]
	v_mfma_f32_16x16x32_bf16 v[10:13], v[202:205], v[138:141], v[10:13]
	v_mfma_f32_16x16x32_bf16 v[6:9], v[202:205], v[152:155], v[6:9]
	v_mfma_f32_16x16x32_bf16 v[58:61], v[156:159], v[114:117], v[58:61]
	v_mfma_f32_16x16x32_bf16 v[134:137], v[164:167], v[118:121], v[58:61]
	v_mfma_f32_16x16x32_bf16 v[58:61], v[182:185], v[98:101], v[66:69]
	v_mfma_f32_16x16x32_bf16 v[138:141], v[186:189], v[106:109], v[58:61]
	v_mfma_f32_16x16x32_bf16 v[58:61], v[182:185], v[114:117], v[70:73]
	v_mfma_f32_16x16x32_bf16 v[146:149], v[186:189], v[118:121], v[58:61]
	v_mfma_f32_16x16x32_bf16 v[58:61], v[190:193], v[98:101], v[74:77]
	v_mfma_f32_16x16x32_bf16 v[152:155], v[194:197], v[106:109], v[58:61]
	v_mfma_f32_16x16x32_bf16 v[58:61], v[190:193], v[114:117], v[82:85]
	v_mfma_f32_16x16x32_bf16 v[2:5], v[156:159], v[98:101], v[2:5]
	v_mfma_f32_16x16x32_bf16 v[156:159], v[194:197], v[118:121], v[58:61]
	v_mfma_f32_16x16x32_bf16 v[58:61], v[198:201], v[98:101], v[86:89]
	v_mfma_f32_16x16x32_bf16 v[2:5], v[164:167], v[106:109], v[2:5]
	v_mfma_f32_16x16x32_bf16 v[164:167], v[202:205], v[106:109], v[58:61]
	v_mfma_f32_16x16x32_bf16 v[58:61], v[198:201], v[114:117], v[90:93]
	v_mfma_f32_16x16x32_bf16 v[182:185], v[202:205], v[118:121], v[58:61]
	s_barrier
	ds_read_b128 v[186:189], v150
	ds_read_b128 v[190:193], v150 offset:1024
	ds_read_b128 v[194:197], v150 offset:2048
	ds_read_b128 v[198:201], v150 offset:3072
	s_nop 0
	s_nop 0
	ds_read_b128 v[58:61], v142 offset:32768
	ds_read_b128 v[66:69], v142 offset:33792
	ds_read_b128 v[70:73], v142 offset:34816
	ds_read_b128 v[74:77], v142 offset:35840
	ds_read_b128 v[202:205], v142 offset:36864
	ds_read_b128 v[206:209], v142 offset:37888
	ds_read_b128 v[222:225], v142 offset:38912
	ds_read_b128 v[226:229], v142 offset:39936
	s_waitcnt vmcnt(2)
	s_barrier
	s_waitcnt lgkmcnt(0)
	v_mfma_f32_16x16x32_bf16 v[82:85], v[58:61], v[186:189], v[126:129]
	v_mfma_f32_16x16x32_bf16 v[118:121], v[66:69], v[190:193], v[82:85]
	v_mfma_f32_16x16x32_bf16 v[82:85], v[58:61], v[194:197], v[122:125]
	v_mfma_f32_16x16x32_bf16 v[126:129], v[66:69], v[198:201], v[82:85]
	v_mfma_f32_16x16x32_bf16 v[82:85], v[70:73], v[186:189], v[130:133]
	v_mfma_f32_16x16x32_bf16 v[114:117], v[74:77], v[190:193], v[82:85]
	v_mfma_f32_16x16x32_bf16 v[82:85], v[70:73], v[194:197], v[210:213]
	v_mfma_f32_16x16x32_bf16 v[122:125], v[74:77], v[198:201], v[82:85]
	v_mfma_f32_16x16x32_bf16 v[82:85], v[202:205], v[186:189], v[110:113]
	v_mfma_f32_16x16x32_bf16 v[106:109], v[206:209], v[190:193], v[82:85]
	v_mfma_f32_16x16x32_bf16 v[82:85], v[202:205], v[194:197], v[214:217]
	v_mfma_f32_16x16x32_bf16 v[110:113], v[206:209], v[198:201], v[82:85]
	v_mfma_f32_16x16x32_bf16 v[82:85], v[222:225], v[186:189], v[102:105]
	v_mfma_f32_16x16x32_bf16 v[98:101], v[226:229], v[190:193], v[82:85]
	v_mfma_f32_16x16x32_bf16 v[82:85], v[222:225], v[194:197], v[218:221]
	v_mfma_f32_16x16x32_bf16 v[102:105], v[226:229], v[198:201], v[82:85]
	s_barrier
; #define G_LDA(dst, b, h)                                                                                                  \
;   _Pragma("unroll") for (int m = 0; m < 4; ++m) _Pragma("unroll") for (int k = 0; k < 2; ++k)                             \
;       dst[m][k] = *(const bf16x8*)((const char*)G_SA(b, h) + ((wr * 4 + m) * 2 + k) * 1024 + rdo)
; #define G_LDB(dst, b, h)                                                                                                  \
;   _Pragma("unroll") for (int n = 0; n < 2; ++n) _Pragma("unroll") for (int k = 0; k < 2; ++k)                             \
;       dst[n][k] = *(const bf16x8*)((const char*)G_SB(b, h) + ((wc * 2 + n) * 2 + k) * 1024 + rdo)
; #define G_WAIT_V(n) asm volatile("s_waitcnt vmcnt(" #n ")" ::: "memory")
; #define G_WAIT_L(n) asm volatile("s_waitcnt lgkmcnt(" #n ")" ::: "memory")
; #define G_BAR __builtin_amdgcn_s_barrier()
;     ...
;     G_LDB(B0, 1, 0); G_LDA(At, 1, 0); G_WAIT_V(2); G_BAR; G_WAIT_L(0); G_MMA(0, 0, At, B0); G_BAR;
;     G_LDB(B1, 1, 1); G_WAIT_V(0); G_BAR; G_WAIT_L(0); G_MMA(0, 1, At, B1); G_BAR;
;     G_LDA(At, 1, 1); G_BAR; G_WAIT_L(0); G_MMA(1, 0, At, B0); G_MMA(1, 1, At, B1); G_BAR;
;   }
;   if (wr == 0) G_BAR;
	ds_read_b128 v[130:133], v145
	ds_read_b128 v[210:213], v145 offset:1024
	ds_read_b128 v[214:217], v145 offset:2048
	ds_read_b128 v[218:221], v145 offset:3072
	s_waitcnt vmcnt(0)
	s_barrier
	s_waitcnt lgkmcnt(0)
	v_mfma_f32_16x16x32_bf16 v[82:85], v[58:61], v[130:133], v[94:97]
	v_mfma_f32_16x16x32_bf16 v[58:61], v[58:61], v[214:217], v[78:81]
	v_mfma_f32_16x16x32_bf16 v[94:97], v[66:69], v[218:221], v[58:61]
	v_mfma_f32_16x16x32_bf16 v[58:61], v[70:73], v[130:133], v[62:65]
	v_mfma_f32_16x16x32_bf16 v[54:57], v[70:73], v[214:217], v[54:57]
	v_mfma_f32_16x16x32_bf16 v[50:53], v[202:205], v[130:133], v[50:53]
	v_mfma_f32_16x16x32_bf16 v[46:49], v[202:205], v[214:217], v[46:49]
	v_mfma_f32_16x16x32_bf16 v[42:45], v[222:225], v[130:133], v[42:45]
	v_mfma_f32_16x16x32_bf16 v[38:41], v[222:225], v[214:217], v[38:41]
	v_mfma_f32_16x16x32_bf16 v[86:89], v[66:69], v[210:213], v[82:85]
	v_mfma_f32_16x16x32_bf16 v[82:85], v[74:77], v[210:213], v[58:61]
	v_mfma_f32_16x16x32_bf16 v[90:93], v[74:77], v[218:221], v[54:57]
	v_mfma_f32_16x16x32_bf16 v[74:77], v[206:209], v[210:213], v[50:53]
	v_mfma_f32_16x16x32_bf16 v[78:81], v[206:209], v[218:221], v[46:49]
	v_mfma_f32_16x16x32_bf16 v[66:69], v[226:229], v[210:213], v[42:45]
	v_mfma_f32_16x16x32_bf16 v[70:73], v[226:229], v[218:221], v[38:41]
	s_barrier
	ds_read_b128 v[202:205], v142 offset:49152
	ds_read_b128 v[206:209], v142 offset:50176
	ds_read_b128 v[222:225], v142 offset:51200
	ds_read_b128 v[226:229], v142 offset:52224
	ds_read_b128 v[230:233], v142 offset:53248
	ds_read_b128 v[234:237], v142 offset:54272
	ds_read_b128 v[238:241], v142 offset:55296
	ds_read_b128 v[142:145], v142 offset:56320
	s_barrier
	s_waitcnt lgkmcnt(0)
	v_mfma_f32_16x16x32_bf16 v[34:37], v[202:205], v[186:189], v[34:37]
	v_mfma_f32_16x16x32_bf16 v[30:33], v[202:205], v[194:197], v[30:33]
	v_mfma_f32_16x16x32_bf16 v[26:29], v[222:225], v[186:189], v[26:29]
	v_mfma_f32_16x16x32_bf16 v[22:25], v[222:225], v[194:197], v[22:25]
	v_mfma_f32_16x16x32_bf16 v[18:21], v[230:233], v[186:189], v[18:21]
	v_mfma_f32_16x16x32_bf16 v[14:17], v[230:233], v[194:197], v[14:17]
	v_mfma_f32_16x16x32_bf16 v[10:13], v[238:241], v[186:189], v[10:13]
	v_mfma_f32_16x16x32_bf16 v[6:9], v[238:241], v[194:197], v[6:9]
	v_mfma_f32_16x16x32_bf16 v[54:57], v[206:209], v[190:193], v[34:37]
	v_mfma_f32_16x16x32_bf16 v[62:65], v[206:209], v[198:201], v[30:33]
	v_mfma_f32_16x16x32_bf16 v[50:53], v[226:229], v[190:193], v[26:29]
	v_mfma_f32_16x16x32_bf16 v[58:61], v[226:229], v[198:201], v[22:25]
	v_mfma_f32_16x16x32_bf16 v[42:45], v[234:237], v[190:193], v[18:21]
	v_mfma_f32_16x16x32_bf16 v[46:49], v[234:237], v[198:201], v[14:17]
	v_mfma_f32_16x16x32_bf16 v[34:37], v[142:145], v[190:193], v[10:13]
	v_mfma_f32_16x16x32_bf16 v[38:41], v[142:145], v[198:201], v[6:9]
	v_mfma_f32_16x16x32_bf16 v[2:5], v[202:205], v[130:133], v[2:5]
	v_mfma_f32_16x16x32_bf16 v[22:25], v[206:209], v[210:213], v[2:5]
	v_mfma_f32_16x16x32_bf16 v[2:5], v[202:205], v[214:217], v[134:137]
	v_mfma_f32_16x16x32_bf16 v[30:33], v[206:209], v[218:221], v[2:5]
	v_mfma_f32_16x16x32_bf16 v[2:5], v[222:225], v[130:133], v[138:141]
	v_mfma_f32_16x16x32_bf16 v[18:21], v[226:229], v[210:213], v[2:5]
	v_mfma_f32_16x16x32_bf16 v[2:5], v[222:225], v[214:217], v[146:149]
	v_mfma_f32_16x16x32_bf16 v[26:29], v[226:229], v[218:221], v[2:5]
	v_mfma_f32_16x16x32_bf16 v[2:5], v[230:233], v[130:133], v[152:155]
	v_mfma_f32_16x16x32_bf16 v[10:13], v[234:237], v[210:213], v[2:5]
	v_mfma_f32_16x16x32_bf16 v[2:5], v[230:233], v[214:217], v[156:159]
	v_mfma_f32_16x16x32_bf16 v[14:17], v[234:237], v[218:221], v[2:5]
	v_mfma_f32_16x16x32_bf16 v[2:5], v[238:241], v[130:133], v[164:167]
	v_mfma_f32_16x16x32_bf16 v[6:9], v[238:241], v[214:217], v[182:185]
	v_mfma_f32_16x16x32_bf16 v[2:5], v[142:145], v[210:213], v[2:5]
	v_mfma_f32_16x16x32_bf16 v[6:9], v[142:145], v[218:221], v[6:9]
	v_cmp_gt_u32_e32 vcc, s67, v0
	s_barrier
	s_and_saveexec_b64 s[16:17], vcc
	s_cbranch_execz .LBB0_43
	s_barrier

; #define G_LDA(dst, b, h)                                                                                                  \
;   _Pragma("unroll") for (int m = 0; m < 4; ++m) _Pragma("unroll") for (int k = 0; k < 2; ++k)                             \
;       dst[m][k] = *(const bf16x8*)((const char*)G_SA(b, h) + ((wr * 4 + m) * 2 + k) * 1024 + rdo)
; #define G_LDB(dst, b, h)                                                                                                  \
;   _Pragma("unroll") for (int n = 0; n < 2; ++n) _Pragma("unroll") for (int k = 0; k < 2; ++k)                             \
;       dst[n][k] = *(const bf16x8*)((const char*)G_SB(b, h) + ((wc * 2 + n) * 2 + k) * 1024 + rdo)
; #define G_WAIT_V(n) asm volatile("s_waitcnt vmcnt(" #n ")" ::: "memory")
; #define G_WAIT_L(n) asm volatile("s_waitcnt lgkmcnt(" #n ")" ::: "memory")
; #define G_BAR __builtin_amdgcn_s_barrier()
; #define G_SCHED __builtin_amdgcn_sched_barrier(0)
;     ...
;   for (int tt = 0; tt < nt - 2; tt += 2) {
;     G_LDB(B0, 0, 0); G_SCHED; G_LDA(At, 0, 0); G_STAGE(G_SA(1, 1), A, oa0, oa1, LDA, 128, KA(tt + 1));
;     G_WAIT_L(8); G_BAR; G_WAIT_L(0); G_MMA(0, 0, At, B0); G_BAR; G_SCHED;
;     G_LDB(B1, 0, 1); G_STAGE(G_SB(0, 0), B, ob0, ob1, LDB, 0, KB(tt + 2));
;     G_BAR; G_WAIT_L(0); G_MMA(0, 1, At, B1); G_BAR;
;     G_LDA(At, 0, 1); G_STAGE(G_SA(0, 0), A, oa0, oa1, LDA, 0, KA(tt + 2));
;     G_BAR; G_WAIT_L(0); G_MMA(1, 0, At, B0); G_BAR; G_SCHED;
;     G_STAGE(G_SB(0, 1), B, ob0, ob1, LDB, 128, KB(tt + 2));
;     G_WAIT_V(6); G_BAR; G_MMA(1, 1, At, B1); G_BAR;
.LBB0_66:
	ds_read_b128 v[164:167], v160
	ds_read_b128 v[182:185], v160 offset:1024
	ds_read_b128 v[186:189], v160 offset:2048
	ds_read_b128 v[190:193], v160 offset:3072
	v_lshl_add_u64 v[242:243], v[136:137], 0, s[22:23]
	v_lshl_add_u64 v[226:227], v[242:243], 0, s[78:79]
	s_add_u32 m0, s32, 0xc000
	v_lshl_add_u64 v[244:245], v[134:135], 0, s[22:23]
	ds_read_b128 v[194:197], v142
	ds_read_b128 v[198:201], v142 offset:1024
	ds_read_b128 v[202:205], v142 offset:2048
	ds_read_b128 v[206:209], v142 offset:3072
	ds_read_b128 v[210:213], v142 offset:4096
	ds_read_b128 v[214:217], v142 offset:5120
	ds_read_b128 v[218:221], v142 offset:6144
	ds_read_b128 v[222:225], v142 offset:7168
	global_load_lds_dwordx4 v[226:227], off
	s_add_u32 m0, s32, 0xe000
	v_lshl_add_u64 v[226:227], v[244:245], 0, s[78:79]
	global_load_lds_dwordx4 v[226:227], off
	s_waitcnt lgkmcnt(8)
	s_barrier
	s_waitcnt lgkmcnt(0)
	v_mfma_f32_16x16x32_bf16 v[126:129], v[194:197], v[164:167], v[126:129]
	v_mfma_f32_16x16x32_bf16 v[122:125], v[194:197], v[186:189], v[122:125]
	v_mfma_f32_16x16x32_bf16 v[118:121], v[202:205], v[164:167], v[118:121]
	v_mfma_f32_16x16x32_bf16 v[114:117], v[202:205], v[186:189], v[114:117]
	v_mfma_f32_16x16x32_bf16 v[110:113], v[210:213], v[164:167], v[110:113]
	v_mfma_f32_16x16x32_bf16 v[106:109], v[210:213], v[186:189], v[106:109]
	v_mfma_f32_16x16x32_bf16 v[102:105], v[218:221], v[164:167], v[102:105]
	v_mfma_f32_16x16x32_bf16 v[98:101], v[218:221], v[186:189], v[98:101]
	v_mfma_f32_16x16x32_bf16 v[126:129], v[198:201], v[182:185], v[126:129]
	v_mfma_f32_16x16x32_bf16 v[122:125], v[198:201], v[190:193], v[122:125]
	v_mfma_f32_16x16x32_bf16 v[118:121], v[206:209], v[182:185], v[118:121]
	v_mfma_f32_16x16x32_bf16 v[114:117], v[206:209], v[190:193], v[114:117]
	v_mfma_f32_16x16x32_bf16 v[110:113], v[214:217], v[182:185], v[110:113]
	v_mfma_f32_16x16x32_bf16 v[106:109], v[214:217], v[190:193], v[106:109]
	v_mfma_f32_16x16x32_bf16 v[102:105], v[222:225], v[182:185], v[102:105]
	v_mfma_f32_16x16x32_bf16 v[98:101], v[222:225], v[190:193], v[98:101]
	s_barrier
	v_lshl_add_u64 v[246:247], v[140:141], 0, s[22:23]
	v_lshl_add_u64 v[248:249], v[246:247], 0, s[48:49]
	s_add_u32 m0, s32, 0x10000
	ds_read_b128 v[226:229], v158
	ds_read_b128 v[230:233], v158 offset:1024
	ds_read_b128 v[234:237], v158 offset:2048
	ds_read_b128 v[238:241], v158 offset:3072
	global_load_lds_dwordx4 v[248:249], off
	v_lshl_add_u64 v[248:249], v[138:139], 0, s[22:23]
	s_add_u32 m0, s32, 0x12000
	v_lshl_add_u64 v[250:251], v[248:249], 0, s[48:49]
	global_load_lds_dwordx4 v[250:251], off
	s_barrier
	s_waitcnt lgkmcnt(0)
	v_mfma_f32_16x16x32_bf16 v[94:97], v[194:197], v[226:229], v[94:97]
	v_mfma_f32_16x16x32_bf16 v[90:93], v[194:197], v[234:237], v[90:93]
	v_mfma_f32_16x16x32_bf16 v[86:89], v[202:205], v[226:229], v[86:89]
	v_mfma_f32_16x16x32_bf16 v[82:85], v[202:205], v[234:237], v[82:85]
	v_mfma_f32_16x16x32_bf16 v[78:81], v[210:213], v[226:229], v[78:81]
	v_mfma_f32_16x16x32_bf16 v[74:77], v[210:213], v[234:237], v[74:77]
	v_mfma_f32_16x16x32_bf16 v[70:73], v[218:221], v[226:229], v[70:73]
	v_mfma_f32_16x16x32_bf16 v[66:69], v[218:221], v[234:237], v[66:69]
	v_mfma_f32_16x16x32_bf16 v[94:97], v[198:201], v[230:233], v[94:97]
	v_mfma_f32_16x16x32_bf16 v[90:93], v[198:201], v[238:241], v[90:93]
	v_mfma_f32_16x16x32_bf16 v[86:89], v[206:209], v[230:233], v[86:89]
	v_mfma_f32_16x16x32_bf16 v[82:85], v[206:209], v[238:241], v[82:85]
	v_mfma_f32_16x16x32_bf16 v[78:81], v[214:217], v[230:233], v[78:81]
	v_mfma_f32_16x16x32_bf16 v[74:77], v[214:217], v[238:241], v[74:77]
	v_mfma_f32_16x16x32_bf16 v[70:73], v[222:225], v[230:233], v[70:73]
	v_mfma_f32_16x16x32_bf16 v[66:69], v[222:225], v[238:241], v[66:69]
	v_lshl_add_u64 v[250:251], v[242:243], 0, s[82:83]
	s_mov_b32 m0, s32
	s_barrier
	ds_read_b128 v[194:197], v142 offset:16384
	ds_read_b128 v[198:201], v142 offset:17408
	ds_read_b128 v[202:205], v142 offset:18432
	ds_read_b128 v[206:209], v142 offset:19456
	ds_read_b128 v[210:213], v142 offset:20480
	ds_read_b128 v[214:217], v142 offset:21504
	ds_read_b128 v[218:221], v142 offset:22528
	ds_read_b128 v[222:225], v142 offset:23552
	global_load_lds_dwordx4 v[250:251], off
	s_add_u32 m0, s32, 0x1f00
	s_nop 0
	global_load_lds_dwordx4 v[244:245], off offset:256
	s_barrier
	s_waitcnt lgkmcnt(0)
	v_mfma_f32_16x16x32_bf16 v[62:65], v[194:197], v[164:167], v[62:65]
	v_mfma_f32_16x16x32_bf16 v[58:61], v[194:197], v[186:189], v[58:61]
	v_mfma_f32_16x16x32_bf16 v[54:57], v[202:205], v[164:167], v[54:57]
	v_mfma_f32_16x16x32_bf16 v[50:53], v[202:205], v[186:189], v[50:53]
	v_mfma_f32_16x16x32_bf16 v[46:49], v[210:213], v[164:167], v[46:49]
	v_mfma_f32_16x16x32_bf16 v[42:45], v[210:213], v[186:189], v[42:45]
	v_mfma_f32_16x16x32_bf16 v[38:41], v[218:221], v[164:167], v[38:41]
	v_mfma_f32_16x16x32_bf16 v[34:37], v[218:221], v[186:189], v[34:37]
	v_mfma_f32_16x16x32_bf16 v[62:65], v[198:201], v[182:185], v[62:65]
	v_mfma_f32_16x16x32_bf16 v[58:61], v[198:201], v[190:193], v[58:61]
	v_mfma_f32_16x16x32_bf16 v[54:57], v[206:209], v[182:185], v[54:57]
	v_mfma_f32_16x16x32_bf16 v[50:53], v[206:209], v[190:193], v[50:53]
	v_mfma_f32_16x16x32_bf16 v[46:49], v[214:217], v[182:185], v[46:49]
	v_mfma_f32_16x16x32_bf16 v[42:45], v[214:217], v[190:193], v[42:45]
	v_mfma_f32_16x16x32_bf16 v[38:41], v[222:225], v[182:185], v[38:41]
	v_mfma_f32_16x16x32_bf16 v[34:37], v[222:225], v[190:193], v[34:37]
	s_barrier
	v_lshl_add_u64 v[164:165], v[246:247], 0, s[24:25]
	s_add_u32 m0, s32, 0x14000
	s_nop 0
	global_load_lds_dwordx4 v[164:165], off
	s_add_u32 m0, s32, 0x16000
	v_lshl_add_u64 v[164:165], v[248:249], 0, s[24:25]
	global_load_lds_dwordx4 v[164:165], off
	s_waitcnt vmcnt(6)
	s_barrier
; #define G_LDA(dst, b, h)                                                                                                  \
;   _Pragma("unroll") for (int m = 0; m < 4; ++m) _Pragma("unroll") for (int k = 0; k < 2; ++k)                             \
;       dst[m][k] = *(const bf16x8*)((const char*)G_SA(b, h) + ((wr * 4 + m) * 2 + k) * 1024 + rdo)
; #define G_LDB(dst, b, h)                                                                                                  \
;   _Pragma("unroll") for (int n = 0; n < 2; ++n) _Pragma("unroll") for (int k = 0; k < 2; ++k)                             \
;       dst[n][k] = *(const bf16x8*)((const char*)G_SB(b, h) + ((wc * 2 + n) * 2 + k) * 1024 + rdo)
; #define G_WAIT_V(n) asm volatile("s_waitcnt vmcnt(" #n ")" ::: "memory")
; #define G_WAIT_L(n) asm volatile("s_waitcnt lgkmcnt(" #n ")" ::: "memory")
; #define G_BAR __builtin_amdgcn_s_barrier()
; #define G_SCHED __builtin_amdgcn_sched_barrier(0)
;     ...
;     G_WAIT_V(6); G_BAR; G_MMA(1, 1, At, B1); G_BAR;
;     G_LDB(B0, 1, 0); G_SCHED; G_LDA(At, 1, 0); G_STAGE(G_SA(0, 1), A, oa0, oa1, LDA, 128, KA(tt + 2));
;     G_WAIT_L(8); G_BAR; G_WAIT_L(0); G_MMA(0, 0, At, B0); G_BAR; G_SCHED;
;     G_LDB(B1, 1, 1); G_STAGE(G_SB(1, 0), B, ob0, ob1, LDB, 0, KB(tt + 3));
;     G_BAR; G_WAIT_L(0); G_MMA(0, 1, At, B1); G_BAR;
;     G_LDA(At, 1, 1); G_STAGE(G_SA(1, 0), A, oa0, oa1, LDA, 0, KA(tt + 3));
	v_mfma_f32_16x16x32_bf16 v[30:33], v[194:197], v[226:229], v[30:33]
	v_mfma_f32_16x16x32_bf16 v[26:29], v[194:197], v[234:237], v[26:29]
	v_mfma_f32_16x16x32_bf16 v[22:25], v[202:205], v[226:229], v[22:25]
	v_mfma_f32_16x16x32_bf16 v[18:21], v[202:205], v[234:237], v[18:21]
	v_mfma_f32_16x16x32_bf16 v[14:17], v[210:213], v[226:229], v[14:17]
	v_mfma_f32_16x16x32_bf16 v[10:13], v[210:213], v[234:237], v[10:13]
	v_mfma_f32_16x16x32_bf16 v[6:9], v[218:221], v[226:229], v[6:9]
	v_mfma_f32_16x16x32_bf16 v[2:5], v[218:221], v[234:237], v[2:5]
	v_mfma_f32_16x16x32_bf16 v[30:33], v[198:201], v[230:233], v[30:33]
	v_mfma_f32_16x16x32_bf16 v[26:29], v[198:201], v[238:241], v[26:29]
	v_mfma_f32_16x16x32_bf16 v[22:25], v[206:209], v[230:233], v[22:25]
	v_mfma_f32_16x16x32_bf16 v[18:21], v[206:209], v[238:241], v[18:21]
	v_mfma_f32_16x16x32_bf16 v[14:17], v[214:217], v[230:233], v[14:17]
	v_mfma_f32_16x16x32_bf16 v[10:13], v[214:217], v[238:241], v[10:13]
	v_mfma_f32_16x16x32_bf16 v[6:9], v[222:225], v[230:233], v[6:9]
	v_mfma_f32_16x16x32_bf16 v[2:5], v[222:225], v[238:241], v[2:5]
	s_barrier
	ds_read_b128 v[164:167], v149
	ds_read_b128 v[182:185], v149 offset:1024
	ds_read_b128 v[186:189], v149 offset:2048
	ds_read_b128 v[190:193], v149 offset:3072
	v_lshl_add_u64 v[226:227], v[242:243], 0, s[86:87]
	s_add_u32 m0, s32, 0x4000
	ds_read_b128 v[194:197], v142 offset:32768
	ds_read_b128 v[198:201], v142 offset:33792
	ds_read_b128 v[202:205], v142 offset:34816
	ds_read_b128 v[206:209], v142 offset:35840
	ds_read_b128 v[210:213], v142 offset:36864
	ds_read_b128 v[214:217], v142 offset:37888
	ds_read_b128 v[218:221], v142 offset:38912
	ds_read_b128 v[222:225], v142 offset:39936
	global_load_lds_dwordx4 v[226:227], off
	s_add_u32 m0, s32, 0x6000
	v_lshl_add_u64 v[226:227], v[244:245], 0, s[86:87]
	global_load_lds_dwordx4 v[226:227], off
	s_waitcnt lgkmcnt(8)
	s_barrier
	s_waitcnt lgkmcnt(0)
	v_mfma_f32_16x16x32_bf16 v[126:129], v[194:197], v[164:167], v[126:129]
	v_mfma_f32_16x16x32_bf16 v[122:125], v[194:197], v[186:189], v[122:125]
	v_mfma_f32_16x16x32_bf16 v[118:121], v[202:205], v[164:167], v[118:121]
	v_mfma_f32_16x16x32_bf16 v[114:117], v[202:205], v[186:189], v[114:117]
	v_mfma_f32_16x16x32_bf16 v[110:113], v[210:213], v[164:167], v[110:113]
	v_mfma_f32_16x16x32_bf16 v[106:109], v[210:213], v[186:189], v[106:109]
	v_mfma_f32_16x16x32_bf16 v[102:105], v[218:221], v[164:167], v[102:105]
	v_mfma_f32_16x16x32_bf16 v[98:101], v[218:221], v[186:189], v[98:101]
	v_mfma_f32_16x16x32_bf16 v[126:129], v[198:201], v[182:185], v[126:129]
	v_mfma_f32_16x16x32_bf16 v[122:125], v[198:201], v[190:193], v[122:125]
	v_mfma_f32_16x16x32_bf16 v[118:121], v[206:209], v[182:185], v[118:121]
	v_mfma_f32_16x16x32_bf16 v[114:117], v[206:209], v[190:193], v[114:117]
	v_mfma_f32_16x16x32_bf16 v[110:113], v[214:217], v[182:185], v[110:113]
	v_mfma_f32_16x16x32_bf16 v[106:109], v[214:217], v[190:193], v[106:109]
	v_mfma_f32_16x16x32_bf16 v[102:105], v[222:225], v[182:185], v[102:105]
	v_mfma_f32_16x16x32_bf16 v[98:101], v[222:225], v[190:193], v[98:101]
	s_barrier
	v_lshl_add_u64 v[250:251], v[246:247], 0, s[26:27]
	s_add_u32 m0, s32, 0x18000
	ds_read_b128 v[226:229], v145
	ds_read_b128 v[230:233], v145 offset:1024
	ds_read_b128 v[234:237], v145 offset:2048
	ds_read_b128 v[238:241], v145 offset:3072
	global_load_lds_dwordx4 v[250:251], off
	s_add_u32 m0, s32, 0x1a000
	v_lshl_add_u64 v[250:251], v[248:249], 0, s[26:27]
	global_load_lds_dwordx4 v[250:251], off
	s_barrier
	s_waitcnt lgkmcnt(0)
	v_mfma_f32_16x16x32_bf16 v[94:97], v[194:197], v[226:229], v[94:97]
	v_mfma_f32_16x16x32_bf16 v[90:93], v[194:197], v[234:237], v[90:93]
	v_mfma_f32_16x16x32_bf16 v[86:89], v[202:205], v[226:229], v[86:89]
	v_mfma_f32_16x16x32_bf16 v[82:85], v[202:205], v[234:237], v[82:85]
	v_mfma_f32_16x16x32_bf16 v[78:81], v[210:213], v[226:229], v[78:81]
	v_mfma_f32_16x16x32_bf16 v[74:77], v[210:213], v[234:237], v[74:77]
	v_mfma_f32_16x16x32_bf16 v[70:73], v[218:221], v[226:229], v[70:73]
	v_mfma_f32_16x16x32_bf16 v[66:69], v[218:221], v[234:237], v[66:69]
	v_mfma_f32_16x16x32_bf16 v[94:97], v[198:201], v[230:233], v[94:97]
	v_mfma_f32_16x16x32_bf16 v[90:93], v[198:201], v[238:241], v[90:93]
	v_mfma_f32_16x16x32_bf16 v[86:89], v[206:209], v[230:233], v[86:89]
	v_mfma_f32_16x16x32_bf16 v[82:85], v[206:209], v[238:241], v[82:85]
	v_mfma_f32_16x16x32_bf16 v[78:81], v[214:217], v[230:233], v[78:81]
	v_mfma_f32_16x16x32_bf16 v[74:77], v[214:217], v[238:241], v[74:77]
	v_mfma_f32_16x16x32_bf16 v[70:73], v[222:225], v[230:233], v[70:73]
	v_mfma_f32_16x16x32_bf16 v[66:69], v[222:225], v[238:241], v[66:69]
	s_add_u32 m0, s32, 0x7e80
	s_barrier
	ds_read_b128 v[194:197], v142 offset:49152
	ds_read_b128 v[198:201], v142 offset:50176
	ds_read_b128 v[202:205], v142 offset:51200
	ds_read_b128 v[206:209], v142 offset:52224
	ds_read_b128 v[210:213], v142 offset:53248
	ds_read_b128 v[214:217], v142 offset:54272
	ds_read_b128 v[218:221], v142 offset:55296
	ds_read_b128 v[222:225], v142 offset:56320
	global_load_lds_dwordx4 v[242:243], off offset:384
	s_add_u32 m0, s32, 0xa000
	v_lshl_add_u64 v[242:243], v[244:245], 0, s[90:91]
	global_load_lds_dwordx4 v[242:243], off
	s_barrier
; #define G_LDA(dst, b, h)                                                                                                  \
;   _Pragma("unroll") for (int m = 0; m < 4; ++m) _Pragma("unroll") for (int k = 0; k < 2; ++k)                             \
;       dst[m][k] = *(const bf16x8*)((const char*)G_SA(b, h) + ((wr * 4 + m) * 2 + k) * 1024 + rdo)
; #define G_LDB(dst, b, h)                                                                                                  \
;   _Pragma("unroll") for (int n = 0; n < 2; ++n) _Pragma("unroll") for (int k = 0; k < 2; ++k)                             \
;       dst[n][k] = *(const bf16x8*)((const char*)G_SB(b, h) + ((wc * 2 + n) * 2 + k) * 1024 + rdo)
; #define G_WAIT_V(n) asm volatile("s_waitcnt vmcnt(" #n ")" ::: "memory")
; #define G_WAIT_L(n) asm volatile("s_waitcnt lgkmcnt(" #n ")" ::: "memory")
; #define G_BAR __builtin_amdgcn_s_barrier()
; #define G_SCHED __builtin_amdgcn_sched_barrier(0)
; DI void br_flush(PREF p, f32x4 (&acc)[2][2][4][2], int slot) { br_store(p, acc, slot); zero_acc256(acc); }
;     ...
;     G_BAR; G_WAIT_L(0); G_MMA(1, 0, At, B0); G_BAR; G_SCHED;
;     G_STAGE(G_SB(1, 1), B, ob0, ob1, LDB, 128, KB(tt + 3));
;     G_WAIT_V(6); G_BAR; G_MMA(1, 1, At, B1); G_BAR;
;     if (MODE && ((tt + 1) & 3) == 3) br_flush(p, acc, (tt + 1) >> 2);
;   }
;   {
;     G_LDB(B0, 0, 0); G_LDA(At, 0, 0); G_STAGE(G_SA(1, 1), A, oa0, oa1, LDA, 128, KA(nt - 1));
;     G_BAR; G_WAIT_L(0); G_MMA(0, 0, At, B0); G_BAR;
;     G_LDB(B1, 0, 1); G_BAR; G_WAIT_L(0); G_MMA(0, 1, At, B1); G_BAR;
	s_waitcnt lgkmcnt(0)
	v_mfma_f32_16x16x32_bf16 v[62:65], v[194:197], v[164:167], v[62:65]
	v_mfma_f32_16x16x32_bf16 v[58:61], v[194:197], v[186:189], v[58:61]
	v_mfma_f32_16x16x32_bf16 v[54:57], v[202:205], v[164:167], v[54:57]
	v_mfma_f32_16x16x32_bf16 v[50:53], v[202:205], v[186:189], v[50:53]
	v_mfma_f32_16x16x32_bf16 v[46:49], v[210:213], v[164:167], v[46:49]
	v_mfma_f32_16x16x32_bf16 v[42:45], v[210:213], v[186:189], v[42:45]
	v_mfma_f32_16x16x32_bf16 v[38:41], v[218:221], v[164:167], v[38:41]
	v_mfma_f32_16x16x32_bf16 v[34:37], v[218:221], v[186:189], v[34:37]
	v_mfma_f32_16x16x32_bf16 v[62:65], v[198:201], v[182:185], v[62:65]
	v_mfma_f32_16x16x32_bf16 v[58:61], v[198:201], v[190:193], v[58:61]
	v_mfma_f32_16x16x32_bf16 v[54:57], v[206:209], v[182:185], v[54:57]
	v_mfma_f32_16x16x32_bf16 v[50:53], v[206:209], v[190:193], v[50:53]
	v_mfma_f32_16x16x32_bf16 v[46:49], v[214:217], v[182:185], v[46:49]
	v_mfma_f32_16x16x32_bf16 v[42:45], v[214:217], v[190:193], v[42:45]
	v_mfma_f32_16x16x32_bf16 v[38:41], v[222:225], v[182:185], v[38:41]
	v_mfma_f32_16x16x32_bf16 v[34:37], v[222:225], v[190:193], v[34:37]
	s_barrier
	v_lshl_add_u64 v[164:165], v[246:247], 0, s[36:37]
	s_add_u32 m0, s32, 0x1c000
	s_nop 0
	global_load_lds_dwordx4 v[164:165], off
	s_add_u32 m0, s32, 0x1e000
	v_lshl_add_u64 v[164:165], v[248:249], 0, s[36:37]
	global_load_lds_dwordx4 v[164:165], off
	s_waitcnt vmcnt(6)
	s_barrier
	v_mfma_f32_16x16x32_bf16 v[30:33], v[194:197], v[226:229], v[30:33]
	v_mfma_f32_16x16x32_bf16 v[26:29], v[194:197], v[234:237], v[26:29]
	v_mfma_f32_16x16x32_bf16 v[22:25], v[202:205], v[226:229], v[22:25]
	v_mfma_f32_16x16x32_bf16 v[18:21], v[202:205], v[234:237], v[18:21]
	v_mfma_f32_16x16x32_bf16 v[14:17], v[210:213], v[226:229], v[14:17]
	v_mfma_f32_16x16x32_bf16 v[10:13], v[210:213], v[234:237], v[10:13]
	v_mfma_f32_16x16x32_bf16 v[6:9], v[218:221], v[226:229], v[6:9]
	v_mfma_f32_16x16x32_bf16 v[2:5], v[218:221], v[234:237], v[2:5]
	v_mfma_f32_16x16x32_bf16 v[30:33], v[198:201], v[230:233], v[30:33]
	v_mfma_f32_16x16x32_bf16 v[26:29], v[198:201], v[238:241], v[26:29]
	v_mfma_f32_16x16x32_bf16 v[22:25], v[206:209], v[230:233], v[22:25]
	v_mfma_f32_16x16x32_bf16 v[18:21], v[206:209], v[238:241], v[18:21]
	v_mfma_f32_16x16x32_bf16 v[14:17], v[214:217], v[230:233], v[14:17]
	v_mfma_f32_16x16x32_bf16 v[10:13], v[214:217], v[238:241], v[10:13]
	v_mfma_f32_16x16x32_bf16 v[6:9], v[222:225], v[230:233], v[6:9]
	v_mfma_f32_16x16x32_bf16 v[2:5], v[222:225], v[238:241], v[2:5]
	s_add_i32 s9, s9, 2
	s_add_u32 s22, s22, 0x100
	s_addc_u32 s23, s23, 0
	s_cmp_lt_u32 s9, 12
	s_barrier
	s_cbranch_scc1 .LBB0_66
	s_add_u32 s0, s20, 0x40780
	s_addc_u32 s1, s21, 0
	v_lshl_add_u64 v[132:133], v[132:133], 1, s[0:1]
	s_add_u32 m0, s32, 0xc000
	v_lshl_add_u64 v[130:131], v[130:131], 1, s[0:1]
	ds_read_b128 v[134:137], v160
	ds_read_b128 v[138:141], v160 offset:1024
	ds_read_b128 v[150:153], v160 offset:2048
	ds_read_b128 v[154:157], v160 offset:3072
	ds_read_b128 v[164:167], v142
	ds_read_b128 v[182:185], v142 offset:1024
	ds_read_b128 v[186:189], v142 offset:2048
	ds_read_b128 v[190:193], v142 offset:3072
	ds_read_b128 v[194:197], v142 offset:4096
	ds_read_b128 v[198:201], v142 offset:5120
	ds_read_b128 v[202:205], v142 offset:6144
	ds_read_b128 v[206:209], v142 offset:7168
	global_load_lds_dwordx4 v[132:133], off
	s_add_u32 m0, s32, 0xe000
	s_nop 0
	global_load_lds_dwordx4 v[130:131], off
	s_barrier
	s_waitcnt lgkmcnt(0)
	v_mfma_f32_16x16x32_bf16 v[126:129], v[164:167], v[134:137], v[126:129]
	v_mfma_f32_16x16x32_bf16 v[122:125], v[164:167], v[150:153], v[122:125]
	v_mfma_f32_16x16x32_bf16 v[110:113], v[194:197], v[134:137], v[110:113]
	v_mfma_f32_16x16x32_bf16 v[102:105], v[202:205], v[134:137], v[102:105]
	v_mfma_f32_16x16x32_bf16 v[126:129], v[182:185], v[138:141], v[126:129]
	v_mfma_f32_16x16x32_bf16 v[122:125], v[182:185], v[154:157], v[122:125]
	v_mfma_f32_16x16x32_bf16 v[118:121], v[186:189], v[134:137], v[118:121]
	v_mfma_f32_16x16x32_bf16 v[114:117], v[186:189], v[150:153], v[114:117]
	v_mfma_f32_16x16x32_bf16 v[110:113], v[198:201], v[138:141], v[110:113]
	v_mfma_f32_16x16x32_bf16 v[106:109], v[194:197], v[150:153], v[106:109]
	v_mfma_f32_16x16x32_bf16 v[102:105], v[206:209], v[138:141], v[102:105]
	v_mfma_f32_16x16x32_bf16 v[98:101], v[202:205], v[150:153], v[98:101]
	v_mfma_f32_16x16x32_bf16 v[130:133], v[190:193], v[138:141], v[118:121]
	v_mfma_f32_16x16x32_bf16 v[210:213], v[190:193], v[154:157], v[114:117]
	v_mfma_f32_16x16x32_bf16 v[214:217], v[198:201], v[154:157], v[106:109]
	v_mfma_f32_16x16x32_bf16 v[218:221], v[206:209], v[154:157], v[98:101]
	s_barrier
	s_nop 1
	s_nop 0
	ds_read_b128 v[98:101], v158
	ds_read_b128 v[106:109], v158 offset:1024
	ds_read_b128 v[114:117], v158 offset:2048
	ds_read_b128 v[118:121], v158 offset:3072
	s_barrier
	s_waitcnt lgkmcnt(0)
	v_mfma_f32_16x16x32_bf16 v[94:97], v[164:167], v[98:101], v[94:97]
	v_mfma_f32_16x16x32_bf16 v[90:93], v[164:167], v[114:117], v[90:93]
	v_mfma_f32_16x16x32_bf16 v[78:81], v[194:197], v[98:101], v[78:81]
	v_mfma_f32_16x16x32_bf16 v[70:73], v[202:205], v[98:101], v[70:73]
	v_mfma_f32_16x16x32_bf16 v[94:97], v[182:185], v[106:109], v[94:97]
	v_mfma_f32_16x16x32_bf16 v[90:93], v[182:185], v[118:121], v[90:93]
	v_mfma_f32_16x16x32_bf16 v[86:89], v[186:189], v[98:101], v[86:89]
	v_mfma_f32_16x16x32_bf16 v[82:85], v[186:189], v[114:117], v[82:85]
	v_mfma_f32_16x16x32_bf16 v[78:81], v[198:201], v[106:109], v[78:81]
	v_mfma_f32_16x16x32_bf16 v[74:77], v[194:197], v[114:117], v[74:77]
	v_mfma_f32_16x16x32_bf16 v[70:73], v[206:209], v[106:109], v[70:73]
	v_mfma_f32_16x16x32_bf16 v[66:69], v[202:205], v[114:117], v[66:69]
	v_mfma_f32_16x16x32_bf16 v[158:161], v[190:193], v[106:109], v[86:89]
	v_mfma_f32_16x16x32_bf16 v[164:167], v[190:193], v[118:121], v[82:85]
	v_mfma_f32_16x16x32_bf16 v[182:185], v[198:201], v[118:121], v[74:77]
	v_mfma_f32_16x16x32_bf16 v[186:189], v[206:209], v[118:121], v[66:69]
	s_barrier
; #define G_LDA(dst, b, h)                                                                                                  \
;   _Pragma("unroll") for (int m = 0; m < 4; ++m) _Pragma("unroll") for (int k = 0; k < 2; ++k)                             \
;       dst[m][k] = *(const bf16x8*)((const char*)G_SA(b, h) + ((wr * 4 + m) * 2 + k) * 1024 + rdo)
; #define G_LDB(dst, b, h)                                                                                                  \
;   _Pragma("unroll") for (int n = 0; n < 2; ++n) _Pragma("unroll") for (int k = 0; k < 2; ++k)                             \
;       dst[n][k] = *(const bf16x8*)((const char*)G_SB(b, h) + ((wc * 2 + n) * 2 + k) * 1024 + rdo)
; #define G_WAIT_V(n) asm volatile("s_waitcnt vmcnt(" #n ")" ::: "memory")
; #define G_WAIT_L(n) asm volatile("s_waitcnt lgkmcnt(" #n ")" ::: "memory")
; #define G_BAR __builtin_amdgcn_s_barrier()
;     ...
;     G_LDB(B1, 0, 1); G_BAR; G_WAIT_L(0); G_MMA(0, 1, At, B1); G_BAR;
;     G_LDA(At, 0, 1); G_WAIT_V(4); G_BAR; G_WAIT_L(0); G_MMA(1, 0, At, B0); G_MMA(1, 1, At, B1); G_BAR;
;   }
;   {
;     G_LDB(B0, 1, 0); G_LDA(At, 1, 0); G_WAIT_V(2); G_BAR; G_WAIT_L(0); G_MMA(0, 0, At, B0); G_BAR;
	s_nop 1
	s_nop 0
	ds_read_b128 v[66:69], v142 offset:16384
	ds_read_b128 v[74:77], v142 offset:17408
	ds_read_b128 v[82:85], v142 offset:18432
	ds_read_b128 v[86:89], v142 offset:19456
	ds_read_b128 v[190:193], v142 offset:20480
	ds_read_b128 v[194:197], v142 offset:21504
	ds_read_b128 v[198:201], v142 offset:22528
	ds_read_b128 v[202:205], v142 offset:23552
	s_waitcnt vmcnt(4)
	s_barrier
	s_waitcnt lgkmcnt(0)
	v_mfma_f32_16x16x32_bf16 v[62:65], v[66:69], v[134:137], v[62:65]
	v_mfma_f32_16x16x32_bf16 v[58:61], v[66:69], v[150:153], v[58:61]
	v_mfma_f32_16x16x32_bf16 v[46:49], v[190:193], v[134:137], v[46:49]
	v_mfma_f32_16x16x32_bf16 v[38:41], v[198:201], v[134:137], v[38:41]
	v_mfma_f32_16x16x32_bf16 v[62:65], v[74:77], v[138:141], v[62:65]
	v_mfma_f32_16x16x32_bf16 v[58:61], v[74:77], v[154:157], v[58:61]
	v_mfma_f32_16x16x32_bf16 v[54:57], v[82:85], v[134:137], v[54:57]
	v_mfma_f32_16x16x32_bf16 v[50:53], v[82:85], v[150:153], v[50:53]
	v_mfma_f32_16x16x32_bf16 v[46:49], v[194:197], v[138:141], v[46:49]
	v_mfma_f32_16x16x32_bf16 v[42:45], v[190:193], v[150:153], v[42:45]
	v_mfma_f32_16x16x32_bf16 v[38:41], v[202:205], v[138:141], v[38:41]
	v_mfma_f32_16x16x32_bf16 v[34:37], v[198:201], v[150:153], v[34:37]
	v_mfma_f32_16x16x32_bf16 v[206:209], v[86:89], v[138:141], v[54:57]
	v_mfma_f32_16x16x32_bf16 v[222:225], v[86:89], v[154:157], v[50:53]
	v_mfma_f32_16x16x32_bf16 v[226:229], v[194:197], v[154:157], v[42:45]
	v_mfma_f32_16x16x32_bf16 v[134:137], v[202:205], v[154:157], v[34:37]
	v_mfma_f32_16x16x32_bf16 v[30:33], v[66:69], v[98:101], v[30:33]
	v_mfma_f32_16x16x32_bf16 v[26:29], v[66:69], v[114:117], v[26:29]
	v_mfma_f32_16x16x32_bf16 v[14:17], v[190:193], v[98:101], v[14:17]
	v_mfma_f32_16x16x32_bf16 v[6:9], v[198:201], v[98:101], v[6:9]
	v_mfma_f32_16x16x32_bf16 v[30:33], v[74:77], v[106:109], v[30:33]
	v_mfma_f32_16x16x32_bf16 v[26:29], v[74:77], v[118:121], v[26:29]
	v_mfma_f32_16x16x32_bf16 v[22:25], v[82:85], v[98:101], v[22:25]
	v_mfma_f32_16x16x32_bf16 v[18:21], v[82:85], v[114:117], v[18:21]
	v_mfma_f32_16x16x32_bf16 v[14:17], v[194:197], v[106:109], v[14:17]
	v_mfma_f32_16x16x32_bf16 v[10:13], v[190:193], v[114:117], v[10:13]
	v_mfma_f32_16x16x32_bf16 v[6:9], v[202:205], v[106:109], v[6:9]
	v_mfma_f32_16x16x32_bf16 v[2:5], v[198:201], v[114:117], v[2:5]
	v_mfma_f32_16x16x32_bf16 v[138:141], v[86:89], v[106:109], v[22:25]
	v_mfma_f32_16x16x32_bf16 v[150:153], v[86:89], v[118:121], v[18:21]
	v_mfma_f32_16x16x32_bf16 v[154:157], v[194:197], v[118:121], v[10:13]
	v_mfma_f32_16x16x32_bf16 v[190:193], v[202:205], v[118:121], v[2:5]
	s_barrier
	s_nop 1
	s_nop 0
	ds_read_b128 v[2:5], v149
	ds_read_b128 v[10:13], v149 offset:1024
	ds_read_b128 v[18:21], v149 offset:2048
	ds_read_b128 v[22:25], v149 offset:3072
	ds_read_b128 v[34:37], v142 offset:32768
	ds_read_b128 v[42:45], v142 offset:33792
	ds_read_b128 v[50:53], v142 offset:34816
	ds_read_b128 v[54:57], v142 offset:35840
	ds_read_b128 v[66:69], v142 offset:36864
	ds_read_b128 v[146:149], v142 offset:37888
	ds_read_b128 v[194:197], v142 offset:38912
	ds_read_b128 v[198:201], v142 offset:39936
	s_waitcnt vmcnt(2)
	s_barrier
	s_waitcnt lgkmcnt(0)
	v_mfma_f32_16x16x32_bf16 v[74:77], v[34:37], v[2:5], v[126:129]
	v_mfma_f32_16x16x32_bf16 v[118:121], v[42:45], v[10:13], v[74:77]
	v_mfma_f32_16x16x32_bf16 v[74:77], v[34:37], v[18:21], v[122:125]
	v_mfma_f32_16x16x32_bf16 v[126:129], v[42:45], v[22:25], v[74:77]
	v_mfma_f32_16x16x32_bf16 v[74:77], v[50:53], v[2:5], v[130:133]
	v_mfma_f32_16x16x32_bf16 v[114:117], v[54:57], v[10:13], v[74:77]
	v_mfma_f32_16x16x32_bf16 v[74:77], v[50:53], v[18:21], v[210:213]
	v_mfma_f32_16x16x32_bf16 v[122:125], v[54:57], v[22:25], v[74:77]
	v_mfma_f32_16x16x32_bf16 v[74:77], v[66:69], v[2:5], v[110:113]
	v_mfma_f32_16x16x32_bf16 v[106:109], v[146:149], v[10:13], v[74:77]
	v_mfma_f32_16x16x32_bf16 v[74:77], v[66:69], v[18:21], v[214:217]
	v_mfma_f32_16x16x32_bf16 v[110:113], v[146:149], v[22:25], v[74:77]
	v_mfma_f32_16x16x32_bf16 v[74:77], v[194:197], v[2:5], v[102:105]
	v_mfma_f32_16x16x32_bf16 v[98:101], v[198:201], v[10:13], v[74:77]
	v_mfma_f32_16x16x32_bf16 v[74:77], v[194:197], v[18:21], v[218:221]
	v_mfma_f32_16x16x32_bf16 v[102:105], v[198:201], v[22:25], v[74:77]
	s_barrier
; #define G_LDA(dst, b, h)                                                                                                  \
;   _Pragma("unroll") for (int m = 0; m < 4; ++m) _Pragma("unroll") for (int k = 0; k < 2; ++k)                             \
;       dst[m][k] = *(const bf16x8*)((const char*)G_SA(b, h) + ((wr * 4 + m) * 2 + k) * 1024 + rdo)
; #define G_LDB(dst, b, h)                                                                                                  \
;   _Pragma("unroll") for (int n = 0; n < 2; ++n) _Pragma("unroll") for (int k = 0; k < 2; ++k)                             \
;       dst[n][k] = *(const bf16x8*)((const char*)G_SB(b, h) + ((wc * 2 + n) * 2 + k) * 1024 + rdo)
; #define G_WAIT_V(n) asm volatile("s_waitcnt vmcnt(" #n ")" ::: "memory")
; #define G_WAIT_L(n) asm volatile("s_waitcnt lgkmcnt(" #n ")" ::: "memory")
; #define G_BAR __builtin_amdgcn_s_barrier()
;     ...
;     G_LDB(B0, 1, 0); G_LDA(At, 1, 0); G_WAIT_V(2); G_BAR; G_WAIT_L(0); G_MMA(0, 0, At, B0); G_BAR;
;     G_LDB(B1, 1, 1); G_WAIT_V(0); G_BAR; G_WAIT_L(0); G_MMA(0, 1, At, B1); G_BAR;
;     G_LDA(At, 1, 1); G_BAR; G_WAIT_L(0); G_MMA(1, 0, At, B0); G_MMA(1, 1, At, B1); G_BAR;
;   }
;   if (wr == 0) G_BAR;
	ds_read_b128 v[130:133], v145
	ds_read_b128 v[202:205], v145 offset:1024
	ds_read_b128 v[210:213], v145 offset:2048
	ds_read_b128 v[214:217], v145 offset:3072
	s_waitcnt vmcnt(0)
	s_barrier
	s_waitcnt lgkmcnt(0)
	v_mfma_f32_16x16x32_bf16 v[74:77], v[34:37], v[130:133], v[94:97]
	v_mfma_f32_16x16x32_bf16 v[34:37], v[34:37], v[210:213], v[90:93]
	v_mfma_f32_16x16x32_bf16 v[94:97], v[42:45], v[214:217], v[34:37]
	v_mfma_f32_16x16x32_bf16 v[34:37], v[50:53], v[130:133], v[158:161]
	v_mfma_f32_16x16x32_bf16 v[82:85], v[54:57], v[202:205], v[34:37]
	v_mfma_f32_16x16x32_bf16 v[34:37], v[50:53], v[210:213], v[164:167]
	v_mfma_f32_16x16x32_bf16 v[90:93], v[54:57], v[214:217], v[34:37]
	v_mfma_f32_16x16x32_bf16 v[34:37], v[66:69], v[130:133], v[78:81]
	v_mfma_f32_16x16x32_bf16 v[86:89], v[42:45], v[202:205], v[74:77]
	v_mfma_f32_16x16x32_bf16 v[74:77], v[146:149], v[202:205], v[34:37]
	v_mfma_f32_16x16x32_bf16 v[34:37], v[66:69], v[210:213], v[182:185]
	v_mfma_f32_16x16x32_bf16 v[78:81], v[146:149], v[214:217], v[34:37]
	v_mfma_f32_16x16x32_bf16 v[34:37], v[194:197], v[130:133], v[70:73]
	v_mfma_f32_16x16x32_bf16 v[66:69], v[198:201], v[202:205], v[34:37]
	v_mfma_f32_16x16x32_bf16 v[34:37], v[194:197], v[210:213], v[186:189]
	v_mfma_f32_16x16x32_bf16 v[70:73], v[198:201], v[214:217], v[34:37]
	s_barrier
	ds_read_b128 v[144:147], v142 offset:49152
	ds_read_b128 v[158:161], v142 offset:50176
	ds_read_b128 v[164:167], v142 offset:51200
	ds_read_b128 v[182:185], v142 offset:52224
	ds_read_b128 v[186:189], v142 offset:53248
	ds_read_b128 v[194:197], v142 offset:54272
	ds_read_b128 v[198:201], v142 offset:55296
	ds_read_b128 v[218:221], v142 offset:56320
	s_barrier
	s_waitcnt lgkmcnt(0)
	v_mfma_f32_16x16x32_bf16 v[34:37], v[144:147], v[2:5], v[62:65]
	v_mfma_f32_16x16x32_bf16 v[54:57], v[158:161], v[10:13], v[34:37]
	v_mfma_f32_16x16x32_bf16 v[34:37], v[144:147], v[18:21], v[58:61]
	v_mfma_f32_16x16x32_bf16 v[62:65], v[158:161], v[22:25], v[34:37]
	v_mfma_f32_16x16x32_bf16 v[34:37], v[164:167], v[2:5], v[206:209]
	v_mfma_f32_16x16x32_bf16 v[50:53], v[182:185], v[10:13], v[34:37]
	v_mfma_f32_16x16x32_bf16 v[34:37], v[164:167], v[18:21], v[222:225]
	v_mfma_f32_16x16x32_bf16 v[58:61], v[182:185], v[22:25], v[34:37]
	v_mfma_f32_16x16x32_bf16 v[34:37], v[186:189], v[2:5], v[46:49]
	v_mfma_f32_16x16x32_bf16 v[42:45], v[194:197], v[10:13], v[34:37]
	v_mfma_f32_16x16x32_bf16 v[34:37], v[186:189], v[18:21], v[226:229]
	v_mfma_f32_16x16x32_bf16 v[2:5], v[198:201], v[2:5], v[38:41]
	v_mfma_f32_16x16x32_bf16 v[46:49], v[194:197], v[22:25], v[34:37]
	v_mfma_f32_16x16x32_bf16 v[34:37], v[218:221], v[10:13], v[2:5]
	v_mfma_f32_16x16x32_bf16 v[2:5], v[198:201], v[18:21], v[134:137]
	v_mfma_f32_16x16x32_bf16 v[38:41], v[218:221], v[22:25], v[2:5]
	v_mfma_f32_16x16x32_bf16 v[2:5], v[144:147], v[130:133], v[30:33]
	v_mfma_f32_16x16x32_bf16 v[22:25], v[158:161], v[202:205], v[2:5]
	v_mfma_f32_16x16x32_bf16 v[2:5], v[144:147], v[210:213], v[26:29]
	v_mfma_f32_16x16x32_bf16 v[30:33], v[158:161], v[214:217], v[2:5]
	v_mfma_f32_16x16x32_bf16 v[2:5], v[164:167], v[130:133], v[138:141]
	v_mfma_f32_16x16x32_bf16 v[18:21], v[182:185], v[202:205], v[2:5]
	v_mfma_f32_16x16x32_bf16 v[2:5], v[164:167], v[210:213], v[150:153]
	v_mfma_f32_16x16x32_bf16 v[26:29], v[182:185], v[214:217], v[2:5]
	v_mfma_f32_16x16x32_bf16 v[2:5], v[186:189], v[130:133], v[14:17]
	v_mfma_f32_16x16x32_bf16 v[10:13], v[194:197], v[202:205], v[2:5]
	v_mfma_f32_16x16x32_bf16 v[2:5], v[186:189], v[210:213], v[154:157]
	v_mfma_f32_16x16x32_bf16 v[14:17], v[194:197], v[214:217], v[2:5]
	v_mfma_f32_16x16x32_bf16 v[2:5], v[198:201], v[130:133], v[6:9]
	v_mfma_f32_16x16x32_bf16 v[6:9], v[198:201], v[210:213], v[190:193]
	v_mfma_f32_16x16x32_bf16 v[2:5], v[218:221], v[202:205], v[2:5]
	v_mfma_f32_16x16x32_bf16 v[6:9], v[218:221], v[214:217], v[6:9]
	v_cmp_gt_u32_e32 vcc, s67, v0
	s_barrier
	s_and_saveexec_b64 s[20:21], vcc
	s_cbranch_execz .LBB0_69
	s_barrier

; #define G_LDA(dst, b, h)                                                                                                  \
;   _Pragma("unroll") for (int m = 0; m < 4; ++m) _Pragma("unroll") for (int k = 0; k < 2; ++k)                             \
;       dst[m][k] = *(const bf16x8*)((const char*)G_SA(b, h) + ((wr * 4 + m) * 2 + k) * 1024 + rdo)
; #define G_LDB(dst, b, h)                                                                                                  \
;   _Pragma("unroll") for (int n = 0; n < 2; ++n) _Pragma("unroll") for (int k = 0; k < 2; ++k)                             \
;       dst[n][k] = *(const bf16x8*)((const char*)G_SB(b, h) + ((wc * 2 + n) * 2 + k) * 1024 + rdo)
; #define G_WAIT_L(n) asm volatile("s_waitcnt lgkmcnt(" #n ")" ::: "memory")
; #define G_BAR __builtin_amdgcn_s_barrier()
; #define G_SCHED __builtin_amdgcn_sched_barrier(0)
;     ...
;     G_LDB(B0, 0, 0); G_SCHED; G_LDA(At, 0, 0); G_STAGE(G_SA(1, 1), A, oa0, oa1, LDA, 128, KA(tt + 1));
;     G_WAIT_L(8); G_BAR; G_WAIT_L(0); G_MMA(0, 0, At, B0); G_BAR; G_SCHED;
;     G_LDB(B1, 0, 1); G_STAGE(G_SB(0, 0), B, ob0, ob1, LDB, 0, KB(tt + 2));
;     G_BAR; G_WAIT_L(0); G_MMA(0, 1, At, B1); G_BAR;
;     G_LDA(At, 0, 1); G_STAGE(G_SA(0, 0), A, oa0, oa1, LDA, 0, KA(tt + 2));
;     G_BAR; G_WAIT_L(0); G_MMA(1, 0, At, B0); G_BAR; G_SCHED;
.LBB0_96:
	ds_read_b128 v[182:185], v151
	ds_read_b128 v[186:189], v151 offset:1024
	ds_read_b128 v[190:193], v151 offset:2048
	ds_read_b128 v[194:197], v151 offset:3072
	v_lshl_add_u64 v[166:167], s[30:31], 0, v[140:141]
	v_lshl_add_u64 v[164:165], v[166:167], 0, s[78:79]
	s_add_u32 m0, s32, 0xc000
	ds_read_b128 v[198:201], v143
	ds_read_b128 v[202:205], v143 offset:1024
	ds_read_b128 v[206:209], v143 offset:2048
	ds_read_b128 v[210:213], v143 offset:3072
	ds_read_b128 v[214:217], v143 offset:4096
	ds_read_b128 v[218:221], v143 offset:5120
	ds_read_b128 v[222:225], v143 offset:6144
	ds_read_b128 v[226:229], v143 offset:7168
	global_load_lds_dwordx4 v[164:165], off
	v_lshl_add_u64 v[246:247], s[30:31], 0, v[138:139]
	v_lshl_add_u64 v[230:231], v[246:247], 0, s[78:79]
	s_add_u32 m0, s32, 0xe000
	s_add_i32 s34, s13, -1
	global_load_lds_dwordx4 v[230:231], off
	s_waitcnt lgkmcnt(8)
	s_barrier
	s_waitcnt lgkmcnt(0)
	v_mfma_f32_16x16x32_bf16 v[126:129], v[198:201], v[182:185], v[126:129]
	v_mfma_f32_16x16x32_bf16 v[122:125], v[198:201], v[190:193], v[122:125]
	v_mfma_f32_16x16x32_bf16 v[118:121], v[206:209], v[182:185], v[118:121]
	v_mfma_f32_16x16x32_bf16 v[114:117], v[206:209], v[190:193], v[114:117]
	v_mfma_f32_16x16x32_bf16 v[110:113], v[214:217], v[182:185], v[110:113]
	v_mfma_f32_16x16x32_bf16 v[106:109], v[214:217], v[190:193], v[106:109]
	v_mfma_f32_16x16x32_bf16 v[102:105], v[222:225], v[182:185], v[102:105]
	v_mfma_f32_16x16x32_bf16 v[98:101], v[222:225], v[190:193], v[98:101]
	v_mfma_f32_16x16x32_bf16 v[126:129], v[202:205], v[186:189], v[126:129]
	v_mfma_f32_16x16x32_bf16 v[122:125], v[202:205], v[194:197], v[122:125]
	v_mfma_f32_16x16x32_bf16 v[118:121], v[210:213], v[186:189], v[118:121]
	v_mfma_f32_16x16x32_bf16 v[114:117], v[210:213], v[194:197], v[114:117]
	v_mfma_f32_16x16x32_bf16 v[110:113], v[218:221], v[186:189], v[110:113]
	v_mfma_f32_16x16x32_bf16 v[106:109], v[218:221], v[194:197], v[106:109]
	v_mfma_f32_16x16x32_bf16 v[102:105], v[226:229], v[186:189], v[102:105]
	v_mfma_f32_16x16x32_bf16 v[98:101], v[226:229], v[194:197], v[98:101]
	s_barrier
	s_add_i32 s0, s25, 0xffff0000
	s_sub_i32 s1, s23, 64
	s_and_b32 s0, s0, 0x1c0000
	s_and_b32 s1, s1, 0x80
	s_or_b32 s0, s0, s1
	s_lshl_b32 s35, s0, 1
	s_add_u32 s0, s26, s35
	s_addc_u32 s1, s27, 0
	v_lshl_add_u64 v[248:249], s[0:1], 0, v[134:135]
	s_add_u32 m0, s32, 0x10000
	ds_read_b128 v[230:233], v146
	ds_read_b128 v[234:237], v146 offset:1024
	ds_read_b128 v[238:241], v146 offset:2048
	ds_read_b128 v[242:245], v146 offset:3072
	global_load_lds_dwordx4 v[248:249], off
	v_lshl_add_u64 v[248:249], s[0:1], 0, v[136:137]
	s_add_u32 m0, s32, 0x12000
	s_nop 0
	global_load_lds_dwordx4 v[248:249], off
	s_barrier
	s_waitcnt lgkmcnt(0)
	v_mfma_f32_16x16x32_bf16 v[94:97], v[198:201], v[230:233], v[94:97]
	v_mfma_f32_16x16x32_bf16 v[90:93], v[198:201], v[238:241], v[90:93]
	v_mfma_f32_16x16x32_bf16 v[86:89], v[206:209], v[230:233], v[86:89]
	v_mfma_f32_16x16x32_bf16 v[82:85], v[206:209], v[238:241], v[82:85]
	v_mfma_f32_16x16x32_bf16 v[78:81], v[214:217], v[230:233], v[78:81]
	v_mfma_f32_16x16x32_bf16 v[74:77], v[214:217], v[238:241], v[74:77]
	v_mfma_f32_16x16x32_bf16 v[70:73], v[222:225], v[230:233], v[70:73]
	v_mfma_f32_16x16x32_bf16 v[66:69], v[222:225], v[238:241], v[66:69]
	v_mfma_f32_16x16x32_bf16 v[94:97], v[202:205], v[234:237], v[94:97]
	v_mfma_f32_16x16x32_bf16 v[90:93], v[202:205], v[242:245], v[90:93]
	v_mfma_f32_16x16x32_bf16 v[86:89], v[210:213], v[234:237], v[86:89]
	v_mfma_f32_16x16x32_bf16 v[82:85], v[210:213], v[242:245], v[82:85]
	v_mfma_f32_16x16x32_bf16 v[78:81], v[218:221], v[234:237], v[78:81]
	v_mfma_f32_16x16x32_bf16 v[74:77], v[218:221], v[242:245], v[74:77]
	v_mfma_f32_16x16x32_bf16 v[70:73], v[226:229], v[234:237], v[70:73]
	v_mfma_f32_16x16x32_bf16 v[66:69], v[226:229], v[242:245], v[66:69]
	v_lshl_add_u64 v[248:249], v[166:167], 0, s[82:83]
	s_mov_b32 m0, s32
	s_barrier
	ds_read_b128 v[198:201], v143 offset:16384
	ds_read_b128 v[202:205], v143 offset:17408
	ds_read_b128 v[206:209], v143 offset:18432
	ds_read_b128 v[210:213], v143 offset:19456
	ds_read_b128 v[214:217], v143 offset:20480
	ds_read_b128 v[218:221], v143 offset:21504
	ds_read_b128 v[222:225], v143 offset:22528
	ds_read_b128 v[226:229], v143 offset:23552
	global_load_lds_dwordx4 v[248:249], off
	s_add_u32 m0, s32, 0x1f00
	s_nop 0
	global_load_lds_dwordx4 v[246:247], off offset:256
	s_barrier
	s_waitcnt lgkmcnt(0)
	v_mfma_f32_16x16x32_bf16 v[62:65], v[198:201], v[182:185], v[62:65]
	v_mfma_f32_16x16x32_bf16 v[58:61], v[198:201], v[190:193], v[58:61]
	v_mfma_f32_16x16x32_bf16 v[54:57], v[206:209], v[182:185], v[54:57]
	v_mfma_f32_16x16x32_bf16 v[50:53], v[206:209], v[190:193], v[50:53]
	v_mfma_f32_16x16x32_bf16 v[46:49], v[214:217], v[182:185], v[46:49]
	v_mfma_f32_16x16x32_bf16 v[42:45], v[214:217], v[190:193], v[42:45]
	v_mfma_f32_16x16x32_bf16 v[38:41], v[222:225], v[182:185], v[38:41]
	v_mfma_f32_16x16x32_bf16 v[34:37], v[222:225], v[190:193], v[34:37]
	v_mfma_f32_16x16x32_bf16 v[62:65], v[202:205], v[186:189], v[62:65]
	v_mfma_f32_16x16x32_bf16 v[58:61], v[202:205], v[194:197], v[58:61]
	v_mfma_f32_16x16x32_bf16 v[54:57], v[210:213], v[186:189], v[54:57]
	v_mfma_f32_16x16x32_bf16 v[50:53], v[210:213], v[194:197], v[50:53]
	v_mfma_f32_16x16x32_bf16 v[46:49], v[218:221], v[186:189], v[46:49]
	v_mfma_f32_16x16x32_bf16 v[42:45], v[218:221], v[194:197], v[42:45]
	v_mfma_f32_16x16x32_bf16 v[38:41], v[226:229], v[186:189], v[38:41]
	v_mfma_f32_16x16x32_bf16 v[34:37], v[226:229], v[194:197], v[34:37]
	s_barrier
; #define G_LDA(dst, b, h)                                                                                                  \
;   _Pragma("unroll") for (int m = 0; m < 4; ++m) _Pragma("unroll") for (int k = 0; k < 2; ++k)                             \
;       dst[m][k] = *(const bf16x8*)((const char*)G_SA(b, h) + ((wr * 4 + m) * 2 + k) * 1024 + rdo)
; #define G_LDB(dst, b, h)                                                                                                  \
;   _Pragma("unroll") for (int n = 0; n < 2; ++n) _Pragma("unroll") for (int k = 0; k < 2; ++k)                             \
;       dst[n][k] = *(const bf16x8*)((const char*)G_SB(b, h) + ((wc * 2 + n) * 2 + k) * 1024 + rdo)
; #define G_WAIT_V(n) asm volatile("s_waitcnt vmcnt(" #n ")" ::: "memory")
; #define G_WAIT_L(n) asm volatile("s_waitcnt lgkmcnt(" #n ")" ::: "memory")
; #define G_BAR __builtin_amdgcn_s_barrier()
; #define G_SCHED __builtin_amdgcn_sched_barrier(0)
;     ...
;     G_STAGE(G_SB(0, 1), B, ob0, ob1, LDB, 128, KB(tt + 2));
;     G_WAIT_V(6); G_BAR; G_MMA(1, 1, At, B1); G_BAR;
;     G_LDB(B0, 1, 0); G_SCHED; G_LDA(At, 1, 0); G_STAGE(G_SA(0, 1), A, oa0, oa1, LDA, 128, KA(tt + 2));
;     G_WAIT_L(8); G_BAR; G_WAIT_L(0); G_MMA(0, 0, At, B0); G_BAR; G_SCHED;
;     G_LDB(B1, 1, 1); G_STAGE(G_SB(1, 0), B, ob0, ob1, LDB, 0, KB(tt + 3));
;     G_BAR; G_WAIT_L(0); G_MMA(0, 1, At, B1); G_BAR;
;     G_LDA(At, 1, 1); G_STAGE(G_SA(1, 0), A, oa0, oa1, LDA, 0, KA(tt + 3));
	s_add_u32 s0, s28, s35
	s_addc_u32 s1, s29, 0
	s_add_u32 m0, s32, 0x14000
	v_lshl_add_u64 v[182:183], s[0:1], 0, v[134:135]
	global_load_lds_dwordx4 v[182:183], off
	v_lshl_add_u64 v[182:183], s[0:1], 0, v[136:137]
	s_add_u32 m0, s32, 0x16000
	s_nop 0
	global_load_lds_dwordx4 v[182:183], off
	s_waitcnt vmcnt(6)
	s_barrier
	v_mfma_f32_16x16x32_bf16 v[30:33], v[198:201], v[230:233], v[30:33]
	v_mfma_f32_16x16x32_bf16 v[26:29], v[198:201], v[238:241], v[26:29]
	v_mfma_f32_16x16x32_bf16 v[22:25], v[206:209], v[230:233], v[22:25]
	v_mfma_f32_16x16x32_bf16 v[18:21], v[206:209], v[238:241], v[18:21]
	v_mfma_f32_16x16x32_bf16 v[14:17], v[214:217], v[230:233], v[14:17]
	v_mfma_f32_16x16x32_bf16 v[10:13], v[214:217], v[238:241], v[10:13]
	v_mfma_f32_16x16x32_bf16 v[6:9], v[222:225], v[230:233], v[6:9]
	v_mfma_f32_16x16x32_bf16 v[2:5], v[222:225], v[238:241], v[2:5]
	v_mfma_f32_16x16x32_bf16 v[30:33], v[202:205], v[234:237], v[30:33]
	v_mfma_f32_16x16x32_bf16 v[26:29], v[202:205], v[242:245], v[26:29]
	v_mfma_f32_16x16x32_bf16 v[22:25], v[210:213], v[234:237], v[22:25]
	v_mfma_f32_16x16x32_bf16 v[18:21], v[210:213], v[242:245], v[18:21]
	v_mfma_f32_16x16x32_bf16 v[14:17], v[218:221], v[234:237], v[14:17]
	v_mfma_f32_16x16x32_bf16 v[10:13], v[218:221], v[242:245], v[10:13]
	v_mfma_f32_16x16x32_bf16 v[6:9], v[226:229], v[234:237], v[6:9]
	v_mfma_f32_16x16x32_bf16 v[2:5], v[226:229], v[242:245], v[2:5]
	s_barrier
	ds_read_b128 v[182:185], v145
	ds_read_b128 v[186:189], v145 offset:1024
	ds_read_b128 v[190:193], v145 offset:2048
	ds_read_b128 v[194:197], v145 offset:3072
	v_lshl_add_u64 v[230:231], v[166:167], 0, s[86:87]
	s_add_u32 m0, s32, 0x4000
	ds_read_b128 v[198:201], v143 offset:32768
	ds_read_b128 v[202:205], v143 offset:33792
	ds_read_b128 v[206:209], v143 offset:34816
	ds_read_b128 v[210:213], v143 offset:35840
	ds_read_b128 v[214:217], v143 offset:36864
	ds_read_b128 v[218:221], v143 offset:37888
	ds_read_b128 v[222:225], v143 offset:38912
	ds_read_b128 v[226:229], v143 offset:39936
	global_load_lds_dwordx4 v[230:231], off
	s_add_u32 m0, s32, 0x6000
	v_lshl_add_u64 v[230:231], v[246:247], 0, s[86:87]
	global_load_lds_dwordx4 v[230:231], off
	s_waitcnt lgkmcnt(8)
	s_barrier
	s_waitcnt lgkmcnt(0)
	v_mfma_f32_16x16x32_bf16 v[126:129], v[198:201], v[182:185], v[126:129]
	v_mfma_f32_16x16x32_bf16 v[122:125], v[198:201], v[190:193], v[122:125]
	v_mfma_f32_16x16x32_bf16 v[118:121], v[206:209], v[182:185], v[118:121]
	v_mfma_f32_16x16x32_bf16 v[114:117], v[206:209], v[190:193], v[114:117]
	v_mfma_f32_16x16x32_bf16 v[110:113], v[214:217], v[182:185], v[110:113]
	v_mfma_f32_16x16x32_bf16 v[106:109], v[214:217], v[190:193], v[106:109]
	v_mfma_f32_16x16x32_bf16 v[102:105], v[222:225], v[182:185], v[102:105]
	v_mfma_f32_16x16x32_bf16 v[98:101], v[222:225], v[190:193], v[98:101]
	v_mfma_f32_16x16x32_bf16 v[126:129], v[202:205], v[186:189], v[126:129]
	v_mfma_f32_16x16x32_bf16 v[122:125], v[202:205], v[194:197], v[122:125]
	v_mfma_f32_16x16x32_bf16 v[118:121], v[210:213], v[186:189], v[118:121]
	v_mfma_f32_16x16x32_bf16 v[114:117], v[210:213], v[194:197], v[114:117]
	v_mfma_f32_16x16x32_bf16 v[110:113], v[218:221], v[186:189], v[110:113]
	v_mfma_f32_16x16x32_bf16 v[106:109], v[218:221], v[194:197], v[106:109]
	v_mfma_f32_16x16x32_bf16 v[102:105], v[226:229], v[186:189], v[102:105]
	v_mfma_f32_16x16x32_bf16 v[98:101], v[226:229], v[194:197], v[98:101]
	s_barrier
	s_and_b32 s0, s25, 0x1c0000
	s_and_b32 s1, s23, 0xc0
	s_or_b32 s0, s0, s1
	s_lshl_b32 s35, s0, 1
	s_add_u32 s0, s26, s35
	s_addc_u32 s1, s27, 0
	v_lshl_add_u64 v[248:249], s[0:1], 0, v[134:135]
	s_add_u32 m0, s32, 0x18000
	ds_read_b128 v[230:233], v144
	ds_read_b128 v[234:237], v144 offset:1024
	ds_read_b128 v[238:241], v144 offset:2048
	ds_read_b128 v[242:245], v144 offset:3072
	global_load_lds_dwordx4 v[248:249], off
	v_lshl_add_u64 v[248:249], s[0:1], 0, v[136:137]
	s_add_u32 m0, s32, 0x1a000
	s_nop 0
	global_load_lds_dwordx4 v[248:249], off
	s_barrier
	s_waitcnt lgkmcnt(0)
	v_mfma_f32_16x16x32_bf16 v[94:97], v[198:201], v[230:233], v[94:97]
	v_mfma_f32_16x16x32_bf16 v[90:93], v[198:201], v[238:241], v[90:93]
	v_mfma_f32_16x16x32_bf16 v[86:89], v[206:209], v[230:233], v[86:89]
	v_mfma_f32_16x16x32_bf16 v[82:85], v[206:209], v[238:241], v[82:85]
	v_mfma_f32_16x16x32_bf16 v[78:81], v[214:217], v[230:233], v[78:81]
	v_mfma_f32_16x16x32_bf16 v[74:77], v[214:217], v[238:241], v[74:77]
	v_mfma_f32_16x16x32_bf16 v[70:73], v[222:225], v[230:233], v[70:73]
	v_mfma_f32_16x16x32_bf16 v[66:69], v[222:225], v[238:241], v[66:69]
	v_mfma_f32_16x16x32_bf16 v[94:97], v[202:205], v[234:237], v[94:97]
	v_mfma_f32_16x16x32_bf16 v[90:93], v[202:205], v[242:245], v[90:93]
	v_mfma_f32_16x16x32_bf16 v[86:89], v[210:213], v[234:237], v[86:89]
	v_mfma_f32_16x16x32_bf16 v[82:85], v[210:213], v[242:245], v[82:85]
	v_mfma_f32_16x16x32_bf16 v[78:81], v[218:221], v[234:237], v[78:81]
	v_mfma_f32_16x16x32_bf16 v[74:77], v[218:221], v[242:245], v[74:77]
	v_mfma_f32_16x16x32_bf16 v[70:73], v[226:229], v[234:237], v[70:73]
	v_mfma_f32_16x16x32_bf16 v[66:69], v[226:229], v[242:245], v[66:69]
	s_add_u32 m0, s32, 0x7e80
	s_barrier
	ds_read_b128 v[198:201], v143 offset:49152
	ds_read_b128 v[202:205], v143 offset:50176
	ds_read_b128 v[206:209], v143 offset:51200
	ds_read_b128 v[210:213], v143 offset:52224
	ds_read_b128 v[214:217], v143 offset:53248
	ds_read_b128 v[218:221], v143 offset:54272
	ds_read_b128 v[222:225], v143 offset:55296
	ds_read_b128 v[226:229], v143 offset:56320
	global_load_lds_dwordx4 v[166:167], off offset:384
	s_add_u32 m0, s32, 0x9e80
	s_nop 0
	global_load_lds_dwordx4 v[246:247], off offset:384
	s_barrier
; #define G_WAIT_V(n) asm volatile("s_waitcnt vmcnt(" #n ")" ::: "memory")
; #define G_WAIT_L(n) asm volatile("s_waitcnt lgkmcnt(" #n ")" ::: "memory")
; #define G_BAR __builtin_amdgcn_s_barrier()
; #define G_SCHED __builtin_amdgcn_sched_barrier(0)
; DI void br_flush(PREF p, f32x4 (&acc)[2][2][4][2], int slot) { br_store(p, acc, slot); zero_acc256(acc); }
;     ...
;     G_BAR; G_WAIT_L(0); G_MMA(1, 0, At, B0); G_BAR; G_SCHED;
;     G_STAGE(G_SB(1, 1), B, ob0, ob1, LDB, 128, KB(tt + 3));
;     G_WAIT_V(6); G_BAR; G_MMA(1, 1, At, B1); G_BAR;
;     if (MODE && ((tt + 1) & 3) == 3) br_flush(p, acc, (tt + 1) >> 2);
	s_waitcnt lgkmcnt(0)
	v_mfma_f32_16x16x32_bf16 v[62:65], v[198:201], v[182:185], v[62:65]
	v_mfma_f32_16x16x32_bf16 v[58:61], v[198:201], v[190:193], v[58:61]
	v_mfma_f32_16x16x32_bf16 v[54:57], v[206:209], v[182:185], v[54:57]
	v_mfma_f32_16x16x32_bf16 v[50:53], v[206:209], v[190:193], v[50:53]
	v_mfma_f32_16x16x32_bf16 v[46:49], v[214:217], v[182:185], v[46:49]
	v_mfma_f32_16x16x32_bf16 v[42:45], v[214:217], v[190:193], v[42:45]
	v_mfma_f32_16x16x32_bf16 v[38:41], v[222:225], v[182:185], v[38:41]
	v_mfma_f32_16x16x32_bf16 v[34:37], v[222:225], v[190:193], v[34:37]
	v_mfma_f32_16x16x32_bf16 v[62:65], v[202:205], v[186:189], v[62:65]
	v_mfma_f32_16x16x32_bf16 v[58:61], v[202:205], v[194:197], v[58:61]
	v_mfma_f32_16x16x32_bf16 v[54:57], v[210:213], v[186:189], v[54:57]
	v_mfma_f32_16x16x32_bf16 v[50:53], v[210:213], v[194:197], v[50:53]
	v_mfma_f32_16x16x32_bf16 v[46:49], v[218:221], v[186:189], v[46:49]
	v_mfma_f32_16x16x32_bf16 v[42:45], v[218:221], v[194:197], v[42:45]
	v_mfma_f32_16x16x32_bf16 v[38:41], v[226:229], v[186:189], v[38:41]
	v_mfma_f32_16x16x32_bf16 v[34:37], v[226:229], v[194:197], v[34:37]
	s_barrier
	s_add_u32 s0, s28, s35
	s_addc_u32 s1, s29, 0
	s_add_u32 m0, s32, 0x1c000
	v_lshl_add_u64 v[166:167], s[0:1], 0, v[134:135]
	global_load_lds_dwordx4 v[166:167], off
	v_lshl_add_u64 v[166:167], s[0:1], 0, v[136:137]
	s_add_u32 m0, s32, 0x1e000
	s_nop 0
	global_load_lds_dwordx4 v[166:167], off
	s_waitcnt vmcnt(6)
	s_barrier
	v_mfma_f32_16x16x32_bf16 v[30:33], v[198:201], v[230:233], v[30:33]
	v_mfma_f32_16x16x32_bf16 v[26:29], v[198:201], v[238:241], v[26:29]
	v_mfma_f32_16x16x32_bf16 v[22:25], v[206:209], v[230:233], v[22:25]
	v_mfma_f32_16x16x32_bf16 v[18:21], v[206:209], v[238:241], v[18:21]
	v_mfma_f32_16x16x32_bf16 v[14:17], v[214:217], v[230:233], v[14:17]
	v_mfma_f32_16x16x32_bf16 v[10:13], v[214:217], v[238:241], v[10:13]
	v_mfma_f32_16x16x32_bf16 v[6:9], v[222:225], v[230:233], v[6:9]
	v_mfma_f32_16x16x32_bf16 v[2:5], v[222:225], v[238:241], v[2:5]
	v_mfma_f32_16x16x32_bf16 v[30:33], v[202:205], v[234:237], v[30:33]
	v_mfma_f32_16x16x32_bf16 v[26:29], v[202:205], v[242:245], v[26:29]
	v_mfma_f32_16x16x32_bf16 v[22:25], v[210:213], v[234:237], v[22:25]
	v_mfma_f32_16x16x32_bf16 v[18:21], v[210:213], v[242:245], v[18:21]
	v_mfma_f32_16x16x32_bf16 v[14:17], v[218:221], v[234:237], v[14:17]
	v_mfma_f32_16x16x32_bf16 v[10:13], v[218:221], v[242:245], v[10:13]
	v_mfma_f32_16x16x32_bf16 v[6:9], v[226:229], v[234:237], v[6:9]
	v_mfma_f32_16x16x32_bf16 v[2:5], v[226:229], v[242:245], v[2:5]
	s_and_b32 s0, s34, 3
	s_cmp_eq_u32 s0, 3
	s_barrier
	s_cbranch_scc0 .LBB0_95
; DI unsigned pack2(float a, float b) { unsigned r; asm("v_cvt_pk_bf16_f32 %0, %1, %2\n\ts_nop 1" : "=v"(r) : "v"(a), "v"(b)); return r; }
; DI u32x4* merge_scratch(PREF p, int region) { const int t = tid512(); return (u32x4*)p.fbuf + (size_t)blockIdx.x * 40960 + region * 8192 + (t >> 6) * 1024 + (t & 63); }
; DI void br_store(PREF p, const f32x4 (&acc)[2][2][4][2], int slot) {
;   u32x4* sb = merge_scratch(p, slot);
; #pragma unroll
;   for (int ai = 0; ai < 2; ++ai)
; #pragma unroll
;     for (int bj = 0; bj < 2; ++bj)
; #pragma unroll
;       for (int m = 0; m < 4; ++m) {
;         u32x4 o;
;         o.x = pack2(acc[ai][bj][m][0][0], acc[ai][bj][m][0][1]); o.y = pack2(acc[ai][bj][m][0][2], acc[ai][bj][m][0][3]);
;         o.z = pack2(acc[ai][bj][m][1][0], acc[ai][bj][m][1][1]); o.w = pack2(acc[ai][bj][m][1][2], acc[ai][bj][m][1][3]);
;         sb[((ai * 2 + bj) * 4 + m) * 64] = o;
;       }
; }
; DI void br_flush(PREF p, f32x4 (&acc)[2][2][4][2], int slot) { br_store(p, acc, slot); zero_acc256(acc); }
	v_mov_b32_e32 v0, v168
	s_and_b32 s0, s12, 0x6000
	s_lshl_b32 s0, s0, 4
	v_lshlrev_b32_e32 v165, 4, v0
	s_add_u32 s0, s63, s0
	v_and_b32_e32 v166, 0xfffffc00, v165
	s_addc_u32 s1, s64, 0
	v_ashrrev_i32_e32 v167, 31, v166
	v_and_b32_e32 v0, 63, v0
	v_lshl_add_u64 v[166:167], v[166:167], 4, s[0:1]
	v_lshlrev_b32_e32 v0, 4, v0
	v_lshl_add_u64 v[166:167], v[166:167], 0, v[0:1]
	v_cvt_pk_bf16_f32 v94, v94, v95
	v_cvt_pk_bf16_f32 v95, v96, v97
	v_cvt_pk_bf16_f32 v96, v90, v91
	v_add_co_u32_e32 v90, vcc, s80, v166
	v_cvt_pk_bf16_f32 v97, v92, v93
	s_movk_i32 s0, 0x3000
	s_nop 0
	v_addc_co_u32_e32 v91, vcc, 0, v167, vcc
	v_add_co_u32_e32 v92, vcc, s40, v166
	v_cvt_pk_bf16_f32 v30, v30, v31
	v_cvt_pk_bf16_f32 v31, v32, v33
	v_cvt_pk_bf16_f32 v32, v26, v27
	v_cvt_pk_bf16_f32 v126, v126, v127
	s_nop 1
	v_addc_co_u32_e32 v93, vcc, 0, v167, vcc
	v_add_co_u32_e32 v26, vcc, s0, v166
	v_cvt_pk_bf16_f32 v127, v128, v129
	v_cvt_pk_bf16_f32 v128, v122, v123
	v_cvt_pk_bf16_f32 v129, v124, v125
	v_cvt_pk_bf16_f32 v118, v118, v119
	v_cvt_pk_bf16_f32 v119, v120, v121
	v_cvt_pk_bf16_f32 v120, v114, v115
	v_cvt_pk_bf16_f32 v121, v116, v117
	v_cvt_pk_bf16_f32 v110, v110, v111
	v_cvt_pk_bf16_f32 v111, v112, v113
	v_cvt_pk_bf16_f32 v112, v106, v107
	v_cvt_pk_bf16_f32 v113, v108, v109
	v_cvt_pk_bf16_f32 v102, v102, v103
	v_cvt_pk_bf16_f32 v103, v104, v105
	v_cvt_pk_bf16_f32 v104, v98, v99
	v_cvt_pk_bf16_f32 v105, v100, v101
	v_cvt_pk_bf16_f32 v86, v86, v87
	v_cvt_pk_bf16_f32 v87, v88, v89
	v_cvt_pk_bf16_f32 v88, v82, v83
	v_cvt_pk_bf16_f32 v89, v84, v85
	v_cvt_pk_bf16_f32 v78, v78, v79
	v_cvt_pk_bf16_f32 v79, v80, v81
	v_cvt_pk_bf16_f32 v80, v74, v75
	v_cvt_pk_bf16_f32 v81, v76, v77
	v_cvt_pk_bf16_f32 v70, v70, v71
	v_cvt_pk_bf16_f32 v71, v72, v73
	v_cvt_pk_bf16_f32 v72, v66, v67
	v_cvt_pk_bf16_f32 v73, v68, v69
	v_cvt_pk_bf16_f32 v62, v62, v63
	v_cvt_pk_bf16_f32 v63, v64, v65
	v_cvt_pk_bf16_f32 v64, v58, v59
	v_cvt_pk_bf16_f32 v65, v60, v61
	v_cvt_pk_bf16_f32 v54, v54, v55
	v_cvt_pk_bf16_f32 v55, v56, v57
	v_cvt_pk_bf16_f32 v56, v50, v51
	v_cvt_pk_bf16_f32 v57, v52, v53
	v_cvt_pk_bf16_f32 v46, v46, v47
	v_cvt_pk_bf16_f32 v47, v48, v49
	v_cvt_pk_bf16_f32 v48, v42, v43
	v_cvt_pk_bf16_f32 v49, v44, v45
	v_cvt_pk_bf16_f32 v38, v38, v39
	v_cvt_pk_bf16_f32 v39, v40, v41
	v_cvt_pk_bf16_f32 v40, v34, v35
	v_cvt_pk_bf16_f32 v41, v36, v37
	v_cvt_pk_bf16_f32 v33, v28, v29
	s_nop 1
	v_addc_co_u32_e32 v27, vcc, 0, v167, vcc
	v_cvt_pk_bf16_f32 v22, v22, v23
	v_cvt_pk_bf16_f32 v23, v24, v25
	v_cvt_pk_bf16_f32 v24, v18, v19
	v_cvt_pk_bf16_f32 v25, v20, v21
	v_cvt_pk_bf16_f32 v14, v14, v15
	v_cvt_pk_bf16_f32 v15, v16, v17
	v_cvt_pk_bf16_f32 v16, v10, v11
	v_cvt_pk_bf16_f32 v17, v12, v13
	v_cvt_pk_bf16_f32 v6, v6, v7
	v_cvt_pk_bf16_f32 v7, v8, v9
	v_cvt_pk_bf16_f32 v8, v2, v3
	v_cvt_pk_bf16_f32 v9, v4, v5
	v_mov_b32_e32 v2, 0
	global_store_dwordx4 v[166:167], v[126:129], off
	global_store_dwordx4 v[166:167], v[118:121], off offset:1024
	global_store_dwordx4 v[166:167], v[110:113], off offset:2048
	global_store_dwordx4 v[166:167], v[102:105], off offset:3072
	global_store_dwordx4 v[92:93], v[94:97], off offset:-4096
	global_store_dwordx4 v[90:91], v[86:89], off offset:1024
	global_store_dwordx4 v[90:91], v[78:81], off offset:2048
	global_store_dwordx4 v[90:91], v[70:73], off offset:3072
	global_store_dwordx4 v[92:93], v[62:65], off
	global_store_dwordx4 v[92:93], v[54:57], off offset:1024
	global_store_dwordx4 v[92:93], v[46:49], off offset:2048
	global_store_dwordx4 v[92:93], v[38:41], off offset:3072
	global_store_dwordx4 v[26:27], v[30:33], off
	global_store_dwordx4 v[26:27], v[22:25], off offset:1024
	global_store_dwordx4 v[26:27], v[14:17], off offset:2048
	global_store_dwordx4 v[26:27], v[6:9], off offset:3072
	v_mov_b32_e32 v3, v2
	v_mov_b32_e32 v4, v2
	v_mov_b32_e32 v5, v2
	v_mov_b32_e32 v6, v2
	v_mov_b32_e32 v7, v2
	v_mov_b32_e32 v8, v2
	v_mov_b32_e32 v9, v2
	v_mov_b32_e32 v10, v2
	v_mov_b32_e32 v11, v2
	v_mov_b32_e32 v12, v2
	v_mov_b32_e32 v13, v2
	v_mov_b32_e32 v14, v2
	v_mov_b32_e32 v15, v2
	v_mov_b32_e32 v16, v2
	v_mov_b32_e32 v17, v2
	v_mov_b32_e32 v18, v2
	v_mov_b32_e32 v19, v2
	v_mov_b32_e32 v20, v2
	v_mov_b32_e32 v21, v2
	v_mov_b32_e32 v22, v2
	v_mov_b32_e32 v23, v2
	v_mov_b32_e32 v24, v2
	v_mov_b32_e32 v25, v2
	v_mov_b32_e32 v26, v2
	v_mov_b32_e32 v27, v2
	v_mov_b32_e32 v28, v2
	v_mov_b32_e32 v29, v2
	v_mov_b32_e32 v30, v2
	v_mov_b32_e32 v31, v2
	v_mov_b32_e32 v32, v2
	v_mov_b32_e32 v33, v2
	v_mov_b32_e32 v34, v2
	v_mov_b32_e32 v35, v2
	v_mov_b32_e32 v36, v2
	v_mov_b32_e32 v37, v2
	v_mov_b32_e32 v38, v2
	v_mov_b32_e32 v39, v2
	v_mov_b32_e32 v40, v2
	v_mov_b32_e32 v41, v2
	v_mov_b32_e32 v42, v2
	v_mov_b32_e32 v43, v2
	v_mov_b32_e32 v44, v2
	v_mov_b32_e32 v45, v2
	v_mov_b32_e32 v46, v2
	v_mov_b32_e32 v47, v2
	v_mov_b32_e32 v48, v2
	v_mov_b32_e32 v49, v2
	v_mov_b32_e32 v50, v2
	v_mov_b32_e32 v51, v2
	v_mov_b32_e32 v52, v2
	v_mov_b32_e32 v53, v2
	v_mov_b32_e32 v54, v2
	v_mov_b32_e32 v55, v2
	v_mov_b32_e32 v56, v2
	v_mov_b32_e32 v57, v2
	v_mov_b32_e32 v58, v2
	v_mov_b32_e32 v59, v2
	v_mov_b32_e32 v60, v2
	v_mov_b32_e32 v61, v2
	v_mov_b32_e32 v62, v2
	v_mov_b32_e32 v63, v2
	v_mov_b32_e32 v64, v2
	v_mov_b32_e32 v65, v2
	v_mov_b32_e32 v66, v2
	v_mov_b32_e32 v67, v2
	v_mov_b32_e32 v68, v2
	v_mov_b32_e32 v69, v2
	v_mov_b32_e32 v70, v2
	v_mov_b32_e32 v71, v2
	v_mov_b32_e32 v72, v2
	v_mov_b32_e32 v73, v2
	v_mov_b32_e32 v74, v2
	v_mov_b32_e32 v75, v2
	v_mov_b32_e32 v76, v2
	v_mov_b32_e32 v77, v2
	v_mov_b32_e32 v78, v2
	v_mov_b32_e32 v79, v2
	v_mov_b32_e32 v80, v2
	v_mov_b32_e32 v81, v2
	v_mov_b32_e32 v82, v2
	v_mov_b32_e32 v83, v2
	v_mov_b32_e32 v84, v2
	v_mov_b32_e32 v85, v2
	v_mov_b32_e32 v86, v2
	v_mov_b32_e32 v87, v2
	v_mov_b32_e32 v88, v2
	v_mov_b32_e32 v89, v2
	v_mov_b32_e32 v90, v2
	v_mov_b32_e32 v91, v2
	v_mov_b32_e32 v92, v2
	v_mov_b32_e32 v93, v2
	v_mov_b32_e32 v94, v2
	v_mov_b32_e32 v95, v2
	v_mov_b32_e32 v96, v2
	v_mov_b32_e32 v97, v2
	v_mov_b32_e32 v98, v2
	v_mov_b32_e32 v99, v2
	v_mov_b32_e32 v100, v2
	v_mov_b32_e32 v101, v2
	v_mov_b32_e32 v102, v2
	v_mov_b32_e32 v103, v2
	v_mov_b32_e32 v104, v2
	v_mov_b32_e32 v105, v2
	v_mov_b32_e32 v106, v2
	v_mov_b32_e32 v107, v2
	v_mov_b32_e32 v108, v2
	v_mov_b32_e32 v109, v2
	v_mov_b32_e32 v110, v2
	v_mov_b32_e32 v111, v2
	v_mov_b32_e32 v112, v2
	v_mov_b32_e32 v113, v2
	v_mov_b32_e32 v114, v2
	v_mov_b32_e32 v115, v2
	v_mov_b32_e32 v116, v2
	v_mov_b32_e32 v117, v2
	v_mov_b32_e32 v118, v2
	v_mov_b32_e32 v119, v2
	v_mov_b32_e32 v120, v2
	v_mov_b32_e32 v121, v2
	v_mov_b32_e32 v122, v2
	v_mov_b32_e32 v123, v2
	v_mov_b32_e32 v124, v2
	v_mov_b32_e32 v125, v2
	v_mov_b32_e32 v126, v2
	v_mov_b32_e32 v127, v2
	v_mov_b32_e32 v128, v2
	v_mov_b32_e32 v129, v2
	s_branch .LBB0_95

; #define G_LDA(dst, b, h)                                                                                                  \
;   _Pragma("unroll") for (int m = 0; m < 4; ++m) _Pragma("unroll") for (int k = 0; k < 2; ++k)                             \
;       dst[m][k] = *(const bf16x8*)((const char*)G_SA(b, h) + ((wr * 4 + m) * 2 + k) * 1024 + rdo)
; #define G_LDB(dst, b, h)                                                                                                  \
;   _Pragma("unroll") for (int n = 0; n < 2; ++n) _Pragma("unroll") for (int k = 0; k < 2; ++k)                             \
;       dst[n][k] = *(const bf16x8*)((const char*)G_SB(b, h) + ((wc * 2 + n) * 2 + k) * 1024 + rdo)
; #define G_WAIT_V(n) asm volatile("s_waitcnt vmcnt(" #n ")" ::: "memory")
; #define G_WAIT_L(n) asm volatile("s_waitcnt lgkmcnt(" #n ")" ::: "memory")
; #define G_BAR __builtin_amdgcn_s_barrier()
; #define G_SCHED __builtin_amdgcn_sched_barrier(0)
;     ...
;     G_LDB(B0, 0, 0); G_SCHED; G_LDA(At, 0, 0); G_STAGE(G_SA(1, 1), A, oa0, oa1, LDA, 128, KA(tt + 1));
;     G_WAIT_L(8); G_BAR; G_WAIT_L(0); G_MMA(0, 0, At, B0); G_BAR; G_SCHED;
;     G_LDB(B1, 0, 1); G_STAGE(G_SB(0, 0), B, ob0, ob1, LDB, 0, KB(tt + 2));
;     G_BAR; G_WAIT_L(0); G_MMA(0, 1, At, B1); G_BAR;
;     G_LDA(At, 0, 1); G_STAGE(G_SA(0, 0), A, oa0, oa1, LDA, 0, KA(tt + 2));
;     G_BAR; G_WAIT_L(0); G_MMA(1, 0, At, B0); G_BAR; G_SCHED;
;     G_STAGE(G_SB(0, 1), B, ob0, ob1, LDB, 128, KB(tt + 2));
;     G_WAIT_V(6); G_BAR; G_MMA(1, 1, At, B1); G_BAR;
.LBB0_105:
	ds_read_b128 v[164:167], v160
	ds_read_b128 v[182:185], v160 offset:1024
	ds_read_b128 v[186:189], v160 offset:2048
	ds_read_b128 v[190:193], v160 offset:3072
	v_lshl_add_u64 v[242:243], v[136:137], 0, s[8:9]
	v_lshl_add_u64 v[226:227], v[242:243], 0, s[78:79]
	s_add_u32 m0, s32, 0xc000
	v_lshl_add_u64 v[244:245], v[134:135], 0, s[8:9]
	ds_read_b128 v[194:197], v142
	ds_read_b128 v[198:201], v142 offset:1024
	ds_read_b128 v[202:205], v142 offset:2048
	ds_read_b128 v[206:209], v142 offset:3072
	ds_read_b128 v[210:213], v142 offset:4096
	ds_read_b128 v[214:217], v142 offset:5120
	ds_read_b128 v[218:221], v142 offset:6144
	ds_read_b128 v[222:225], v142 offset:7168
	global_load_lds_dwordx4 v[226:227], off
	s_add_u32 m0, s32, 0xe000
	v_lshl_add_u64 v[226:227], v[244:245], 0, s[78:79]
	global_load_lds_dwordx4 v[226:227], off
	s_waitcnt lgkmcnt(8)
	s_barrier
	s_waitcnt lgkmcnt(0)
	v_mfma_f32_16x16x32_bf16 v[126:129], v[194:197], v[164:167], v[126:129]
	v_mfma_f32_16x16x32_bf16 v[122:125], v[194:197], v[186:189], v[122:125]
	v_mfma_f32_16x16x32_bf16 v[118:121], v[202:205], v[164:167], v[118:121]
	v_mfma_f32_16x16x32_bf16 v[114:117], v[202:205], v[186:189], v[114:117]
	v_mfma_f32_16x16x32_bf16 v[110:113], v[210:213], v[164:167], v[110:113]
	v_mfma_f32_16x16x32_bf16 v[106:109], v[210:213], v[186:189], v[106:109]
	v_mfma_f32_16x16x32_bf16 v[102:105], v[218:221], v[164:167], v[102:105]
	v_mfma_f32_16x16x32_bf16 v[98:101], v[218:221], v[186:189], v[98:101]
	v_mfma_f32_16x16x32_bf16 v[126:129], v[198:201], v[182:185], v[126:129]
	v_mfma_f32_16x16x32_bf16 v[122:125], v[198:201], v[190:193], v[122:125]
	v_mfma_f32_16x16x32_bf16 v[118:121], v[206:209], v[182:185], v[118:121]
	v_mfma_f32_16x16x32_bf16 v[114:117], v[206:209], v[190:193], v[114:117]
	v_mfma_f32_16x16x32_bf16 v[110:113], v[214:217], v[182:185], v[110:113]
	v_mfma_f32_16x16x32_bf16 v[106:109], v[214:217], v[190:193], v[106:109]
	v_mfma_f32_16x16x32_bf16 v[102:105], v[222:225], v[182:185], v[102:105]
	v_mfma_f32_16x16x32_bf16 v[98:101], v[222:225], v[190:193], v[98:101]
	s_barrier
	v_lshl_add_u64 v[246:247], v[140:141], 0, s[8:9]
	v_lshl_add_u64 v[248:249], v[246:247], 0, s[50:51]
	s_add_u32 m0, s32, 0x10000
	ds_read_b128 v[226:229], v158
	ds_read_b128 v[230:233], v158 offset:1024
	ds_read_b128 v[234:237], v158 offset:2048
	ds_read_b128 v[238:241], v158 offset:3072
	global_load_lds_dwordx4 v[248:249], off
	v_lshl_add_u64 v[248:249], v[138:139], 0, s[8:9]
	s_add_u32 m0, s32, 0x12000
	v_lshl_add_u64 v[250:251], v[248:249], 0, s[50:51]
	global_load_lds_dwordx4 v[250:251], off
	s_barrier
	s_waitcnt lgkmcnt(0)
	v_mfma_f32_16x16x32_bf16 v[94:97], v[194:197], v[226:229], v[94:97]
	v_mfma_f32_16x16x32_bf16 v[90:93], v[194:197], v[234:237], v[90:93]
	v_mfma_f32_16x16x32_bf16 v[86:89], v[202:205], v[226:229], v[86:89]
	v_mfma_f32_16x16x32_bf16 v[82:85], v[202:205], v[234:237], v[82:85]
	v_mfma_f32_16x16x32_bf16 v[78:81], v[210:213], v[226:229], v[78:81]
	v_mfma_f32_16x16x32_bf16 v[74:77], v[210:213], v[234:237], v[74:77]
	v_mfma_f32_16x16x32_bf16 v[70:73], v[218:221], v[226:229], v[70:73]
	v_mfma_f32_16x16x32_bf16 v[66:69], v[218:221], v[234:237], v[66:69]
	v_mfma_f32_16x16x32_bf16 v[94:97], v[198:201], v[230:233], v[94:97]
	v_mfma_f32_16x16x32_bf16 v[90:93], v[198:201], v[238:241], v[90:93]
	v_mfma_f32_16x16x32_bf16 v[86:89], v[206:209], v[230:233], v[86:89]
	v_mfma_f32_16x16x32_bf16 v[82:85], v[206:209], v[238:241], v[82:85]
	v_mfma_f32_16x16x32_bf16 v[78:81], v[214:217], v[230:233], v[78:81]
	v_mfma_f32_16x16x32_bf16 v[74:77], v[214:217], v[238:241], v[74:77]
	v_mfma_f32_16x16x32_bf16 v[70:73], v[222:225], v[230:233], v[70:73]
	v_mfma_f32_16x16x32_bf16 v[66:69], v[222:225], v[238:241], v[66:69]
	v_lshl_add_u64 v[250:251], v[242:243], 0, s[82:83]
	s_mov_b32 m0, s32
	s_barrier
	ds_read_b128 v[194:197], v142 offset:16384
	ds_read_b128 v[198:201], v142 offset:17408
	ds_read_b128 v[202:205], v142 offset:18432
	ds_read_b128 v[206:209], v142 offset:19456
	ds_read_b128 v[210:213], v142 offset:20480
	ds_read_b128 v[214:217], v142 offset:21504
	ds_read_b128 v[218:221], v142 offset:22528
	ds_read_b128 v[222:225], v142 offset:23552
	global_load_lds_dwordx4 v[250:251], off
	s_add_u32 m0, s32, 0x1f00
	s_nop 0
	global_load_lds_dwordx4 v[244:245], off offset:256
	s_barrier
	s_waitcnt lgkmcnt(0)
	v_mfma_f32_16x16x32_bf16 v[62:65], v[194:197], v[164:167], v[62:65]
	v_mfma_f32_16x16x32_bf16 v[58:61], v[194:197], v[186:189], v[58:61]
	v_mfma_f32_16x16x32_bf16 v[54:57], v[202:205], v[164:167], v[54:57]
	v_mfma_f32_16x16x32_bf16 v[50:53], v[202:205], v[186:189], v[50:53]
	v_mfma_f32_16x16x32_bf16 v[46:49], v[210:213], v[164:167], v[46:49]
	v_mfma_f32_16x16x32_bf16 v[42:45], v[210:213], v[186:189], v[42:45]
	v_mfma_f32_16x16x32_bf16 v[38:41], v[218:221], v[164:167], v[38:41]
	v_mfma_f32_16x16x32_bf16 v[34:37], v[218:221], v[186:189], v[34:37]
	v_mfma_f32_16x16x32_bf16 v[62:65], v[198:201], v[182:185], v[62:65]
	v_mfma_f32_16x16x32_bf16 v[58:61], v[198:201], v[190:193], v[58:61]
	v_mfma_f32_16x16x32_bf16 v[54:57], v[206:209], v[182:185], v[54:57]
	v_mfma_f32_16x16x32_bf16 v[50:53], v[206:209], v[190:193], v[50:53]
	v_mfma_f32_16x16x32_bf16 v[46:49], v[214:217], v[182:185], v[46:49]
	v_mfma_f32_16x16x32_bf16 v[42:45], v[214:217], v[190:193], v[42:45]
	v_mfma_f32_16x16x32_bf16 v[38:41], v[222:225], v[182:185], v[38:41]
	v_mfma_f32_16x16x32_bf16 v[34:37], v[222:225], v[190:193], v[34:37]
	s_barrier
	v_lshl_add_u64 v[164:165], v[246:247], 0, s[38:39]
	s_add_u32 m0, s32, 0x14000
	s_nop 0
	global_load_lds_dwordx4 v[164:165], off
	s_add_u32 m0, s32, 0x16000
	v_lshl_add_u64 v[164:165], v[248:249], 0, s[38:39]
	global_load_lds_dwordx4 v[164:165], off
	s_waitcnt vmcnt(6)
	s_barrier
; #define G_LDA(dst, b, h)                                                                                                  \
;   _Pragma("unroll") for (int m = 0; m < 4; ++m) _Pragma("unroll") for (int k = 0; k < 2; ++k)                             \
;       dst[m][k] = *(const bf16x8*)((const char*)G_SA(b, h) + ((wr * 4 + m) * 2 + k) * 1024 + rdo)
; #define G_LDB(dst, b, h)                                                                                                  \
;   _Pragma("unroll") for (int n = 0; n < 2; ++n) _Pragma("unroll") for (int k = 0; k < 2; ++k)                             \
;       dst[n][k] = *(const bf16x8*)((const char*)G_SB(b, h) + ((wc * 2 + n) * 2 + k) * 1024 + rdo)
; #define G_WAIT_V(n) asm volatile("s_waitcnt vmcnt(" #n ")" ::: "memory")
; #define G_WAIT_L(n) asm volatile("s_waitcnt lgkmcnt(" #n ")" ::: "memory")
; #define G_BAR __builtin_amdgcn_s_barrier()
; #define G_SCHED __builtin_amdgcn_sched_barrier(0)
;     ...
;     G_WAIT_V(6); G_BAR; G_MMA(1, 1, At, B1); G_BAR;
;     G_LDB(B0, 1, 0); G_SCHED; G_LDA(At, 1, 0); G_STAGE(G_SA(0, 1), A, oa0, oa1, LDA, 128, KA(tt + 2));
;     G_WAIT_L(8); G_BAR; G_WAIT_L(0); G_MMA(0, 0, At, B0); G_BAR; G_SCHED;
;     G_LDB(B1, 1, 1); G_STAGE(G_SB(1, 0), B, ob0, ob1, LDB, 0, KB(tt + 3));
;     G_BAR; G_WAIT_L(0); G_MMA(0, 1, At, B1); G_BAR;
;     G_LDA(At, 1, 1); G_STAGE(G_SA(1, 0), A, oa0, oa1, LDA, 0, KA(tt + 3));
	v_mfma_f32_16x16x32_bf16 v[30:33], v[194:197], v[226:229], v[30:33]
	v_mfma_f32_16x16x32_bf16 v[26:29], v[194:197], v[234:237], v[26:29]
	v_mfma_f32_16x16x32_bf16 v[22:25], v[202:205], v[226:229], v[22:25]
	v_mfma_f32_16x16x32_bf16 v[18:21], v[202:205], v[234:237], v[18:21]
	v_mfma_f32_16x16x32_bf16 v[14:17], v[210:213], v[226:229], v[14:17]
	v_mfma_f32_16x16x32_bf16 v[10:13], v[210:213], v[234:237], v[10:13]
	v_mfma_f32_16x16x32_bf16 v[6:9], v[218:221], v[226:229], v[6:9]
	v_mfma_f32_16x16x32_bf16 v[2:5], v[218:221], v[234:237], v[2:5]
	v_mfma_f32_16x16x32_bf16 v[30:33], v[198:201], v[230:233], v[30:33]
	v_mfma_f32_16x16x32_bf16 v[26:29], v[198:201], v[238:241], v[26:29]
	v_mfma_f32_16x16x32_bf16 v[22:25], v[206:209], v[230:233], v[22:25]
	v_mfma_f32_16x16x32_bf16 v[18:21], v[206:209], v[238:241], v[18:21]
	v_mfma_f32_16x16x32_bf16 v[14:17], v[214:217], v[230:233], v[14:17]
	v_mfma_f32_16x16x32_bf16 v[10:13], v[214:217], v[238:241], v[10:13]
	v_mfma_f32_16x16x32_bf16 v[6:9], v[222:225], v[230:233], v[6:9]
	v_mfma_f32_16x16x32_bf16 v[2:5], v[222:225], v[238:241], v[2:5]
	s_barrier
	ds_read_b128 v[164:167], v148
	ds_read_b128 v[182:185], v148 offset:1024
	ds_read_b128 v[186:189], v148 offset:2048
	ds_read_b128 v[190:193], v148 offset:3072
	v_lshl_add_u64 v[226:227], v[242:243], 0, s[86:87]
	s_add_u32 m0, s32, 0x4000
	ds_read_b128 v[194:197], v142 offset:32768
	ds_read_b128 v[198:201], v142 offset:33792
	ds_read_b128 v[202:205], v142 offset:34816
	ds_read_b128 v[206:209], v142 offset:35840
	ds_read_b128 v[210:213], v142 offset:36864
	ds_read_b128 v[214:217], v142 offset:37888
	ds_read_b128 v[218:221], v142 offset:38912
	ds_read_b128 v[222:225], v142 offset:39936
	global_load_lds_dwordx4 v[226:227], off
	s_add_u32 m0, s32, 0x6000
	v_lshl_add_u64 v[226:227], v[244:245], 0, s[86:87]
	global_load_lds_dwordx4 v[226:227], off
	s_waitcnt lgkmcnt(8)
	s_barrier
	s_waitcnt lgkmcnt(0)
	v_mfma_f32_16x16x32_bf16 v[126:129], v[194:197], v[164:167], v[126:129]
	v_mfma_f32_16x16x32_bf16 v[122:125], v[194:197], v[186:189], v[122:125]
	v_mfma_f32_16x16x32_bf16 v[118:121], v[202:205], v[164:167], v[118:121]
	v_mfma_f32_16x16x32_bf16 v[114:117], v[202:205], v[186:189], v[114:117]
	v_mfma_f32_16x16x32_bf16 v[110:113], v[210:213], v[164:167], v[110:113]
	v_mfma_f32_16x16x32_bf16 v[106:109], v[210:213], v[186:189], v[106:109]
	v_mfma_f32_16x16x32_bf16 v[102:105], v[218:221], v[164:167], v[102:105]
	v_mfma_f32_16x16x32_bf16 v[98:101], v[218:221], v[186:189], v[98:101]
	v_mfma_f32_16x16x32_bf16 v[126:129], v[198:201], v[182:185], v[126:129]
	v_mfma_f32_16x16x32_bf16 v[122:125], v[198:201], v[190:193], v[122:125]
	v_mfma_f32_16x16x32_bf16 v[118:121], v[206:209], v[182:185], v[118:121]
	v_mfma_f32_16x16x32_bf16 v[114:117], v[206:209], v[190:193], v[114:117]
	v_mfma_f32_16x16x32_bf16 v[110:113], v[214:217], v[182:185], v[110:113]
	v_mfma_f32_16x16x32_bf16 v[106:109], v[214:217], v[190:193], v[106:109]
	v_mfma_f32_16x16x32_bf16 v[102:105], v[222:225], v[182:185], v[102:105]
	v_mfma_f32_16x16x32_bf16 v[98:101], v[222:225], v[190:193], v[98:101]
	s_barrier
	v_lshl_add_u64 v[250:251], v[246:247], 0, s[4:5]
	s_add_u32 m0, s32, 0x18000
	ds_read_b128 v[226:229], v145
	ds_read_b128 v[230:233], v145 offset:1024
	ds_read_b128 v[234:237], v145 offset:2048
	ds_read_b128 v[238:241], v145 offset:3072
	global_load_lds_dwordx4 v[250:251], off
	s_add_u32 m0, s32, 0x1a000
	v_lshl_add_u64 v[250:251], v[248:249], 0, s[4:5]
	global_load_lds_dwordx4 v[250:251], off
	s_barrier
	s_waitcnt lgkmcnt(0)
	v_mfma_f32_16x16x32_bf16 v[94:97], v[194:197], v[226:229], v[94:97]
	v_mfma_f32_16x16x32_bf16 v[90:93], v[194:197], v[234:237], v[90:93]
	v_mfma_f32_16x16x32_bf16 v[86:89], v[202:205], v[226:229], v[86:89]
	v_mfma_f32_16x16x32_bf16 v[82:85], v[202:205], v[234:237], v[82:85]
	v_mfma_f32_16x16x32_bf16 v[78:81], v[210:213], v[226:229], v[78:81]
	v_mfma_f32_16x16x32_bf16 v[74:77], v[210:213], v[234:237], v[74:77]
	v_mfma_f32_16x16x32_bf16 v[70:73], v[218:221], v[226:229], v[70:73]
	v_mfma_f32_16x16x32_bf16 v[66:69], v[218:221], v[234:237], v[66:69]
	v_mfma_f32_16x16x32_bf16 v[94:97], v[198:201], v[230:233], v[94:97]
	v_mfma_f32_16x16x32_bf16 v[90:93], v[198:201], v[238:241], v[90:93]
	v_mfma_f32_16x16x32_bf16 v[86:89], v[206:209], v[230:233], v[86:89]
	v_mfma_f32_16x16x32_bf16 v[82:85], v[206:209], v[238:241], v[82:85]
	v_mfma_f32_16x16x32_bf16 v[78:81], v[214:217], v[230:233], v[78:81]
	v_mfma_f32_16x16x32_bf16 v[74:77], v[214:217], v[238:241], v[74:77]
	v_mfma_f32_16x16x32_bf16 v[70:73], v[222:225], v[230:233], v[70:73]
	v_mfma_f32_16x16x32_bf16 v[66:69], v[222:225], v[238:241], v[66:69]
	s_add_u32 m0, s32, 0x7e80
	s_barrier
	ds_read_b128 v[194:197], v142 offset:49152
	ds_read_b128 v[198:201], v142 offset:50176
	ds_read_b128 v[202:205], v142 offset:51200
	ds_read_b128 v[206:209], v142 offset:52224
	ds_read_b128 v[210:213], v142 offset:53248
	ds_read_b128 v[214:217], v142 offset:54272
	ds_read_b128 v[218:221], v142 offset:55296
	ds_read_b128 v[222:225], v142 offset:56320
	global_load_lds_dwordx4 v[242:243], off offset:384
	s_add_u32 m0, s32, 0x9e80
	s_nop 0
	global_load_lds_dwordx4 v[244:245], off offset:384
	s_barrier
; #define G_LDA(dst, b, h)                                                                                                  \
;   _Pragma("unroll") for (int m = 0; m < 4; ++m) _Pragma("unroll") for (int k = 0; k < 2; ++k)                             \
;       dst[m][k] = *(const bf16x8*)((const char*)G_SA(b, h) + ((wr * 4 + m) * 2 + k) * 1024 + rdo)
; #define G_LDB(dst, b, h)                                                                                                  \
;   _Pragma("unroll") for (int n = 0; n < 2; ++n) _Pragma("unroll") for (int k = 0; k < 2; ++k)                             \
;       dst[n][k] = *(const bf16x8*)((const char*)G_SB(b, h) + ((wc * 2 + n) * 2 + k) * 1024 + rdo)
; #define G_WAIT_V(n) asm volatile("s_waitcnt vmcnt(" #n ")" ::: "memory")
; #define G_WAIT_L(n) asm volatile("s_waitcnt lgkmcnt(" #n ")" ::: "memory")
; #define G_BAR __builtin_amdgcn_s_barrier()
; #define G_SCHED __builtin_amdgcn_sched_barrier(0)
; DI void br_flush(PREF p, f32x4 (&acc)[2][2][4][2], int slot) { br_store(p, acc, slot); zero_acc256(acc); }
;     ...
;     G_BAR; G_WAIT_L(0); G_MMA(1, 0, At, B0); G_BAR; G_SCHED;
;     G_STAGE(G_SB(1, 1), B, ob0, ob1, LDB, 128, KB(tt + 3));
;     G_WAIT_V(6); G_BAR; G_MMA(1, 1, At, B1); G_BAR;
;     if (MODE && ((tt + 1) & 3) == 3) br_flush(p, acc, (tt + 1) >> 2);
;   }
;   {
;     G_LDB(B0, 0, 0); G_LDA(At, 0, 0); G_STAGE(G_SA(1, 1), A, oa0, oa1, LDA, 128, KA(nt - 1));
;     G_BAR; G_WAIT_L(0); G_MMA(0, 0, At, B0); G_BAR;
	s_waitcnt lgkmcnt(0)
	v_mfma_f32_16x16x32_bf16 v[62:65], v[194:197], v[164:167], v[62:65]
	v_mfma_f32_16x16x32_bf16 v[58:61], v[194:197], v[186:189], v[58:61]
	v_mfma_f32_16x16x32_bf16 v[54:57], v[202:205], v[164:167], v[54:57]
	v_mfma_f32_16x16x32_bf16 v[50:53], v[202:205], v[186:189], v[50:53]
	v_mfma_f32_16x16x32_bf16 v[46:49], v[210:213], v[164:167], v[46:49]
	v_mfma_f32_16x16x32_bf16 v[42:45], v[210:213], v[186:189], v[42:45]
	v_mfma_f32_16x16x32_bf16 v[38:41], v[218:221], v[164:167], v[38:41]
	v_mfma_f32_16x16x32_bf16 v[34:37], v[218:221], v[186:189], v[34:37]
	v_mfma_f32_16x16x32_bf16 v[62:65], v[198:201], v[182:185], v[62:65]
	v_mfma_f32_16x16x32_bf16 v[58:61], v[198:201], v[190:193], v[58:61]
	v_mfma_f32_16x16x32_bf16 v[54:57], v[206:209], v[182:185], v[54:57]
	v_mfma_f32_16x16x32_bf16 v[50:53], v[206:209], v[190:193], v[50:53]
	v_mfma_f32_16x16x32_bf16 v[46:49], v[214:217], v[182:185], v[46:49]
	v_mfma_f32_16x16x32_bf16 v[42:45], v[214:217], v[190:193], v[42:45]
	v_mfma_f32_16x16x32_bf16 v[38:41], v[222:225], v[182:185], v[38:41]
	v_mfma_f32_16x16x32_bf16 v[34:37], v[222:225], v[190:193], v[34:37]
	s_barrier
	v_lshl_add_u64 v[164:165], v[246:247], 0, s[74:75]
	s_add_u32 m0, s32, 0x1c000
	s_nop 0
	global_load_lds_dwordx4 v[164:165], off
	s_add_u32 m0, s32, 0x1e000
	v_lshl_add_u64 v[164:165], v[248:249], 0, s[74:75]
	global_load_lds_dwordx4 v[164:165], off
	s_waitcnt vmcnt(6)
	s_barrier
	v_mfma_f32_16x16x32_bf16 v[30:33], v[194:197], v[226:229], v[30:33]
	v_mfma_f32_16x16x32_bf16 v[26:29], v[194:197], v[234:237], v[26:29]
	v_mfma_f32_16x16x32_bf16 v[22:25], v[202:205], v[226:229], v[22:25]
	v_mfma_f32_16x16x32_bf16 v[18:21], v[202:205], v[234:237], v[18:21]
	v_mfma_f32_16x16x32_bf16 v[14:17], v[210:213], v[226:229], v[14:17]
	v_mfma_f32_16x16x32_bf16 v[10:13], v[210:213], v[234:237], v[10:13]
	v_mfma_f32_16x16x32_bf16 v[6:9], v[218:221], v[226:229], v[6:9]
	v_mfma_f32_16x16x32_bf16 v[2:5], v[218:221], v[234:237], v[2:5]
	v_mfma_f32_16x16x32_bf16 v[30:33], v[198:201], v[230:233], v[30:33]
	v_mfma_f32_16x16x32_bf16 v[26:29], v[198:201], v[238:241], v[26:29]
	v_mfma_f32_16x16x32_bf16 v[22:25], v[206:209], v[230:233], v[22:25]
	v_mfma_f32_16x16x32_bf16 v[18:21], v[206:209], v[238:241], v[18:21]
	v_mfma_f32_16x16x32_bf16 v[14:17], v[214:217], v[230:233], v[14:17]
	v_mfma_f32_16x16x32_bf16 v[10:13], v[214:217], v[238:241], v[10:13]
	v_mfma_f32_16x16x32_bf16 v[6:9], v[222:225], v[230:233], v[6:9]
	v_mfma_f32_16x16x32_bf16 v[2:5], v[222:225], v[238:241], v[2:5]
	s_add_i32 s10, s10, 2
	s_add_u32 s8, s8, 0x100
	s_addc_u32 s9, s9, 0
	s_cmp_lt_u32 s10, 12
	s_barrier
	s_cbranch_scc1 .LBB0_105
	v_lshl_add_u64 v[132:133], v[132:133], 1, s[34:35]
	s_add_u32 m0, s32, 0xc000
	ds_read_b128 v[134:137], v160
	ds_read_b128 v[138:141], v160 offset:1024
	ds_read_b128 v[150:153], v160 offset:2048
	ds_read_b128 v[154:157], v160 offset:3072
	ds_read_b128 v[164:167], v142
	ds_read_b128 v[182:185], v142 offset:1024
	ds_read_b128 v[186:189], v142 offset:2048
	ds_read_b128 v[190:193], v142 offset:3072
	ds_read_b128 v[194:197], v142 offset:4096
	ds_read_b128 v[198:201], v142 offset:5120
	ds_read_b128 v[202:205], v142 offset:6144
	ds_read_b128 v[206:209], v142 offset:7168
	global_load_lds_dwordx4 v[132:133], off
	s_add_u32 m0, s32, 0xe000
	v_lshl_add_u64 v[130:131], v[130:131], 1, s[34:35]
	global_load_lds_dwordx4 v[130:131], off
	s_lshl_b32 s1, s23, 8
	s_add_u32 s98, s25, s1
	s_addc_u32 s99, s48, 0
	v_bfe_u32 v251, v168, 6, 2
	v_lshlrev_b32_e32 v248, 6, v251
	v_and_b32_e32 v250, 15, v168
	v_lshl_or_b32 v248, v250, 2, v248
	global_load_dword v170, v248, s[98:99]
	s_add_u32 s98, s98, 0x1000
	s_addc_u32 s99, s99, 0
	global_load_dword v252, v248, s[98:99]
	s_add_u32 s98, s98, 0x1000
	s_addc_u32 s99, s99, 0
	global_load_dword v253, v248, s[98:99]
	s_add_u32 s98, s98, 0x1000
	s_addc_u32 s99, s99, 0
	global_load_dword v162, v248, s[98:99]
	s_lshl_b32 s1, s23, 1
	v_lshrrev_b32_e32 v249, 1, v251
	v_add_u32_e32 v249, s1, v249
	v_and_b32_e32 v249, 3, v249
	v_lshrrev_b32_e32 v250, 8, v168
	v_lshl_add_u32 v249, v250, 2, v249
	v_lshlrev_b32_e32 v249, 14, v249
	v_and_b32_e32 v250, 63, v168
	v_lshl_or_b32 v249, v250, 4, v249
	v_and_b32_e32 v250, 1, v251
	v_lshl_or_b32 v249, v250, 3, v249
	s_lshr_b32 s1, s23, 1
	s_lshl_b32 s1, s1, 12
	s_add_u32 s20, s63, s1
	s_addc_u32 s21, s64, 0
	global_load_dwordx2 v[230:231], v249, s[20:21] offset:0
	global_load_dwordx2 v[238:239], v249, s[20:21] offset:1024
	s_add_u32 s20, s20, 0x20000
	s_addc_u32 s21, s21, 0
	global_load_dwordx2 v[232:233], v249, s[20:21] offset:0
	global_load_dwordx2 v[240:241], v249, s[20:21] offset:1024
	s_add_u32 s20, s20, 0x20000
	s_addc_u32 s21, s21, 0
	global_load_dwordx2 v[234:235], v249, s[20:21] offset:0
	global_load_dwordx2 v[242:243], v249, s[20:21] offset:1024
	s_add_u32 s20, s20, 0x20000
	s_addc_u32 s21, s21, 0
	global_load_dwordx2 v[236:237], v249, s[20:21] offset:0
	global_load_dwordx2 v[244:245], v249, s[20:21] offset:1024
	s_barrier
	s_waitcnt lgkmcnt(0)
	v_mfma_f32_16x16x32_bf16 v[126:129], v[164:167], v[134:137], v[126:129]
	v_mfma_f32_16x16x32_bf16 v[122:125], v[164:167], v[150:153], v[122:125]
	v_mfma_f32_16x16x32_bf16 v[114:117], v[186:189], v[150:153], v[114:117]
	v_mfma_f32_16x16x32_bf16 v[110:113], v[194:197], v[134:137], v[110:113]
	v_mfma_f32_16x16x32_bf16 v[106:109], v[194:197], v[150:153], v[106:109]
	v_mfma_f32_16x16x32_bf16 v[102:105], v[202:205], v[134:137], v[102:105]
	v_mfma_f32_16x16x32_bf16 v[98:101], v[202:205], v[150:153], v[98:101]
	v_mfma_f32_16x16x32_bf16 v[126:129], v[182:185], v[138:141], v[126:129]
	v_mfma_f32_16x16x32_bf16 v[122:125], v[182:185], v[154:157], v[122:125]
	v_mfma_f32_16x16x32_bf16 v[118:121], v[186:189], v[134:137], v[118:121]
	v_mfma_f32_16x16x32_bf16 v[114:117], v[190:193], v[154:157], v[114:117]
	v_mfma_f32_16x16x32_bf16 v[110:113], v[198:201], v[138:141], v[110:113]
	v_mfma_f32_16x16x32_bf16 v[106:109], v[198:201], v[154:157], v[106:109]
	v_mfma_f32_16x16x32_bf16 v[102:105], v[206:209], v[138:141], v[102:105]
	v_mfma_f32_16x16x32_bf16 v[98:101], v[206:209], v[154:157], v[98:101]
	v_mfma_f32_16x16x32_bf16 v[118:121], v[190:193], v[138:141], v[118:121]
	s_barrier
; #define G_LDA(dst, b, h)                                                                                                  \
;   _Pragma("unroll") for (int m = 0; m < 4; ++m) _Pragma("unroll") for (int k = 0; k < 2; ++k)                             \
;       dst[m][k] = *(const bf16x8*)((const char*)G_SA(b, h) + ((wr * 4 + m) * 2 + k) * 1024 + rdo)
; #define G_LDB(dst, b, h)                                                                                                  \
;   _Pragma("unroll") for (int n = 0; n < 2; ++n) _Pragma("unroll") for (int k = 0; k < 2; ++k)                             \
;       dst[n][k] = *(const bf16x8*)((const char*)G_SB(b, h) + ((wc * 2 + n) * 2 + k) * 1024 + rdo)
; #define G_WAIT_V(n) asm volatile("s_waitcnt vmcnt(" #n ")" ::: "memory")
; #define G_WAIT_L(n) asm volatile("s_waitcnt lgkmcnt(" #n ")" ::: "memory")
; #define G_BAR __builtin_amdgcn_s_barrier()
;     ...
;     G_LDB(B1, 0, 1); G_BAR; G_WAIT_L(0); G_MMA(0, 1, At, B1); G_BAR;
;     G_LDA(At, 0, 1); G_WAIT_V(4); G_BAR; G_WAIT_L(0); G_MMA(1, 0, At, B0); G_MMA(1, 1, At, B1); G_BAR;
;   }
;   {
;     G_LDB(B0, 1, 0); G_LDA(At, 1, 0); G_WAIT_V(2); G_BAR; G_WAIT_L(0); G_MMA(0, 0, At, B0); G_BAR;
	ds_read_b128 v[130:133], v158
	ds_read_b128 v[210:213], v158 offset:1024
	ds_read_b128 v[214:217], v158 offset:2048
	ds_read_b128 v[158:161], v158 offset:3072
	s_barrier
	s_waitcnt lgkmcnt(0)
	v_mfma_f32_16x16x32_bf16 v[94:97], v[164:167], v[130:133], v[94:97]
	v_mfma_f32_16x16x32_bf16 v[90:93], v[164:167], v[214:217], v[90:93]
	v_mfma_f32_16x16x32_bf16 v[86:89], v[186:189], v[130:133], v[86:89]
	v_mfma_f32_16x16x32_bf16 v[82:85], v[186:189], v[214:217], v[82:85]
	v_mfma_f32_16x16x32_bf16 v[78:81], v[194:197], v[130:133], v[78:81]
	v_mfma_f32_16x16x32_bf16 v[74:77], v[194:197], v[214:217], v[74:77]
	v_mfma_f32_16x16x32_bf16 v[70:73], v[202:205], v[130:133], v[70:73]
	v_mfma_f32_16x16x32_bf16 v[66:69], v[202:205], v[214:217], v[66:69]
	v_mfma_f32_16x16x32_bf16 v[94:97], v[182:185], v[210:213], v[94:97]
	v_mfma_f32_16x16x32_bf16 v[90:93], v[182:185], v[158:161], v[90:93]
	v_mfma_f32_16x16x32_bf16 v[86:89], v[190:193], v[210:213], v[86:89]
	v_mfma_f32_16x16x32_bf16 v[82:85], v[190:193], v[158:161], v[82:85]
	v_mfma_f32_16x16x32_bf16 v[78:81], v[198:201], v[210:213], v[78:81]
	v_mfma_f32_16x16x32_bf16 v[74:77], v[198:201], v[158:161], v[74:77]
	v_mfma_f32_16x16x32_bf16 v[70:73], v[206:209], v[210:213], v[70:73]
	v_mfma_f32_16x16x32_bf16 v[66:69], v[206:209], v[158:161], v[66:69]
	s_barrier
	ds_read_b128 v[164:167], v142 offset:16384
	ds_read_b128 v[182:185], v142 offset:17408
	ds_read_b128 v[186:189], v142 offset:18432
	ds_read_b128 v[190:193], v142 offset:19456
	ds_read_b128 v[194:197], v142 offset:20480
	ds_read_b128 v[198:201], v142 offset:21504
	ds_read_b128 v[202:205], v142 offset:22528
	ds_read_b128 v[206:209], v142 offset:23552
	s_waitcnt vmcnt(16)
	s_barrier
	s_waitcnt lgkmcnt(0)
	v_mfma_f32_16x16x32_bf16 v[62:65], v[164:167], v[134:137], v[62:65]
	v_mfma_f32_16x16x32_bf16 v[58:61], v[164:167], v[150:153], v[58:61]
	v_mfma_f32_16x16x32_bf16 v[54:57], v[186:189], v[134:137], v[54:57]
	v_mfma_f32_16x16x32_bf16 v[50:53], v[186:189], v[150:153], v[50:53]
	v_mfma_f32_16x16x32_bf16 v[46:49], v[194:197], v[134:137], v[46:49]
	v_mfma_f32_16x16x32_bf16 v[38:41], v[202:205], v[134:137], v[38:41]
	v_mfma_f32_16x16x32_bf16 v[34:37], v[202:205], v[150:153], v[34:37]
	v_mfma_f32_16x16x32_bf16 v[62:65], v[182:185], v[138:141], v[62:65]
	v_mfma_f32_16x16x32_bf16 v[58:61], v[182:185], v[154:157], v[58:61]
	v_mfma_f32_16x16x32_bf16 v[54:57], v[190:193], v[138:141], v[54:57]
	v_mfma_f32_16x16x32_bf16 v[50:53], v[190:193], v[154:157], v[50:53]
	v_mfma_f32_16x16x32_bf16 v[46:49], v[198:201], v[138:141], v[46:49]
	v_mfma_f32_16x16x32_bf16 v[42:45], v[194:197], v[150:153], v[42:45]
	v_mfma_f32_16x16x32_bf16 v[38:41], v[206:209], v[138:141], v[38:41]
	v_mfma_f32_16x16x32_bf16 v[34:37], v[206:209], v[154:157], v[34:37]
	v_mfma_f32_16x16x32_bf16 v[42:45], v[198:201], v[154:157], v[42:45]
	v_mfma_f32_16x16x32_bf16 v[26:29], v[164:167], v[214:217], v[26:29]
	v_mfma_f32_16x16x32_bf16 v[22:25], v[186:189], v[130:133], v[22:25]
	v_mfma_f32_16x16x32_bf16 v[14:17], v[194:197], v[130:133], v[14:17]
	v_mfma_f32_16x16x32_bf16 v[10:13], v[194:197], v[214:217], v[10:13]
	v_mfma_f32_16x16x32_bf16 v[2:5], v[202:205], v[214:217], v[2:5]
	v_mfma_f32_16x16x32_bf16 v[30:33], v[164:167], v[130:133], v[30:33]
	v_mfma_f32_16x16x32_bf16 v[26:29], v[182:185], v[158:161], v[26:29]
	v_mfma_f32_16x16x32_bf16 v[22:25], v[190:193], v[210:213], v[22:25]
	v_mfma_f32_16x16x32_bf16 v[18:21], v[186:189], v[214:217], v[18:21]
	v_mfma_f32_16x16x32_bf16 v[14:17], v[198:201], v[210:213], v[14:17]
	v_mfma_f32_16x16x32_bf16 v[10:13], v[198:201], v[158:161], v[10:13]
	v_mfma_f32_16x16x32_bf16 v[6:9], v[202:205], v[130:133], v[6:9]
	v_mfma_f32_16x16x32_bf16 v[2:5], v[206:209], v[158:161], v[2:5]
	v_mfma_f32_16x16x32_bf16 v[30:33], v[182:185], v[210:213], v[30:33]
	v_mfma_f32_16x16x32_bf16 v[18:21], v[190:193], v[158:161], v[18:21]
	v_mfma_f32_16x16x32_bf16 v[6:9], v[206:209], v[210:213], v[6:9]
	s_barrier
	ds_read_b128 v[130:133], v148
	ds_read_b128 v[154:157], v148 offset:1024
	ds_read_b128 v[164:167], v148 offset:2048
	ds_read_b128 v[182:185], v148 offset:3072
	ds_read_b128 v[186:189], v142 offset:32768
	ds_read_b128 v[190:193], v142 offset:33792
	ds_read_b128 v[194:197], v142 offset:34816
	ds_read_b128 v[198:201], v142 offset:35840
	ds_read_b128 v[202:205], v142 offset:36864
	ds_read_b128 v[206:209], v142 offset:37888
	ds_read_b128 v[210:213], v142 offset:38912
	ds_read_b128 v[214:217], v142 offset:39936
	s_waitcnt vmcnt(14)
	s_barrier
; #define G_LDA(dst, b, h)                                                                                                  \
;   _Pragma("unroll") for (int m = 0; m < 4; ++m) _Pragma("unroll") for (int k = 0; k < 2; ++k)                             \
;       dst[m][k] = *(const bf16x8*)((const char*)G_SA(b, h) + ((wr * 4 + m) * 2 + k) * 1024 + rdo)
; #define G_LDB(dst, b, h)                                                                                                  \
;   _Pragma("unroll") for (int n = 0; n < 2; ++n) _Pragma("unroll") for (int k = 0; k < 2; ++k)                             \
;       dst[n][k] = *(const bf16x8*)((const char*)G_SB(b, h) + ((wc * 2 + n) * 2 + k) * 1024 + rdo)
; #define G_WAIT_V(n) asm volatile("s_waitcnt vmcnt(" #n ")" ::: "memory")
; #define G_WAIT_L(n) asm volatile("s_waitcnt lgkmcnt(" #n ")" ::: "memory")
; #define G_BAR __builtin_amdgcn_s_barrier()
;     ...
;     G_LDB(B0, 1, 0); G_LDA(At, 1, 0); G_WAIT_V(2); G_BAR; G_WAIT_L(0); G_MMA(0, 0, At, B0); G_BAR;
;     G_LDB(B1, 1, 1); G_WAIT_V(0); G_BAR; G_WAIT_L(0); G_MMA(0, 1, At, B1); G_BAR;
;     G_LDA(At, 1, 1); G_BAR; G_WAIT_L(0); G_MMA(1, 0, At, B0); G_MMA(1, 1, At, B1); G_BAR;
;   }
;   if (wr == 0) G_BAR;
	s_waitcnt lgkmcnt(0)
	v_mfma_f32_16x16x32_bf16 v[126:129], v[186:189], v[130:133], v[126:129]
	v_mfma_f32_16x16x32_bf16 v[122:125], v[186:189], v[164:167], v[122:125]
	v_mfma_f32_16x16x32_bf16 v[118:121], v[194:197], v[130:133], v[118:121]
	v_mfma_f32_16x16x32_bf16 v[114:117], v[194:197], v[164:167], v[114:117]
	v_mfma_f32_16x16x32_bf16 v[110:113], v[202:205], v[130:133], v[110:113]
	v_mfma_f32_16x16x32_bf16 v[106:109], v[202:205], v[164:167], v[106:109]
	v_mfma_f32_16x16x32_bf16 v[102:105], v[210:213], v[130:133], v[102:105]
	v_mfma_f32_16x16x32_bf16 v[98:101], v[210:213], v[164:167], v[98:101]
	v_mfma_f32_16x16x32_bf16 v[158:161], v[190:193], v[154:157], v[126:129]
	v_mfma_f32_16x16x32_bf16 v[150:153], v[190:193], v[182:185], v[122:125]
	v_mfma_f32_16x16x32_bf16 v[146:149], v[198:201], v[154:157], v[118:121]
	v_mfma_f32_16x16x32_bf16 v[138:141], v[198:201], v[182:185], v[114:117]
	v_mfma_f32_16x16x32_bf16 v[134:137], v[206:209], v[154:157], v[110:113]
	v_mfma_f32_16x16x32_bf16 v[126:129], v[206:209], v[182:185], v[106:109]
	v_mfma_f32_16x16x32_bf16 v[122:125], v[214:217], v[154:157], v[102:105]
	v_mfma_f32_16x16x32_bf16 v[114:117], v[214:217], v[182:185], v[98:101]
	s_barrier
	ds_read_b128 v[118:121], v145
	ds_read_b128 v[218:221], v145 offset:1024
	ds_read_b128 v[222:225], v145 offset:2048
	ds_read_b128 v[226:229], v145 offset:3072
	s_waitcnt vmcnt(12)
	s_barrier
	s_waitcnt lgkmcnt(0)
	v_mfma_f32_16x16x32_bf16 v[94:97], v[186:189], v[118:121], v[94:97]
	v_mfma_f32_16x16x32_bf16 v[90:93], v[186:189], v[222:225], v[90:93]
	v_mfma_f32_16x16x32_bf16 v[86:89], v[194:197], v[118:121], v[86:89]
	v_mfma_f32_16x16x32_bf16 v[82:85], v[194:197], v[222:225], v[82:85]
	v_mfma_f32_16x16x32_bf16 v[78:81], v[202:205], v[118:121], v[78:81]
	v_mfma_f32_16x16x32_bf16 v[74:77], v[202:205], v[222:225], v[74:77]
	v_mfma_f32_16x16x32_bf16 v[70:73], v[210:213], v[118:121], v[70:73]
	v_mfma_f32_16x16x32_bf16 v[66:69], v[210:213], v[222:225], v[66:69]
	v_mfma_f32_16x16x32_bf16 v[110:113], v[190:193], v[218:221], v[94:97]
	v_mfma_f32_16x16x32_bf16 v[106:109], v[190:193], v[226:229], v[90:93]
	v_mfma_f32_16x16x32_bf16 v[102:105], v[198:201], v[218:221], v[86:89]
	v_mfma_f32_16x16x32_bf16 v[98:101], v[198:201], v[226:229], v[82:85]
	v_mfma_f32_16x16x32_bf16 v[94:97], v[206:209], v[218:221], v[78:81]
	v_mfma_f32_16x16x32_bf16 v[90:93], v[206:209], v[226:229], v[74:77]
	v_mfma_f32_16x16x32_bf16 v[86:89], v[214:217], v[218:221], v[70:73]
	v_mfma_f32_16x16x32_bf16 v[82:85], v[214:217], v[226:229], v[66:69]
	s_barrier
	ds_read_b128 v[186:189], v142 offset:49152
	ds_read_b128 v[190:193], v142 offset:50176
	ds_read_b128 v[194:197], v142 offset:51200
	ds_read_b128 v[198:201], v142 offset:52224
	ds_read_b128 v[202:205], v142 offset:53248
	ds_read_b128 v[206:209], v142 offset:54272
	ds_read_b128 v[210:213], v142 offset:55296
	ds_read_b128 v[142:145], v142 offset:56320
	s_barrier
	s_waitcnt lgkmcnt(0)
	v_mfma_f32_16x16x32_bf16 v[62:65], v[186:189], v[130:133], v[62:65]
	v_mfma_f32_16x16x32_bf16 v[58:61], v[186:189], v[164:167], v[58:61]
	v_mfma_f32_16x16x32_bf16 v[54:57], v[194:197], v[130:133], v[54:57]
	v_mfma_f32_16x16x32_bf16 v[50:53], v[194:197], v[164:167], v[50:53]
	v_mfma_f32_16x16x32_bf16 v[46:49], v[202:205], v[130:133], v[46:49]
	v_mfma_f32_16x16x32_bf16 v[42:45], v[202:205], v[164:167], v[42:45]
	v_mfma_f32_16x16x32_bf16 v[38:41], v[210:213], v[130:133], v[38:41]
	v_mfma_f32_16x16x32_bf16 v[34:37], v[210:213], v[164:167], v[34:37]
	v_mfma_f32_16x16x32_bf16 v[78:81], v[190:193], v[154:157], v[62:65]
	v_mfma_f32_16x16x32_bf16 v[74:77], v[190:193], v[182:185], v[58:61]
	v_mfma_f32_16x16x32_bf16 v[70:73], v[198:201], v[154:157], v[54:57]
	v_mfma_f32_16x16x32_bf16 v[66:69], v[198:201], v[182:185], v[50:53]
	v_mfma_f32_16x16x32_bf16 v[62:65], v[206:209], v[154:157], v[46:49]
	v_mfma_f32_16x16x32_bf16 v[58:61], v[206:209], v[182:185], v[42:45]
	v_mfma_f32_16x16x32_bf16 v[54:57], v[142:145], v[154:157], v[38:41]
	v_mfma_f32_16x16x32_bf16 v[50:53], v[142:145], v[182:185], v[34:37]
	v_mfma_f32_16x16x32_bf16 v[30:33], v[186:189], v[118:121], v[30:33]
	v_mfma_f32_16x16x32_bf16 v[26:29], v[186:189], v[222:225], v[26:29]
	v_mfma_f32_16x16x32_bf16 v[22:25], v[194:197], v[118:121], v[22:25]
	v_mfma_f32_16x16x32_bf16 v[18:21], v[194:197], v[222:225], v[18:21]
	v_mfma_f32_16x16x32_bf16 v[14:17], v[202:205], v[118:121], v[14:17]
	v_mfma_f32_16x16x32_bf16 v[10:13], v[202:205], v[222:225], v[10:13]
	v_mfma_f32_16x16x32_bf16 v[6:9], v[210:213], v[118:121], v[6:9]
	v_mfma_f32_16x16x32_bf16 v[2:5], v[210:213], v[222:225], v[2:5]
	v_mfma_f32_16x16x32_bf16 v[46:49], v[190:193], v[218:221], v[30:33]
	v_mfma_f32_16x16x32_bf16 v[38:41], v[190:193], v[226:229], v[26:29]
	v_mfma_f32_16x16x32_bf16 v[34:37], v[198:201], v[218:221], v[22:25]
	v_mfma_f32_16x16x32_bf16 v[26:29], v[198:201], v[226:229], v[18:21]
	v_mfma_f32_16x16x32_bf16 v[22:25], v[206:209], v[218:221], v[14:17]
	v_mfma_f32_16x16x32_bf16 v[14:17], v[206:209], v[226:229], v[10:13]
	v_mfma_f32_16x16x32_bf16 v[10:13], v[142:145], v[218:221], v[6:9]
	v_mfma_f32_16x16x32_bf16 v[2:5], v[142:145], v[226:229], v[2:5]
	v_cmp_gt_u32_e32 vcc, s67, v0
	s_barrier
	s_and_saveexec_b64 s[8:9], vcc
	s_cbranch_execz .LBB0_108
	s_barrier

; #define G_LDA(dst, b, h)                                                                                                  \
;   _Pragma("unroll") for (int m = 0; m < 4; ++m) _Pragma("unroll") for (int k = 0; k < 2; ++k)                             \
;       dst[m][k] = *(const bf16x8*)((const char*)G_SA(b, h) + ((wr * 4 + m) * 2 + k) * 1024 + rdo)
; #define G_LDB(dst, b, h)                                                                                                  \
;   _Pragma("unroll") for (int n = 0; n < 2; ++n) _Pragma("unroll") for (int k = 0; k < 2; ++k)                             \
;       dst[n][k] = *(const bf16x8*)((const char*)G_SB(b, h) + ((wc * 2 + n) * 2 + k) * 1024 + rdo)
; #define G_WAIT_V(n) asm volatile("s_waitcnt vmcnt(" #n ")" ::: "memory")
; #define G_WAIT_L(n) asm volatile("s_waitcnt lgkmcnt(" #n ")" ::: "memory")
; #define G_BAR __builtin_amdgcn_s_barrier()
; #define G_SCHED __builtin_amdgcn_sched_barrier(0)
;     ...
;     G_LDB(B0, 0, 0); G_SCHED; G_LDA(At, 0, 0); G_STAGE(G_SA(1, 1), A, oa0, oa1, LDA, 128, KA(tt + 1));
;     G_WAIT_L(8); G_BAR; G_WAIT_L(0); G_MMA(0, 0, At, B0); G_BAR; G_SCHED;
;     G_LDB(B1, 0, 1); G_STAGE(G_SB(0, 0), B, ob0, ob1, LDB, 0, KB(tt + 2));
;     G_BAR; G_WAIT_L(0); G_MMA(0, 1, At, B1); G_BAR;
;     G_LDA(At, 0, 1); G_STAGE(G_SA(0, 0), A, oa0, oa1, LDA, 0, KA(tt + 2));
;     G_BAR; G_WAIT_L(0); G_MMA(1, 0, At, B0); G_BAR; G_SCHED;
;     G_STAGE(G_SB(0, 1), B, ob0, ob1, LDB, 128, KB(tt + 2));
;     G_WAIT_V(6); G_BAR; G_MMA(1, 1, At, B1); G_BAR;
.LBB0_453:
	ds_read_b128 v[182:185], v161
	ds_read_b128 v[186:189], v161 offset:1024
	ds_read_b128 v[190:193], v161 offset:2048
	ds_read_b128 v[194:197], v161 offset:3072
	v_lshl_add_u64 v[166:167], v[136:137], 0, s[20:21]
	v_lshl_add_u64 v[164:165], v[166:167], 0, s[78:79]
	s_add_u32 m0, s32, 0xc000
	ds_read_b128 v[198:201], v143
	ds_read_b128 v[202:205], v143 offset:1024
	ds_read_b128 v[206:209], v143 offset:2048
	ds_read_b128 v[210:213], v143 offset:3072
	ds_read_b128 v[214:217], v143 offset:4096
	ds_read_b128 v[218:221], v143 offset:5120
	ds_read_b128 v[222:225], v143 offset:6144
	ds_read_b128 v[226:229], v143 offset:7168
	global_load_lds_dwordx4 v[164:165], off
	v_lshl_add_u64 v[246:247], v[134:135], 0, s[20:21]
	s_add_u32 m0, s32, 0xe000
	v_lshl_add_u64 v[230:231], v[246:247], 0, s[78:79]
	global_load_lds_dwordx4 v[230:231], off
	s_waitcnt lgkmcnt(8)
	s_barrier
	s_waitcnt lgkmcnt(0)
	v_mfma_f32_16x16x32_bf16 v[126:129], v[198:201], v[182:185], v[126:129]
	v_mfma_f32_16x16x32_bf16 v[122:125], v[198:201], v[190:193], v[122:125]
	v_mfma_f32_16x16x32_bf16 v[118:121], v[206:209], v[182:185], v[118:121]
	v_mfma_f32_16x16x32_bf16 v[114:117], v[206:209], v[190:193], v[114:117]
	v_mfma_f32_16x16x32_bf16 v[110:113], v[214:217], v[182:185], v[110:113]
	v_mfma_f32_16x16x32_bf16 v[106:109], v[214:217], v[190:193], v[106:109]
	v_mfma_f32_16x16x32_bf16 v[102:105], v[222:225], v[182:185], v[102:105]
	v_mfma_f32_16x16x32_bf16 v[98:101], v[222:225], v[190:193], v[98:101]
	v_mfma_f32_16x16x32_bf16 v[126:129], v[202:205], v[186:189], v[126:129]
	v_mfma_f32_16x16x32_bf16 v[122:125], v[202:205], v[194:197], v[122:125]
	v_mfma_f32_16x16x32_bf16 v[118:121], v[210:213], v[186:189], v[118:121]
	v_mfma_f32_16x16x32_bf16 v[114:117], v[210:213], v[194:197], v[114:117]
	v_mfma_f32_16x16x32_bf16 v[110:113], v[218:221], v[186:189], v[110:113]
	v_mfma_f32_16x16x32_bf16 v[106:109], v[218:221], v[194:197], v[106:109]
	v_mfma_f32_16x16x32_bf16 v[102:105], v[226:229], v[186:189], v[102:105]
	v_mfma_f32_16x16x32_bf16 v[98:101], v[226:229], v[194:197], v[98:101]
	s_barrier
	v_lshl_add_u64 v[248:249], v[140:141], 0, s[20:21]
	s_add_u32 m0, s32, 0xff00
	ds_read_b128 v[230:233], v159
	ds_read_b128 v[234:237], v159 offset:1024
	ds_read_b128 v[238:241], v159 offset:2048
	ds_read_b128 v[242:245], v159 offset:3072
	global_load_lds_dwordx4 v[248:249], off offset:256
	v_lshl_add_u64 v[250:251], v[138:139], 0, s[20:21]
	s_add_u32 m0, s32, 0x11f00
	s_nop 0
	global_load_lds_dwordx4 v[250:251], off offset:256
	s_barrier
	s_waitcnt lgkmcnt(0)
	v_mfma_f32_16x16x32_bf16 v[94:97], v[198:201], v[230:233], v[94:97]
	v_mfma_f32_16x16x32_bf16 v[86:89], v[198:201], v[238:241], v[86:89]
	v_mfma_f32_16x16x32_bf16 v[70:73], v[206:209], v[230:233], v[70:73]
	v_mfma_f32_16x16x32_bf16 v[58:61], v[206:209], v[238:241], v[58:61]
	v_mfma_f32_16x16x32_bf16 v[54:57], v[214:217], v[230:233], v[54:57]
	v_mfma_f32_16x16x32_bf16 v[50:53], v[214:217], v[238:241], v[50:53]
	v_mfma_f32_16x16x32_bf16 v[46:49], v[222:225], v[230:233], v[46:49]
	v_mfma_f32_16x16x32_bf16 v[42:45], v[222:225], v[238:241], v[42:45]
	v_mfma_f32_16x16x32_bf16 v[94:97], v[202:205], v[234:237], v[94:97]
	v_mfma_f32_16x16x32_bf16 v[86:89], v[202:205], v[242:245], v[86:89]
	v_mfma_f32_16x16x32_bf16 v[70:73], v[210:213], v[234:237], v[70:73]
	v_mfma_f32_16x16x32_bf16 v[58:61], v[210:213], v[242:245], v[58:61]
	v_mfma_f32_16x16x32_bf16 v[54:57], v[218:221], v[234:237], v[54:57]
	v_mfma_f32_16x16x32_bf16 v[50:53], v[218:221], v[242:245], v[50:53]
	v_mfma_f32_16x16x32_bf16 v[46:49], v[226:229], v[234:237], v[46:49]
	v_mfma_f32_16x16x32_bf16 v[42:45], v[226:229], v[242:245], v[42:45]
	v_lshl_add_u64 v[252:253], v[166:167], 0, s[82:83]
	s_mov_b32 m0, s32
	s_barrier
	ds_read_b128 v[198:201], v143 offset:16384
	ds_read_b128 v[202:205], v143 offset:17408
	ds_read_b128 v[206:209], v143 offset:18432
	ds_read_b128 v[210:213], v143 offset:19456
	ds_read_b128 v[214:217], v143 offset:20480
	ds_read_b128 v[218:221], v143 offset:21504
	ds_read_b128 v[222:225], v143 offset:22528
	ds_read_b128 v[226:229], v143 offset:23552
	global_load_lds_dwordx4 v[252:253], off
	s_add_u32 m0, s32, 0x1f00
	s_nop 0
	global_load_lds_dwordx4 v[246:247], off offset:256
	s_barrier
	s_waitcnt lgkmcnt(0)
	v_mfma_f32_16x16x32_bf16 v[38:41], v[198:201], v[182:185], v[38:41]
	v_mfma_f32_16x16x32_bf16 v[34:37], v[198:201], v[190:193], v[34:37]
	v_mfma_f32_16x16x32_bf16 v[30:33], v[206:209], v[182:185], v[30:33]
	v_mfma_f32_16x16x32_bf16 v[26:29], v[206:209], v[190:193], v[26:29]
	v_mfma_f32_16x16x32_bf16 v[22:25], v[214:217], v[182:185], v[22:25]
	v_mfma_f32_16x16x32_bf16 v[18:21], v[214:217], v[190:193], v[18:21]
	v_mfma_f32_16x16x32_bf16 v[14:17], v[222:225], v[182:185], v[14:17]
	v_mfma_f32_16x16x32_bf16 v[10:13], v[222:225], v[190:193], v[10:13]
	v_mfma_f32_16x16x32_bf16 v[38:41], v[202:205], v[186:189], v[38:41]
	v_mfma_f32_16x16x32_bf16 v[34:37], v[202:205], v[194:197], v[34:37]
	v_mfma_f32_16x16x32_bf16 v[30:33], v[210:213], v[186:189], v[30:33]
	v_mfma_f32_16x16x32_bf16 v[26:29], v[210:213], v[194:197], v[26:29]
	v_mfma_f32_16x16x32_bf16 v[22:25], v[218:221], v[186:189], v[22:25]
	v_mfma_f32_16x16x32_bf16 v[18:21], v[218:221], v[194:197], v[18:21]
	v_mfma_f32_16x16x32_bf16 v[14:17], v[226:229], v[186:189], v[14:17]
	v_mfma_f32_16x16x32_bf16 v[10:13], v[226:229], v[194:197], v[10:13]
	s_barrier
	v_lshl_add_u64 v[182:183], v[248:249], 0, s[86:87]
	s_add_u32 m0, s32, 0x14000
	s_nop 0
	global_load_lds_dwordx4 v[182:183], off
	s_add_u32 m0, s32, 0x16000
	v_lshl_add_u64 v[182:183], v[250:251], 0, s[86:87]
	global_load_lds_dwordx4 v[182:183], off
	s_waitcnt vmcnt(6)
	s_barrier
; #define G_LDA(dst, b, h)                                                                                                  \
;   _Pragma("unroll") for (int m = 0; m < 4; ++m) _Pragma("unroll") for (int k = 0; k < 2; ++k)                             \
;       dst[m][k] = *(const bf16x8*)((const char*)G_SA(b, h) + ((wr * 4 + m) * 2 + k) * 1024 + rdo)
; #define G_LDB(dst, b, h)                                                                                                  \
;   _Pragma("unroll") for (int n = 0; n < 2; ++n) _Pragma("unroll") for (int k = 0; k < 2; ++k)                             \
;       dst[n][k] = *(const bf16x8*)((const char*)G_SB(b, h) + ((wc * 2 + n) * 2 + k) * 1024 + rdo)
; #define G_WAIT_V(n) asm volatile("s_waitcnt vmcnt(" #n ")" ::: "memory")
; #define G_WAIT_L(n) asm volatile("s_waitcnt lgkmcnt(" #n ")" ::: "memory")
; #define G_BAR __builtin_amdgcn_s_barrier()
; #define G_SCHED __builtin_amdgcn_sched_barrier(0)
;     ...
;     G_WAIT_V(6); G_BAR; G_MMA(1, 1, At, B1); G_BAR;
;     G_LDB(B0, 1, 0); G_SCHED; G_LDA(At, 1, 0); G_STAGE(G_SA(0, 1), A, oa0, oa1, LDA, 128, KA(tt + 2));
;     G_WAIT_L(8); G_BAR; G_WAIT_L(0); G_MMA(0, 0, At, B0); G_BAR; G_SCHED;
;     G_LDB(B1, 1, 1); G_STAGE(G_SB(1, 0), B, ob0, ob1, LDB, 0, KB(tt + 3));
;     G_BAR; G_WAIT_L(0); G_MMA(0, 1, At, B1); G_BAR;
;     G_LDA(At, 1, 1); G_STAGE(G_SA(1, 0), A, oa0, oa1, LDA, 0, KA(tt + 3));
	v_mfma_f32_16x16x32_bf16 v[6:9], v[198:201], v[230:233], v[6:9]
	v_mfma_f32_16x16x32_bf16 v[2:5], v[198:201], v[238:241], v[2:5]
	v_mfma_f32_16x16x32_bf16 v[62:65], v[206:209], v[230:233], v[62:65]
	v_mfma_f32_16x16x32_bf16 v[66:69], v[206:209], v[238:241], v[66:69]
	v_mfma_f32_16x16x32_bf16 v[74:77], v[214:217], v[230:233], v[74:77]
	v_mfma_f32_16x16x32_bf16 v[78:81], v[214:217], v[238:241], v[78:81]
	v_mfma_f32_16x16x32_bf16 v[82:85], v[222:225], v[230:233], v[82:85]
	v_mfma_f32_16x16x32_bf16 v[90:93], v[222:225], v[238:241], v[90:93]
	v_mfma_f32_16x16x32_bf16 v[6:9], v[202:205], v[234:237], v[6:9]
	v_mfma_f32_16x16x32_bf16 v[2:5], v[202:205], v[242:245], v[2:5]
	v_mfma_f32_16x16x32_bf16 v[62:65], v[210:213], v[234:237], v[62:65]
	v_mfma_f32_16x16x32_bf16 v[66:69], v[210:213], v[242:245], v[66:69]
	v_mfma_f32_16x16x32_bf16 v[74:77], v[218:221], v[234:237], v[74:77]
	v_mfma_f32_16x16x32_bf16 v[78:81], v[218:221], v[242:245], v[78:81]
	v_mfma_f32_16x16x32_bf16 v[82:85], v[226:229], v[234:237], v[82:85]
	v_mfma_f32_16x16x32_bf16 v[90:93], v[226:229], v[242:245], v[90:93]
	s_barrier
	ds_read_b128 v[182:185], v150
	ds_read_b128 v[186:189], v150 offset:1024
	ds_read_b128 v[190:193], v150 offset:2048
	ds_read_b128 v[194:197], v150 offset:3072
	v_lshl_add_u64 v[230:231], v[166:167], 0, s[86:87]
	s_add_u32 m0, s32, 0x4000
	ds_read_b128 v[198:201], v143 offset:32768
	ds_read_b128 v[202:205], v143 offset:33792
	ds_read_b128 v[206:209], v143 offset:34816
	ds_read_b128 v[210:213], v143 offset:35840
	ds_read_b128 v[214:217], v143 offset:36864
	ds_read_b128 v[218:221], v143 offset:37888
	ds_read_b128 v[222:225], v143 offset:38912
	ds_read_b128 v[226:229], v143 offset:39936
	global_load_lds_dwordx4 v[230:231], off
	s_add_u32 m0, s32, 0x6000
	v_lshl_add_u64 v[230:231], v[246:247], 0, s[86:87]
	global_load_lds_dwordx4 v[230:231], off
	s_waitcnt lgkmcnt(8)
	s_barrier
	s_waitcnt lgkmcnt(0)
	v_mfma_f32_16x16x32_bf16 v[126:129], v[198:201], v[182:185], v[126:129]
	v_mfma_f32_16x16x32_bf16 v[122:125], v[198:201], v[190:193], v[122:125]
	v_mfma_f32_16x16x32_bf16 v[118:121], v[206:209], v[182:185], v[118:121]
	v_mfma_f32_16x16x32_bf16 v[114:117], v[206:209], v[190:193], v[114:117]
	v_mfma_f32_16x16x32_bf16 v[110:113], v[214:217], v[182:185], v[110:113]
	v_mfma_f32_16x16x32_bf16 v[106:109], v[214:217], v[190:193], v[106:109]
	v_mfma_f32_16x16x32_bf16 v[102:105], v[222:225], v[182:185], v[102:105]
	v_mfma_f32_16x16x32_bf16 v[98:101], v[222:225], v[190:193], v[98:101]
	v_mfma_f32_16x16x32_bf16 v[126:129], v[202:205], v[186:189], v[126:129]
	v_mfma_f32_16x16x32_bf16 v[122:125], v[202:205], v[194:197], v[122:125]
	v_mfma_f32_16x16x32_bf16 v[118:121], v[210:213], v[186:189], v[118:121]
	v_mfma_f32_16x16x32_bf16 v[114:117], v[210:213], v[194:197], v[114:117]
	v_mfma_f32_16x16x32_bf16 v[110:113], v[218:221], v[186:189], v[110:113]
	v_mfma_f32_16x16x32_bf16 v[106:109], v[218:221], v[194:197], v[106:109]
	v_mfma_f32_16x16x32_bf16 v[102:105], v[226:229], v[186:189], v[102:105]
	v_mfma_f32_16x16x32_bf16 v[98:101], v[226:229], v[194:197], v[98:101]
	s_barrier
	s_add_u32 m0, s32, 0x17e80
	ds_read_b128 v[230:233], v146
	ds_read_b128 v[234:237], v146 offset:1024
	ds_read_b128 v[238:241], v146 offset:2048
	ds_read_b128 v[242:245], v146 offset:3072
	global_load_lds_dwordx4 v[248:249], off offset:384
	s_add_u32 m0, s32, 0x19e80
	s_nop 0
	global_load_lds_dwordx4 v[250:251], off offset:384
	s_barrier
	s_waitcnt lgkmcnt(0)
	v_mfma_f32_16x16x32_bf16 v[94:97], v[198:201], v[230:233], v[94:97]
	v_mfma_f32_16x16x32_bf16 v[86:89], v[198:201], v[238:241], v[86:89]
	v_mfma_f32_16x16x32_bf16 v[70:73], v[206:209], v[230:233], v[70:73]
	v_mfma_f32_16x16x32_bf16 v[58:61], v[206:209], v[238:241], v[58:61]
	v_mfma_f32_16x16x32_bf16 v[54:57], v[214:217], v[230:233], v[54:57]
	v_mfma_f32_16x16x32_bf16 v[50:53], v[214:217], v[238:241], v[50:53]
	v_mfma_f32_16x16x32_bf16 v[46:49], v[222:225], v[230:233], v[46:49]
	v_mfma_f32_16x16x32_bf16 v[42:45], v[222:225], v[238:241], v[42:45]
	v_mfma_f32_16x16x32_bf16 v[94:97], v[202:205], v[234:237], v[94:97]
	v_mfma_f32_16x16x32_bf16 v[86:89], v[202:205], v[242:245], v[86:89]
	v_mfma_f32_16x16x32_bf16 v[70:73], v[210:213], v[234:237], v[70:73]
	v_mfma_f32_16x16x32_bf16 v[58:61], v[210:213], v[242:245], v[58:61]
	v_mfma_f32_16x16x32_bf16 v[54:57], v[218:221], v[234:237], v[54:57]
	v_mfma_f32_16x16x32_bf16 v[50:53], v[218:221], v[242:245], v[50:53]
	v_mfma_f32_16x16x32_bf16 v[46:49], v[226:229], v[234:237], v[46:49]
	v_mfma_f32_16x16x32_bf16 v[42:45], v[226:229], v[242:245], v[42:45]
	s_add_u32 m0, s32, 0x7e80
	s_barrier
	ds_read_b128 v[198:201], v143 offset:49152
	ds_read_b128 v[202:205], v143 offset:50176
	ds_read_b128 v[206:209], v143 offset:51200
	ds_read_b128 v[210:213], v143 offset:52224
	ds_read_b128 v[214:217], v143 offset:53248
	ds_read_b128 v[218:221], v143 offset:54272
	ds_read_b128 v[222:225], v143 offset:55296
	ds_read_b128 v[226:229], v143 offset:56320
	global_load_lds_dwordx4 v[166:167], off offset:384
	s_add_u32 m0, s32, 0x9e80
	s_nop 0
	global_load_lds_dwordx4 v[246:247], off offset:384
	s_barrier
; #define G_LDA(dst, b, h)                                                                                                  \
;   _Pragma("unroll") for (int m = 0; m < 4; ++m) _Pragma("unroll") for (int k = 0; k < 2; ++k)                             \
;       dst[m][k] = *(const bf16x8*)((const char*)G_SA(b, h) + ((wr * 4 + m) * 2 + k) * 1024 + rdo)
; #define G_LDB(dst, b, h)                                                                                                  \
;   _Pragma("unroll") for (int n = 0; n < 2; ++n) _Pragma("unroll") for (int k = 0; k < 2; ++k)                             \
;       dst[n][k] = *(const bf16x8*)((const char*)G_SB(b, h) + ((wc * 2 + n) * 2 + k) * 1024 + rdo)
; #define G_WAIT_V(n) asm volatile("s_waitcnt vmcnt(" #n ")" ::: "memory")
; #define G_WAIT_L(n) asm volatile("s_waitcnt lgkmcnt(" #n ")" ::: "memory")
; #define G_BAR __builtin_amdgcn_s_barrier()
; #define G_SCHED __builtin_amdgcn_sched_barrier(0)
; DI void br_flush(PREF p, f32x4 (&acc)[2][2][4][2], int slot) { br_store(p, acc, slot); zero_acc256(acc); }
;     ...
;     G_BAR; G_WAIT_L(0); G_MMA(1, 0, At, B0); G_BAR; G_SCHED;
;     G_STAGE(G_SB(1, 1), B, ob0, ob1, LDB, 128, KB(tt + 3));
;     G_WAIT_V(6); G_BAR; G_MMA(1, 1, At, B1); G_BAR;
;     if (MODE && ((tt + 1) & 3) == 3) br_flush(p, acc, (tt + 1) >> 2);
;   }
;   {
;     G_LDB(B0, 0, 0); G_LDA(At, 0, 0); G_STAGE(G_SA(1, 1), A, oa0, oa1, LDA, 128, KA(nt - 1));
;     G_BAR; G_WAIT_L(0); G_MMA(0, 0, At, B0); G_BAR;
;     G_LDB(B1, 0, 1); G_BAR; G_WAIT_L(0); G_MMA(0, 1, At, B1); G_BAR;
	s_waitcnt lgkmcnt(0)
	v_mfma_f32_16x16x32_bf16 v[38:41], v[198:201], v[182:185], v[38:41]
	v_mfma_f32_16x16x32_bf16 v[34:37], v[198:201], v[190:193], v[34:37]
	v_mfma_f32_16x16x32_bf16 v[30:33], v[206:209], v[182:185], v[30:33]
	v_mfma_f32_16x16x32_bf16 v[26:29], v[206:209], v[190:193], v[26:29]
	v_mfma_f32_16x16x32_bf16 v[22:25], v[214:217], v[182:185], v[22:25]
	v_mfma_f32_16x16x32_bf16 v[18:21], v[214:217], v[190:193], v[18:21]
	v_mfma_f32_16x16x32_bf16 v[14:17], v[222:225], v[182:185], v[14:17]
	v_mfma_f32_16x16x32_bf16 v[10:13], v[222:225], v[190:193], v[10:13]
	v_mfma_f32_16x16x32_bf16 v[38:41], v[202:205], v[186:189], v[38:41]
	v_mfma_f32_16x16x32_bf16 v[34:37], v[202:205], v[194:197], v[34:37]
	v_mfma_f32_16x16x32_bf16 v[30:33], v[210:213], v[186:189], v[30:33]
	v_mfma_f32_16x16x32_bf16 v[26:29], v[210:213], v[194:197], v[26:29]
	v_mfma_f32_16x16x32_bf16 v[22:25], v[218:221], v[186:189], v[22:25]
	v_mfma_f32_16x16x32_bf16 v[18:21], v[218:221], v[194:197], v[18:21]
	v_mfma_f32_16x16x32_bf16 v[14:17], v[226:229], v[186:189], v[14:17]
	v_mfma_f32_16x16x32_bf16 v[10:13], v[226:229], v[194:197], v[10:13]
	s_barrier
	v_lshl_add_u64 v[166:167], v[248:249], 0, s[6:7]
	s_add_u32 m0, s32, 0x1c000
	s_nop 0
	global_load_lds_dwordx4 v[166:167], off
	s_add_u32 m0, s32, 0x1e000
	v_lshl_add_u64 v[166:167], v[250:251], 0, s[6:7]
	global_load_lds_dwordx4 v[166:167], off
	s_waitcnt vmcnt(6)
	s_barrier
	v_mfma_f32_16x16x32_bf16 v[6:9], v[198:201], v[230:233], v[6:9]
	v_mfma_f32_16x16x32_bf16 v[2:5], v[198:201], v[238:241], v[2:5]
	v_mfma_f32_16x16x32_bf16 v[62:65], v[206:209], v[230:233], v[62:65]
	v_mfma_f32_16x16x32_bf16 v[66:69], v[206:209], v[238:241], v[66:69]
	v_mfma_f32_16x16x32_bf16 v[74:77], v[214:217], v[230:233], v[74:77]
	v_mfma_f32_16x16x32_bf16 v[78:81], v[214:217], v[238:241], v[78:81]
	v_mfma_f32_16x16x32_bf16 v[82:85], v[222:225], v[230:233], v[82:85]
	v_mfma_f32_16x16x32_bf16 v[90:93], v[222:225], v[238:241], v[90:93]
	v_mfma_f32_16x16x32_bf16 v[6:9], v[202:205], v[234:237], v[6:9]
	v_mfma_f32_16x16x32_bf16 v[2:5], v[202:205], v[242:245], v[2:5]
	v_mfma_f32_16x16x32_bf16 v[62:65], v[210:213], v[234:237], v[62:65]
	v_mfma_f32_16x16x32_bf16 v[66:69], v[210:213], v[242:245], v[66:69]
	v_mfma_f32_16x16x32_bf16 v[74:77], v[218:221], v[234:237], v[74:77]
	v_mfma_f32_16x16x32_bf16 v[78:81], v[218:221], v[242:245], v[78:81]
	v_mfma_f32_16x16x32_bf16 v[82:85], v[226:229], v[234:237], v[82:85]
	v_mfma_f32_16x16x32_bf16 v[90:93], v[226:229], v[242:245], v[90:93]
	s_add_i32 s15, s15, 2
	s_add_u32 s20, s20, 0x100
	s_addc_u32 s21, s21, 0
	s_cmp_lt_u32 s15, 12
	s_barrier
	s_cbranch_scc1 .LBB0_453
	s_add_u32 s0, s18, 0x40780
	s_addc_u32 s1, s19, 0
	v_lshl_add_u64 v[132:133], v[132:133], 1, s[0:1]
	s_add_u32 m0, s32, 0xc000
	v_lshl_add_u64 v[130:131], v[130:131], 1, s[0:1]
	ds_read_b128 v[134:137], v161
	ds_read_b128 v[138:141], v161 offset:1024
	ds_read_b128 v[152:155], v161 offset:2048
	ds_read_b128 v[182:185], v161 offset:3072
	ds_read_b128 v[186:189], v143
	ds_read_b128 v[190:193], v143 offset:1024
	ds_read_b128 v[194:197], v143 offset:2048
	ds_read_b128 v[198:201], v143 offset:3072
	ds_read_b128 v[202:205], v143 offset:4096
	ds_read_b128 v[206:209], v143 offset:5120
	ds_read_b128 v[210:213], v143 offset:6144
	ds_read_b128 v[214:217], v143 offset:7168
	global_load_lds_dwordx4 v[132:133], off
	s_add_u32 m0, s32, 0xe000
	s_nop 0
	global_load_lds_dwordx4 v[130:131], off
	s_barrier
	s_waitcnt lgkmcnt(0)
	v_mfma_f32_16x16x32_bf16 v[126:129], v[186:189], v[134:137], v[126:129]
	v_mfma_f32_16x16x32_bf16 v[122:125], v[186:189], v[152:155], v[122:125]
	v_mfma_f32_16x16x32_bf16 v[110:113], v[202:205], v[134:137], v[110:113]
	v_mfma_f32_16x16x32_bf16 v[102:105], v[210:213], v[134:137], v[102:105]
	v_mfma_f32_16x16x32_bf16 v[126:129], v[190:193], v[138:141], v[126:129]
	v_mfma_f32_16x16x32_bf16 v[122:125], v[190:193], v[182:185], v[122:125]
	v_mfma_f32_16x16x32_bf16 v[118:121], v[194:197], v[134:137], v[118:121]
	v_mfma_f32_16x16x32_bf16 v[114:117], v[194:197], v[152:155], v[114:117]
	v_mfma_f32_16x16x32_bf16 v[110:113], v[206:209], v[138:141], v[110:113]
	v_mfma_f32_16x16x32_bf16 v[106:109], v[202:205], v[152:155], v[106:109]
	v_mfma_f32_16x16x32_bf16 v[102:105], v[214:217], v[138:141], v[102:105]
	v_mfma_f32_16x16x32_bf16 v[98:101], v[210:213], v[152:155], v[98:101]
	v_mfma_f32_16x16x32_bf16 v[130:133], v[198:201], v[138:141], v[118:121]
	v_mfma_f32_16x16x32_bf16 v[164:167], v[198:201], v[182:185], v[114:117]
	v_mfma_f32_16x16x32_bf16 v[218:221], v[206:209], v[182:185], v[106:109]
	v_mfma_f32_16x16x32_bf16 v[222:225], v[214:217], v[182:185], v[98:101]
	s_barrier
	s_nop 1
	s_nop 0
	ds_read_b128 v[98:101], v159
	ds_read_b128 v[106:109], v159 offset:1024
	ds_read_b128 v[114:117], v159 offset:2048
	ds_read_b128 v[118:121], v159 offset:3072
	s_barrier
	s_waitcnt lgkmcnt(0)
	v_mfma_f32_16x16x32_bf16 v[94:97], v[186:189], v[98:101], v[94:97]
	v_mfma_f32_16x16x32_bf16 v[70:73], v[194:197], v[98:101], v[70:73]
	v_mfma_f32_16x16x32_bf16 v[58:61], v[194:197], v[114:117], v[58:61]
	v_mfma_f32_16x16x32_bf16 v[54:57], v[202:205], v[98:101], v[54:57]
	v_mfma_f32_16x16x32_bf16 v[50:53], v[202:205], v[114:117], v[50:53]
	v_mfma_f32_16x16x32_bf16 v[46:49], v[210:213], v[98:101], v[46:49]
	v_mfma_f32_16x16x32_bf16 v[42:45], v[210:213], v[114:117], v[42:45]
	v_mfma_f32_16x16x32_bf16 v[94:97], v[190:193], v[106:109], v[94:97]
	v_mfma_f32_16x16x32_bf16 v[86:89], v[186:189], v[114:117], v[86:89]
	v_mfma_f32_16x16x32_bf16 v[70:73], v[198:201], v[106:109], v[70:73]
	v_mfma_f32_16x16x32_bf16 v[58:61], v[198:201], v[118:121], v[58:61]
	v_mfma_f32_16x16x32_bf16 v[54:57], v[206:209], v[106:109], v[54:57]
	v_mfma_f32_16x16x32_bf16 v[50:53], v[206:209], v[118:121], v[50:53]
	v_mfma_f32_16x16x32_bf16 v[46:49], v[214:217], v[106:109], v[46:49]
	v_mfma_f32_16x16x32_bf16 v[42:45], v[214:217], v[118:121], v[42:45]
	v_mfma_f32_16x16x32_bf16 v[156:159], v[190:193], v[118:121], v[86:89]
	s_barrier
; #define G_LDA(dst, b, h)                                                                                                  \
;   _Pragma("unroll") for (int m = 0; m < 4; ++m) _Pragma("unroll") for (int k = 0; k < 2; ++k)                             \
;       dst[m][k] = *(const bf16x8*)((const char*)G_SA(b, h) + ((wr * 4 + m) * 2 + k) * 1024 + rdo)
; #define G_LDB(dst, b, h)                                                                                                  \
;   _Pragma("unroll") for (int n = 0; n < 2; ++n) _Pragma("unroll") for (int k = 0; k < 2; ++k)                             \
;       dst[n][k] = *(const bf16x8*)((const char*)G_SB(b, h) + ((wc * 2 + n) * 2 + k) * 1024 + rdo)
; #define G_WAIT_V(n) asm volatile("s_waitcnt vmcnt(" #n ")" ::: "memory")
; #define G_WAIT_L(n) asm volatile("s_waitcnt lgkmcnt(" #n ")" ::: "memory")
; #define G_BAR __builtin_amdgcn_s_barrier()
;     ...
;     G_LDA(At, 0, 1); G_WAIT_V(4); G_BAR; G_WAIT_L(0); G_MMA(1, 0, At, B0); G_MMA(1, 1, At, B1); G_BAR;
;   }
;   {
;     G_LDB(B0, 1, 0); G_LDA(At, 1, 0); G_WAIT_V(2); G_BAR; G_WAIT_L(0); G_MMA(0, 0, At, B0); G_BAR;
	s_nop 0
	ds_read_b128 v[86:89], v143 offset:16384
	ds_read_b128 v[186:189], v143 offset:17408
	ds_read_b128 v[190:193], v143 offset:18432
	ds_read_b128 v[194:197], v143 offset:19456
	ds_read_b128 v[198:201], v143 offset:20480
	ds_read_b128 v[202:205], v143 offset:21504
	ds_read_b128 v[206:209], v143 offset:22528
	ds_read_b128 v[210:213], v143 offset:23552
	s_waitcnt vmcnt(4)
	s_barrier
	s_waitcnt lgkmcnt(0)
	v_mfma_f32_16x16x32_bf16 v[38:41], v[86:89], v[134:137], v[38:41]
	v_mfma_f32_16x16x32_bf16 v[34:37], v[86:89], v[152:155], v[34:37]
	v_mfma_f32_16x16x32_bf16 v[30:33], v[190:193], v[134:137], v[30:33]
	v_mfma_f32_16x16x32_bf16 v[26:29], v[190:193], v[152:155], v[26:29]
	v_mfma_f32_16x16x32_bf16 v[22:25], v[198:201], v[134:137], v[22:25]
	v_mfma_f32_16x16x32_bf16 v[18:21], v[198:201], v[152:155], v[18:21]
	v_mfma_f32_16x16x32_bf16 v[14:17], v[206:209], v[134:137], v[14:17]
	v_mfma_f32_16x16x32_bf16 v[10:13], v[206:209], v[152:155], v[10:13]
	v_mfma_f32_16x16x32_bf16 v[38:41], v[186:189], v[138:141], v[38:41]
	v_mfma_f32_16x16x32_bf16 v[34:37], v[186:189], v[182:185], v[34:37]
	v_mfma_f32_16x16x32_bf16 v[30:33], v[194:197], v[138:141], v[30:33]
	v_mfma_f32_16x16x32_bf16 v[26:29], v[194:197], v[182:185], v[26:29]
	v_mfma_f32_16x16x32_bf16 v[22:25], v[202:205], v[138:141], v[22:25]
	v_mfma_f32_16x16x32_bf16 v[18:21], v[202:205], v[182:185], v[18:21]
	v_mfma_f32_16x16x32_bf16 v[14:17], v[210:213], v[138:141], v[14:17]
	v_mfma_f32_16x16x32_bf16 v[10:13], v[210:213], v[182:185], v[10:13]
	v_mfma_f32_16x16x32_bf16 v[62:65], v[190:193], v[98:101], v[62:65]
	v_mfma_f32_16x16x32_bf16 v[134:137], v[194:197], v[106:109], v[62:65]
	v_mfma_f32_16x16x32_bf16 v[62:65], v[190:193], v[114:117], v[66:69]
	v_mfma_f32_16x16x32_bf16 v[138:141], v[194:197], v[118:121], v[62:65]
	v_mfma_f32_16x16x32_bf16 v[62:65], v[198:201], v[98:101], v[74:77]
	v_mfma_f32_16x16x32_bf16 v[152:155], v[202:205], v[106:109], v[62:65]
	v_mfma_f32_16x16x32_bf16 v[62:65], v[198:201], v[114:117], v[78:81]
	v_mfma_f32_16x16x32_bf16 v[6:9], v[86:89], v[98:101], v[6:9]
	v_mfma_f32_16x16x32_bf16 v[2:5], v[86:89], v[114:117], v[2:5]
	v_mfma_f32_16x16x32_bf16 v[182:185], v[202:205], v[118:121], v[62:65]
	v_mfma_f32_16x16x32_bf16 v[62:65], v[206:209], v[98:101], v[82:85]
	v_mfma_f32_16x16x32_bf16 v[6:9], v[186:189], v[106:109], v[6:9]
	v_mfma_f32_16x16x32_bf16 v[2:5], v[186:189], v[118:121], v[2:5]
	v_mfma_f32_16x16x32_bf16 v[186:189], v[210:213], v[106:109], v[62:65]
	v_mfma_f32_16x16x32_bf16 v[62:65], v[206:209], v[114:117], v[90:93]
	v_mfma_f32_16x16x32_bf16 v[190:193], v[210:213], v[118:121], v[62:65]
	s_barrier
	ds_read_b128 v[194:197], v150
	ds_read_b128 v[198:201], v150 offset:1024
	ds_read_b128 v[202:205], v150 offset:2048
	ds_read_b128 v[148:151], v150 offset:3072
	s_nop 0
	s_nop 0
	ds_read_b128 v[62:65], v143 offset:32768
	ds_read_b128 v[66:69], v143 offset:33792
	ds_read_b128 v[74:77], v143 offset:34816
	ds_read_b128 v[78:81], v143 offset:35840
	ds_read_b128 v[206:209], v143 offset:36864
	ds_read_b128 v[210:213], v143 offset:37888
	ds_read_b128 v[214:217], v143 offset:38912
	ds_read_b128 v[226:229], v143 offset:39936
	s_waitcnt vmcnt(2)
	s_barrier
	s_waitcnt lgkmcnt(0)
	v_mfma_f32_16x16x32_bf16 v[82:85], v[62:65], v[194:197], v[126:129]
	v_mfma_f32_16x16x32_bf16 v[118:121], v[66:69], v[198:201], v[82:85]
	v_mfma_f32_16x16x32_bf16 v[82:85], v[62:65], v[202:205], v[122:125]
	v_mfma_f32_16x16x32_bf16 v[126:129], v[66:69], v[148:151], v[82:85]
	v_mfma_f32_16x16x32_bf16 v[82:85], v[74:77], v[194:197], v[130:133]
	v_mfma_f32_16x16x32_bf16 v[114:117], v[78:81], v[198:201], v[82:85]
	v_mfma_f32_16x16x32_bf16 v[82:85], v[74:77], v[202:205], v[164:167]
	v_mfma_f32_16x16x32_bf16 v[122:125], v[78:81], v[148:151], v[82:85]
	v_mfma_f32_16x16x32_bf16 v[82:85], v[206:209], v[194:197], v[110:113]
	v_mfma_f32_16x16x32_bf16 v[106:109], v[210:213], v[198:201], v[82:85]
	v_mfma_f32_16x16x32_bf16 v[82:85], v[206:209], v[202:205], v[218:221]
	v_mfma_f32_16x16x32_bf16 v[110:113], v[210:213], v[148:151], v[82:85]
	v_mfma_f32_16x16x32_bf16 v[82:85], v[214:217], v[194:197], v[102:105]
	v_mfma_f32_16x16x32_bf16 v[98:101], v[226:229], v[198:201], v[82:85]
	v_mfma_f32_16x16x32_bf16 v[82:85], v[214:217], v[202:205], v[222:225]
	v_mfma_f32_16x16x32_bf16 v[102:105], v[226:229], v[148:151], v[82:85]
	s_barrier
; #define G_LDA(dst, b, h)                                                                                                  \
;   _Pragma("unroll") for (int m = 0; m < 4; ++m) _Pragma("unroll") for (int k = 0; k < 2; ++k)                             \
;       dst[m][k] = *(const bf16x8*)((const char*)G_SA(b, h) + ((wr * 4 + m) * 2 + k) * 1024 + rdo)
; #define G_LDB(dst, b, h)                                                                                                  \
;   _Pragma("unroll") for (int n = 0; n < 2; ++n) _Pragma("unroll") for (int k = 0; k < 2; ++k)                             \
;       dst[n][k] = *(const bf16x8*)((const char*)G_SB(b, h) + ((wc * 2 + n) * 2 + k) * 1024 + rdo)
; #define G_WAIT_V(n) asm volatile("s_waitcnt vmcnt(" #n ")" ::: "memory")
; #define G_WAIT_L(n) asm volatile("s_waitcnt lgkmcnt(" #n ")" ::: "memory")
; #define G_BAR __builtin_amdgcn_s_barrier()
;     ...
;     G_LDB(B1, 1, 1); G_WAIT_V(0); G_BAR; G_WAIT_L(0); G_MMA(0, 1, At, B1); G_BAR;
;     G_LDA(At, 1, 1); G_BAR; G_WAIT_L(0); G_MMA(1, 0, At, B0); G_MMA(1, 1, At, B1); G_BAR;
;   }
;   if (wr == 0) G_BAR;
	ds_read_b128 v[130:133], v146
	ds_read_b128 v[164:167], v146 offset:1024
	ds_read_b128 v[218:221], v146 offset:2048
	ds_read_b128 v[144:147], v146 offset:3072
	s_waitcnt vmcnt(0)
	s_barrier
	s_waitcnt lgkmcnt(0)
	v_mfma_f32_16x16x32_bf16 v[82:85], v[62:65], v[130:133], v[94:97]
	v_mfma_f32_16x16x32_bf16 v[62:65], v[62:65], v[218:221], v[156:159]
	v_mfma_f32_16x16x32_bf16 v[94:97], v[66:69], v[144:147], v[62:65]
	v_mfma_f32_16x16x32_bf16 v[62:65], v[74:77], v[130:133], v[70:73]
	v_mfma_f32_16x16x32_bf16 v[58:61], v[74:77], v[218:221], v[58:61]
	v_mfma_f32_16x16x32_bf16 v[54:57], v[206:209], v[130:133], v[54:57]
	v_mfma_f32_16x16x32_bf16 v[50:53], v[206:209], v[218:221], v[50:53]
	v_mfma_f32_16x16x32_bf16 v[46:49], v[214:217], v[130:133], v[46:49]
	v_mfma_f32_16x16x32_bf16 v[42:45], v[214:217], v[218:221], v[42:45]
	v_mfma_f32_16x16x32_bf16 v[86:89], v[66:69], v[164:167], v[82:85]
	v_mfma_f32_16x16x32_bf16 v[82:85], v[78:81], v[164:167], v[62:65]
	v_mfma_f32_16x16x32_bf16 v[90:93], v[78:81], v[144:147], v[58:61]
	v_mfma_f32_16x16x32_bf16 v[74:77], v[210:213], v[164:167], v[54:57]
	v_mfma_f32_16x16x32_bf16 v[78:81], v[210:213], v[144:147], v[50:53]
	v_mfma_f32_16x16x32_bf16 v[66:69], v[226:229], v[164:167], v[46:49]
	v_mfma_f32_16x16x32_bf16 v[70:73], v[226:229], v[144:147], v[42:45]
	s_barrier
	ds_read_b128 v[156:159], v143 offset:49152
	ds_read_b128 v[206:209], v143 offset:50176
	ds_read_b128 v[210:213], v143 offset:51200
	ds_read_b128 v[214:217], v143 offset:52224
	ds_read_b128 v[222:225], v143 offset:53248
	ds_read_b128 v[226:229], v143 offset:54272
	ds_read_b128 v[230:233], v143 offset:55296
	ds_read_b128 v[234:237], v143 offset:56320
	s_barrier
	s_waitcnt lgkmcnt(0)
	v_mfma_f32_16x16x32_bf16 v[38:41], v[156:159], v[194:197], v[38:41]
	v_mfma_f32_16x16x32_bf16 v[34:37], v[156:159], v[202:205], v[34:37]
	v_mfma_f32_16x16x32_bf16 v[30:33], v[210:213], v[194:197], v[30:33]
	v_mfma_f32_16x16x32_bf16 v[26:29], v[210:213], v[202:205], v[26:29]
	v_mfma_f32_16x16x32_bf16 v[22:25], v[222:225], v[194:197], v[22:25]
	v_mfma_f32_16x16x32_bf16 v[18:21], v[222:225], v[202:205], v[18:21]
	v_mfma_f32_16x16x32_bf16 v[14:17], v[230:233], v[194:197], v[14:17]
	v_mfma_f32_16x16x32_bf16 v[10:13], v[230:233], v[202:205], v[10:13]
	v_mfma_f32_16x16x32_bf16 v[54:57], v[206:209], v[198:201], v[38:41]
	v_mfma_f32_16x16x32_bf16 v[62:65], v[206:209], v[148:151], v[34:37]
	v_mfma_f32_16x16x32_bf16 v[50:53], v[214:217], v[198:201], v[30:33]
	v_mfma_f32_16x16x32_bf16 v[58:61], v[214:217], v[148:151], v[26:29]
	v_mfma_f32_16x16x32_bf16 v[42:45], v[226:229], v[198:201], v[22:25]
	v_mfma_f32_16x16x32_bf16 v[46:49], v[226:229], v[148:151], v[18:21]
	v_mfma_f32_16x16x32_bf16 v[34:37], v[234:237], v[198:201], v[14:17]
	v_mfma_f32_16x16x32_bf16 v[38:41], v[234:237], v[148:151], v[10:13]
	v_mfma_f32_16x16x32_bf16 v[2:5], v[156:159], v[218:221], v[2:5]
	v_mfma_f32_16x16x32_bf16 v[30:33], v[206:209], v[144:147], v[2:5]
	v_mfma_f32_16x16x32_bf16 v[2:5], v[210:213], v[130:133], v[134:137]
	v_mfma_f32_16x16x32_bf16 v[18:21], v[214:217], v[164:167], v[2:5]
	v_mfma_f32_16x16x32_bf16 v[2:5], v[210:213], v[218:221], v[138:141]
	v_mfma_f32_16x16x32_bf16 v[26:29], v[214:217], v[144:147], v[2:5]
	v_mfma_f32_16x16x32_bf16 v[2:5], v[222:225], v[130:133], v[152:155]
	v_mfma_f32_16x16x32_bf16 v[6:9], v[156:159], v[130:133], v[6:9]
	v_mfma_f32_16x16x32_bf16 v[10:13], v[226:229], v[164:167], v[2:5]
	v_mfma_f32_16x16x32_bf16 v[2:5], v[222:225], v[218:221], v[182:185]
	v_mfma_f32_16x16x32_bf16 v[22:25], v[206:209], v[164:167], v[6:9]
	v_mfma_f32_16x16x32_bf16 v[14:17], v[226:229], v[144:147], v[2:5]
	v_mfma_f32_16x16x32_bf16 v[2:5], v[230:233], v[130:133], v[186:189]
	v_mfma_f32_16x16x32_bf16 v[6:9], v[230:233], v[218:221], v[190:193]
	v_mfma_f32_16x16x32_bf16 v[2:5], v[234:237], v[164:167], v[2:5]
	v_mfma_f32_16x16x32_bf16 v[6:9], v[234:237], v[144:147], v[6:9]
	v_cmp_gt_u32_e32 vcc, s67, v0
	s_barrier
	s_and_saveexec_b64 s[18:19], vcc
	s_cbranch_execz .LBB0_456
	s_barrier
